# combo9: combo8 + accumulator zero-init with 64-bit moves + EpiUp conv halo: acc*rs multiply fused into the row_shr DPP op against a once-per-unit pre-shifted rs
# speedup vs baseline: 1.0056x; 1.0010x over previous
; template <class Epi, class Sched, bool ALIGN_EPI = false, bool SP2 = false>
; __device__ __forceinline__ void gemm_phase(PG8_LAS unsigned char* lds, const Gemm g, const Sched& S, const Epi& E, const int tid_arg) {
;     ...
;     Unit cur, nxt; int ui = 0;
;     if (!S.next(0, cur)) return;
;     f32x4 acc[2][2][4][2];
; #pragma unroll
;     for (int a = 0; a < 2; ++a)
; #pragma unroll
;         for (int b = 0; b < 2; ++b)
; #pragma unroll
;             for (int m = 0; m < 4; ++m)
; #pragma unroll
;                 for (int n = 0; n < 2; ++n) acc[a][b][m][n] = (f32x4){0.f, 0.f, 0.f, 0.f};
;     bf16x8 At[4][2], B0[2][2], B1[2][2];
;     const char* cA = (const char*)g.A + (size_t)cur.pm * tstep; const char* cB = (const char*)g.Bt + (size_t)cur.pn * tstep;
;     ...
; #pragma unroll
;         for (int a = 0; a < 2; ++a)
; #pragma unroll
;             for (int b = 0; b < 2; ++b)
; #pragma unroll
;                 for (int m = 0; m < 4; ++m)
; #pragma unroll
;                     for (int n = 0; n < 2; ++n) acc[a][b][m][n] = (f32x4){0.f, 0.f, 0.f, 0.f};
;         cur = nxt; cA = nA; cB = nB; ++ui;
.LBB0_252:
	s_ashr_i32 s23, s22, 31
	s_lshl_b64 s[0:1], s[22:23], 19
	s_add_u32 s24, s2, s0
	s_addc_u32 s25, s3, s1
	s_and_b64 s[0:1], s[4:5], exec
	s_cselect_b32 s23, s25, s35
	s_cselect_b32 s36, s24, s34
	s_ashr_i32 s21, s20, 31
	s_lshl_b64 s[0:1], s[20:21], 19
	s_add_u32 s26, s33, s0
	s_addc_u32 s27, s38, s1
	s_and_b64 s[0:1], s[4:5], exec
	s_cselect_b32 s21, s27, s9
	s_cselect_b32 s37, s26, s8
	s_add_u32 s68, s8, 0x100
	s_addc_u32 s69, s9, 0
	s_add_u32 s8, s34, 0x40080
	v_mov_b32_e32 v0, 0
	s_addc_u32 s9, s35, 0
	s_mov_b32 s70, -2
	v_mov_b32_e32 v1, v0
	v_mov_b64_e32 v[2:3], 0
	v_mov_b64_e32 v[4:5], 0
	v_mov_b64_e32 v[6:7], 0
	v_mov_b64_e32 v[16:17], 0
	v_mov_b64_e32 v[18:19], 0
	v_mov_b64_e32 v[20:21], 0
	v_mov_b64_e32 v[22:23], 0
	v_mov_b64_e32 v[32:33], 0
	v_mov_b64_e32 v[34:35], 0
	v_mov_b64_e32 v[36:37], 0
	v_mov_b64_e32 v[38:39], 0
	v_mov_b64_e32 v[48:49], 0
	v_mov_b64_e32 v[50:51], 0
	v_mov_b64_e32 v[52:53], 0
	v_mov_b64_e32 v[54:55], 0
	v_mov_b64_e32 v[8:9], 0
	v_mov_b64_e32 v[10:11], 0
	v_mov_b64_e32 v[12:13], 0
	v_mov_b64_e32 v[14:15], 0
	v_mov_b64_e32 v[24:25], 0
	v_mov_b64_e32 v[26:27], 0
	v_mov_b64_e32 v[28:29], 0
	v_mov_b64_e32 v[30:31], 0
	v_mov_b64_e32 v[40:41], 0
	v_mov_b64_e32 v[42:43], 0
	v_mov_b64_e32 v[44:45], 0
	v_mov_b64_e32 v[46:47], 0
	v_mov_b64_e32 v[56:57], 0
	v_mov_b64_e32 v[58:59], 0
	v_mov_b64_e32 v[60:61], 0
	v_mov_b64_e32 v[62:63], 0
	v_mov_b64_e32 v[64:65], 0
	v_mov_b64_e32 v[66:67], 0
	v_mov_b64_e32 v[68:69], 0
	v_mov_b64_e32 v[70:71], 0
	v_mov_b64_e32 v[80:81], 0
	v_mov_b64_e32 v[82:83], 0
	v_mov_b64_e32 v[84:85], 0
	v_mov_b64_e32 v[86:87], 0
	v_mov_b64_e32 v[96:97], 0
	v_mov_b64_e32 v[98:99], 0
	v_mov_b64_e32 v[100:101], 0
	v_mov_b64_e32 v[102:103], 0
	v_mov_b64_e32 v[112:113], 0
	v_mov_b64_e32 v[114:115], 0
	v_mov_b64_e32 v[116:117], 0
	v_mov_b64_e32 v[118:119], 0
	v_mov_b64_e32 v[72:73], 0
	v_mov_b64_e32 v[74:75], 0
	v_mov_b64_e32 v[76:77], 0
	v_mov_b64_e32 v[78:79], 0
	v_mov_b64_e32 v[88:89], 0
	v_mov_b64_e32 v[90:91], 0
	v_mov_b64_e32 v[92:93], 0
	v_mov_b64_e32 v[94:95], 0
	v_mov_b64_e32 v[104:105], 0
	v_mov_b64_e32 v[106:107], 0
	v_mov_b64_e32 v[108:109], 0
	v_mov_b64_e32 v[110:111], 0
	v_mov_b64_e32 v[120:121], 0
	v_mov_b64_e32 v[122:123], 0
	v_mov_b64_e32 v[124:125], 0
	v_mov_b64_e32 v[126:127], 0

; #define PG8_WAIT_V(n) asm volatile("s_waitcnt vmcnt(" #n ")" ::: "memory")
; template <class Epi, class Sched, bool ALIGN_EPI = false, bool SP2 = false>
; __device__ __forceinline__ void gemm_phase(PG8_LAS unsigned char* lds, const Gemm g, const Sched& S, const Epi& E, const int tid_arg) {
;     ...
;     const int tid = tid_l, wid = __builtin_amdgcn_readfirstlane(tid >> 6), lane = tid & 63, wr = wid >> 2, wc = wid & 3, fr = lane & 15, fq = lane >> 4;
;     const int K = g.K, nt = K / BK;
;     unsigned voffA[2], voffB[2];
; #pragma unroll
;     for (int i = 0; i < 2; ++i) { int R, C; stage_rc(tid * 16 + i * 8192, R, C); const int Rb = Epi::PERM ? ((R & ~31) + perm32(R & 31)) : R;
;         const int Ra = Epi::PERMA ? ((R & ~63) + 4 * (R & 15) + ((R >> 4) & 3)) : R;
;         voffA[i] = (unsigned)(Ra * K + C) * 2u; voffB[i] = (unsigned)(Rb * K + C) * 2u; }
;     const size_t kstep = (size_t)(BK * 2);
;     const size_t hstep = (size_t)HALF * K * 2;
;     const size_t tstep = 2 * hstep;
;     const unsigned ldsw = (unsigned)wid * 1024u;
;     const int aoff = lds_byte(wr * 64 + fr, fq * 8), boff = lds_byte(wc * 32 + fr, fq * 8);
;     ...
;     Unit cur, nxt; int ui = 0;
;     if (!S.next(0, cur)) return;
;     f32x4 acc[2][2][4][2];
; #pragma unroll
;     for (int a = 0; a < 2; ++a)
; #pragma unroll
;         for (int b = 0; b < 2; ++b)
; #pragma unroll
;             for (int m = 0; m < 4; ++m)
; #pragma unroll
;                 for (int n = 0; n < 2; ++n) acc[a][b][m][n] = (f32x4){0.f, 0.f, 0.f, 0.f};
;     bf16x8 At[4][2], B0[2][2], B1[2][2];
;     const char* cA = (const char*)g.A + (size_t)cur.pm * tstep; const char* cB = (const char*)g.Bt + (size_t)cur.pn * tstep;
;     S.a_ready(cur);
;     if constexpr (SP2) {
;         PG8_STAGE(PG8_SB(0, 0), cB, voffB); PG8_STAGE(PG8_SB(0, 1), cB + hstep, voffB); PG8_STAGE(PG8_SA(0, 0), cA, voffA); PG8_STAGE(PG8_SA(0, 1), cA + hstep, voffA);
;         if (wr == 1) PG8_BAR;
;         PG8_WAIT_V(2); PG8_BAR;
;         PG8_STAGE(PG8_SB(1, 0), cB + kstep, voffB); PG8_STAGE(PG8_SA(1, 0), cA + kstep, voffA); PG8_STAGE(PG8_SB(1, 1), cB + hstep + kstep, voffB);
;         PG8_WAIT_V(6); PG8_BAR;
;     } else {
;         PG8_STAGE(PG8_SB(0, 0), cB, voffB); PG8_STAGE(PG8_SA(0, 0), cA, voffA); PG8_STAGE(PG8_SB(0, 1), cB + hstep, voffB); PG8_STAGE(PG8_SA(0, 1), cA + hstep, voffA);
;         if (wr == 1) PG8_BAR;
;         PG8_WAIT_V(4); PG8_BAR;
.LBB0_679:
	s_waitcnt lgkmcnt(0)
	s_add_u32 s20, s16, 0x9804000
	s_addc_u32 s21, s17, 0
	s_add_u32 s55, s12, 0x17984000
	s_addc_u32 s56, s13, 0
	s_add_u32 s22, s0, 0x1c484000
	s_addc_u32 s23, s1, 0
	s_and_b32 s12, s24, 3
	s_add_i32 s59, s49, 0x18000
	s_mov_b64 s[24:25], 0x80
	v_lshl_add_u64 v[6:7], v[6:7], 0, s[24:25]
	s_mov_b32 m0, s59
	s_add_i32 s60, s49, 0x1a000
	s_lshl_b32 s57, s30, 6
	s_lshl_b32 s13, s30, 13
	s_lshl_b32 s58, s12, 5
	s_lshl_b32 s14, s12, 12
	s_waitcnt vmcnt(2)
	s_barrier
	global_load_lds_dwordx4 v[6:7], off
	v_lshl_add_u64 v[4:5], v[4:5], 0, s[24:25]
	s_mov_b32 m0, s60
	s_add_i32 s61, s49, 0x8000
	s_add_i32 s62, s49, 0xa000
	global_load_lds_dwordx4 v[4:5], off
	v_lshl_add_u64 v[0:1], v[0:1], 0, s[24:25]
	s_mov_b32 m0, s61
	s_add_u32 s0, s10, 0x40080
	global_load_lds_dwordx4 v[0:1], off
	v_lshl_add_u64 v[0:1], v[2:3], 0, s[24:25]
	s_mov_b32 m0, s62
	s_addc_u32 s1, s11, 0
	s_add_i32 s63, s49, 0x1c000
	global_load_lds_dwordx4 v[0:1], off
	v_lshl_add_u64 v[0:1], s[0:1], 0, v[188:189]
	s_mov_b32 m0, s63
	s_add_i32 s64, s49, 0x1e000
	global_load_lds_dwordx4 v[0:1], off
	v_lshl_add_u64 v[0:1], s[0:1], 0, v[192:193]
	s_mov_b32 m0, s64
	v_bfe_u32 v205, v8, 4, 2
	global_load_lds_dwordx4 v[0:1], off
	v_and_b32_e32 v204, 15, v8
	v_lshlrev_b32_e32 v0, 4, v205
	v_lshlrev_b32_e32 v1, 2, v8
	v_lshl_or_b32 v0, v204, 6, v0
	v_and_b32_e32 v1, 32, v1
	v_bitop3_b32 v206, v0, s13, v1 bitop3:0xde
	v_bitop3_b32 v2, v0, s14, v1 bitop3:0xde
	v_and_b32_e32 v1, 1, v14
	v_add3_u32 v0, v16, v17, v18
	v_lshlrev_b32_e32 v1, 6, v1
	v_lshl_or_b32 v0, v0, 11, v1
	s_mov_b64 s[0:1], 0x40080
	s_cmpk_lt_u32 s28, 0x100
	v_lshl_add_u32 v0, v15, 1, v0
	v_mov_b32_e32 v1, v189
	s_cselect_b64 s[26:27], -1, 0
	s_and_b32 s69, s28, 0xffffff00
	s_lshl_b32 s12, s12, 6
	v_lshl_add_u64 v[194:195], v[0:1], 0, s[0:1]
	v_and_b32_e32 v1, 1, v9
	s_or_b32 s66, s12, s69
	s_lshl_b32 s71, s30, 11
	v_add3_u32 v0, v11, v12, v13
	v_lshlrev_b32_e32 v1, 6, v1
	s_waitcnt vmcnt(6)
	s_cmp_gt_i32 s30, 0
	v_lshl_or_b32 v0, v0, 11, v1
	s_cselect_b64 s[28:29], -1, 0
	s_cmp_gt_i32 s30, -2
	v_readlane_b32 s12, v251, 0
	v_lshl_add_u32 v0, v10, 1, v0
	v_mov_b32_e32 v1, v189
	s_movk_i32 s65, 0x100
	s_mov_b32 s16, 0
	s_cselect_b64 s[30:31], -1, 0
	s_ashr_i32 s67, s12, 31
	s_mov_b32 s68, s12
	s_add_i32 s69, s69, 0x24040
	s_add_i32 s70, s71, 0x20000
	s_add_i32 s71, s71, 0x1f800
	v_lshl_add_u64 v[196:197], v[0:1], 0, s[0:1]
	v_or_b32_e32 v207, 0x10000, v2
	v_add_u32_e32 v208, 0x10400, v2
	v_add_u32_e32 v209, 0x10800, v2
	v_add_u32_e32 v210, 0x10c00, v2
	v_or_b32_e32 v211, 0x14000, v2
	v_add_u32_e32 v212, 0x14400, v2
	v_add_u32_e32 v213, 0x14800, v2
	v_add_u32_e32 v214, 0x14c00, v2
	s_add_i32 s72, s49, 0xc000
	s_add_i32 s73, s49, 0xe000
	v_or_b32_e32 v215, 0x18000, v2
	v_add_u32_e32 v216, 0x18400, v2
	v_add_u32_e32 v217, 0x18800, v2
	v_add_u32_e32 v218, 0x18c00, v2
	v_or_b32_e32 v219, 0x1c000, v2
	v_add_u32_e32 v220, 0x1c400, v2
	v_add_u32_e32 v221, 0x1c800, v2
	v_add_u32_e32 v222, 0x1cc00, v2
	s_movk_i32 s74, 0x1600
	v_mov_b32_e32 v223, 0x358637bd
	v_mov_b32_e32 v224, 0x22040
	v_mov_b32_e32 v225, 0x24040
	s_barrier
	v_readlane_b32 s13, v251, 1
	s_branch .LBB0_682

;     __host__ __device__ bool next(int i, Unit& u) const {
;         const long L = (long)i * G + c; if (L >= nwg) return false;
;         int wgid = (int)L; { const int q = nwg / NXCD, r = nwg % NXCD, xcd = wgid % NXCD, off = wgid / NXCD; wgid = (xcd < r ? xcd * (q + 1) : r * (q + 1) + (xcd - r) * q) + off; }
;         const int nig = WGM * nN, gid = wgid / nig, fm = gid * WGM, gsz = (nM - fm) < WGM ? (nM - fm) : WGM;
;         u.pm = fm + ((wgid % nig) % gsz); u.pn = (wgid % nig) / gsz; return true;
; template <class Epi, class Sched, bool ALIGN_EPI = false, bool SP2 = false>
; __device__ __forceinline__ void gemm_phase(PG8_LAS unsigned char* lds, const Gemm g, const Sched& S, const Epi& E, const int tid_arg) {
;     ...
; #pragma unroll
;         for (int a = 0; a < 2; ++a)
; #pragma unroll
;             for (int b = 0; b < 2; ++b)
; #pragma unroll
;                 for (int m = 0; m < 4; ++m)
; #pragma unroll
;                     for (int n = 0; n < 2; ++n) acc[a][b][m][n] = (f32x4){0.f, 0.f, 0.f, 0.f};
.LBB0_682:
	s_add_i32 s75, s16, 1
	s_mul_i32 s0, s75, s67
	s_mul_hi_u32 s1, s75, s68
	s_add_i32 s1, s1, s0
	s_mul_i32 s0, s75, s68
	s_add_u32 s0, s0, s86
	s_addc_u32 s1, s1, s87
	v_mov_b64_e32 v[198:199], 0xb00
	v_mov_b64_e32 v[200:201], 0xaff
	v_cmp_gt_i64_e32 vcc, s[0:1], v[200:201]
	v_cmp_lt_i64_e64 s[12:13], s[0:1], v[198:199]
	s_cbranch_vccnz .LBB0_684
	s_ashr_i32 s1, s0, 31
	s_lshr_b32 s1, s1, 29
	s_add_i32 s1, s0, s1
	s_ashr_i32 s14, s1, 3
	s_and_b32 s1, s1, -8
	s_sub_i32 s0, s0, s1
	s_cmp_lt_i32 s0, 0
	s_movk_i32 s1, 0x161
	s_cselect_b32 s1, s1, 0x160
	s_mul_i32 s0, s1, s0
	s_add_i32 s0, s0, s14
	s_mul_hi_i32 s1, s0, 0x2e8ba2e9
	s_lshr_b32 s14, s1, 31
	s_ashr_i32 s1, s1, 5
	s_add_i32 s1, s1, s14
	s_lshl_b32 s14, s1, 3
	s_sub_i32 s15, 0x80, s14
	s_min_i32 s15, s15, 8
	s_abs_i32 s17, s15
	v_cvt_f32_u32_e32 v0, s17
	s_sub_i32 s35, 0, s17
	s_mulk_i32 s1, 0xb0
	s_sub_i32 s0, s0, s1
	v_rcp_iflag_f32_e32 v0, v0
	s_abs_i32 s1, s0
	s_xor_b32 s34, s0, s15
	s_ashr_i32 s34, s34, 31
	v_mul_f32_e32 v0, 0x4f7ffffe, v0
	v_cvt_u32_f32_e32 v0, v0
	s_nop 0
	v_readfirstlane_b32 s36, v0
	s_mul_i32 s35, s35, s36
	s_mul_hi_u32 s35, s36, s35
	s_add_i32 s36, s36, s35
	s_mul_hi_u32 s35, s1, s36
	s_mul_i32 s36, s35, s17
	s_sub_i32 s1, s1, s36
	s_add_i32 s37, s35, 1
	s_sub_i32 s36, s1, s17
	s_cmp_ge_u32 s1, s17
	s_cselect_b32 s35, s37, s35
	s_cselect_b32 s1, s36, s1
	s_add_i32 s36, s35, 1
	s_cmp_ge_u32 s1, s17
	s_cselect_b32 s1, s36, s35
	s_xor_b32 s1, s1, s34
	s_sub_i32 s34, s1, s34
	s_mul_i32 s1, s34, s15
	s_sub_i32 s0, s0, s1
	s_add_i32 s36, s0, s14
.LBB0_684:
	s_ashr_i32 s37, s36, 31
	s_lshl_b64 s[0:1], s[36:37], 19
	s_add_u32 s38, s2, s0
	s_addc_u32 s39, s3, s1
	s_and_b64 s[0:1], s[12:13], exec
	s_cselect_b32 s17, s39, s5
	s_cselect_b32 s37, s38, s4
	s_ashr_i32 s35, s34, 31
	s_lshl_b64 s[0:1], s[34:35], 19
	s_add_u32 s40, s33, s0
	s_addc_u32 s41, s48, s1
	s_and_b64 s[0:1], s[12:13], exec
	s_cselect_b32 s35, s41, s11
	s_cselect_b32 s46, s40, s10
	s_add_u32 s47, s10, 0x100
	v_mov_b32_e32 v0, 0
	s_addc_u32 s78, s11, 0
	s_mov_b32 s79, -2
	v_mov_b32_e32 v1, v0
	v_mov_b32_e32 v2, v0
	v_mov_b32_e32 v3, v0
	v_mov_b32_e32 v64, v0
	v_mov_b32_e32 v65, v0
	v_mov_b32_e32 v66, v0
	v_mov_b32_e32 v67, v0
	v_mov_b32_e32 v8, v0
	v_mov_b32_e32 v9, v0
	v_mov_b32_e32 v10, v0
	v_mov_b32_e32 v11, v0
	v_mov_b32_e32 v76, v0
	v_mov_b32_e32 v77, v0
	v_mov_b32_e32 v78, v0
	v_mov_b32_e32 v79, v0
	v_mov_b32_e32 v16, v0
	v_mov_b32_e32 v17, v0
	v_mov_b32_e32 v18, v0
	v_mov_b32_e32 v19, v0
	s_waitcnt vmcnt(0)
	v_mov_b64_e32 v[84:85], 0
	v_mov_b64_e32 v[86:87], 0
	v_mov_b64_e32 v[24:25], 0
	v_mov_b64_e32 v[26:27], 0
	v_mov_b64_e32 v[92:93], 0
	v_mov_b64_e32 v[94:95], 0
	v_mov_b64_e32 v[4:5], 0
	v_mov_b64_e32 v[6:7], 0
	v_mov_b64_e32 v[68:69], 0
	v_mov_b64_e32 v[70:71], 0
	v_mov_b64_e32 v[12:13], 0
	v_mov_b64_e32 v[14:15], 0
	v_mov_b64_e32 v[80:81], 0
	v_mov_b64_e32 v[82:83], 0
	v_mov_b64_e32 v[20:21], 0
	v_mov_b64_e32 v[22:23], 0
	v_mov_b64_e32 v[88:89], 0
	v_mov_b64_e32 v[90:91], 0
	v_mov_b64_e32 v[28:29], 0
	v_mov_b64_e32 v[30:31], 0
	v_mov_b64_e32 v[96:97], 0
	v_mov_b64_e32 v[98:99], 0
	v_mov_b64_e32 v[32:33], 0
	v_mov_b64_e32 v[34:35], 0
	v_mov_b64_e32 v[104:105], 0
	v_mov_b64_e32 v[106:107], 0
	v_mov_b64_e32 v[40:41], 0
	v_mov_b64_e32 v[42:43], 0
	v_mov_b64_e32 v[112:113], 0
	v_mov_b64_e32 v[114:115], 0
	v_mov_b64_e32 v[48:49], 0
	v_mov_b64_e32 v[50:51], 0
	v_mov_b64_e32 v[120:121], 0
	v_mov_b64_e32 v[122:123], 0
	v_mov_b64_e32 v[56:57], 0
	v_mov_b64_e32 v[58:59], 0
	v_mov_b64_e32 v[128:129], 0
	v_mov_b64_e32 v[130:131], 0
	v_mov_b64_e32 v[36:37], 0
	v_mov_b64_e32 v[38:39], 0
	v_mov_b64_e32 v[108:109], 0
	v_mov_b64_e32 v[110:111], 0
	v_mov_b64_e32 v[44:45], 0
	v_mov_b64_e32 v[46:47], 0
	v_mov_b64_e32 v[116:117], 0
	v_mov_b64_e32 v[118:119], 0
	v_mov_b64_e32 v[52:53], 0
	v_mov_b64_e32 v[54:55], 0
	v_mov_b64_e32 v[124:125], 0
	v_mov_b64_e32 v[126:127], 0
	v_mov_b64_e32 v[60:61], 0
	v_mov_b64_e32 v[62:63], 0
	v_mov_b64_e32 v[132:133], 0
	v_mov_b64_e32 v[134:135], 0

; __device__ __forceinline__ unsigned pk2(float lo, float hi) { f32x2_t v = {lo, hi}; bf16x2_t b = __builtin_convertvector(v, bf16x2_t); return __builtin_bit_cast(unsigned, b); }
; __device__ __forceinline__ float sigmoidf_(float v) { return fast_rcp(1.0f + fast_exp2(-v * LOG2E)); }
;     __device__ __forceinline__ void run(const f32x4 (&acc)[2][2][4][2], const Unit& u, const Unit& nxt, bool has_next, int ui, int wr, int wc, int fr_in, int fq_in) const {
;     ...
;             for (int ai = 0; ai < 2; ++ai) {
;                 const int grp = 2 * ai + wr;
;                 f32x4 hg2 = {0.f, 0.f, 0.f, 0.f}, hg3 = hg2, hv2 = hg2, hv3 = hg2;
;                 if (grp > 0 && fr == 0) { const PG8_LAS float* xp = xr + ((grp - 1) * 2) * 256 + cl;
;                     hg2 = *(const PG8_LAS f32x4*)(xp); hg3 = *(const PG8_LAS f32x4*)(xp + 256); hv2 = *(const PG8_LAS f32x4*)(xp + 128); hv3 = *(const PG8_LAS f32x4*)(xp + 256 + 128); }
;                 f32x4 pg2, pg1, pv2, pv1;
;                 {
;                     const f32x4 g2 = acc[ai][0][2][n] * rs[ai][2], g3 = acc[ai][0][3][n] * rs[ai][3], v2 = acc[ai][1][2][n] * rs[ai][2], v3 = acc[ai][1][3][n] * rs[ai][3];
; #pragma unroll
;                     for (int i = 0; i < 4; ++i) {
;                         float a0 = g2[i], a1 = g3[i], a2 = v2[i], a3 = v3[i];
;                         asm volatile("" : "+v"(a0), "+v"(a1), "+v"(a2), "+v"(a3));
;                         const float t0 = DPPF(a0, 0x111), t1 = DPPF(a1, 0x111), t2 = DPPF(a2, 0x111), t3 = DPPF(a3, 0x111);
;                         pg2[i] = t0 + hg2[i]; pg1[i] = t1 + hg3[i]; pv2[i] = t2 + hv2[i]; pv1[i] = t3 + hv3[i]; }
;                 }
; #pragma unroll
;                 for (int m = 0; m < 4; ++m) {
;                     const f32x4 gc = acc[ai][0][m][n] * rs[ai][m], vc = acc[ai][1][m][n] * rs[ai][m];
;                     const f32x4 cgt = bg + wg0 * pg2 + wg1 * pg1 + wg2 * gc, cvl = bv + wv0 * pv2 + wv1 * pv1 + wv2 * vc;
;                     float a[4];
; #pragma unroll
;                     for (int i = 0; i < 4; ++i) a[i] = cgt[i] * sigmoidf_(cgt[i]) * cvl[i];
;                     u32x2 w; w.x = pk2(a[0], a[1]); w.y = pk2(a[2], a[3]);
;                     *(u32x2*)(A + (size_t)(u.pm * BM + ai * 128 + wr * 64 + 4 * fr + m) * DFF + ch) = w;
;                     pg2 = pg1; pg1 = gc; pv2 = pv1; pv1 = vc;
;                 }
.LBB0_719:
	s_or_b64 exec, exec, s[0:1]
	s_lshl_b32 s0, s42, 8
	s_add_i32 s0, s0, s57
	v_lshl_add_u32 v231, v169, 2, s0
	v_mov_b32_dpp v198, v102 row_shr:1 row_mask:0xf bank_mask:0xf bound_ctrl:1
	v_mov_b32_dpp v199, v103 row_shr:1 row_mask:0xf bank_mask:0xf bound_ctrl:1
	v_mov_b32_dpp v200, v74 row_shr:1 row_mask:0xf bank_mask:0xf bound_ctrl:1
	v_mov_b32_dpp v201, v75 row_shr:1 row_mask:0xf bank_mask:0xf bound_ctrl:1
	v_mul_f32_dpp v234, v116, v198 row_shr:1 row_mask:0xf bank_mask:0xf bound_ctrl:1
	s_nop 0
	v_mul_f32_dpp v240, v104, v199 row_shr:1 row_mask:0xf bank_mask:0xf bound_ctrl:1
	v_mul_f32_dpp v236, v108, v199 row_shr:1 row_mask:0xf bank_mask:0xf bound_ctrl:1
	v_mul_f32_dpp v238, v112, v198 row_shr:1 row_mask:0xf bank_mask:0xf bound_ctrl:1
	v_mul_f32_dpp v235, v117, v198 row_shr:1 row_mask:0xf bank_mask:0xf bound_ctrl:1
	v_mul_f32_dpp v237, v109, v199 row_shr:1 row_mask:0xf bank_mask:0xf bound_ctrl:1
	v_mul_f32_dpp v239, v113, v198 row_shr:1 row_mask:0xf bank_mask:0xf bound_ctrl:1
	s_waitcnt lgkmcnt(0)
	v_pk_add_f32 v[182:183], v[182:183], v[234:235]
	v_mul_f32_dpp v241, v105, v199 row_shr:1 row_mask:0xf bank_mask:0xf bound_ctrl:1
	v_pk_add_f32 v[178:179], v[178:179], v[236:237]
	v_pk_fma_f32 v[182:183], v[152:153], v[182:183], v[164:165]
	v_mul_f32_dpp v242, v118, v198 row_shr:1 row_mask:0xf bank_mask:0xf bound_ctrl:1
	v_mul_f32_dpp v248, v106, v199 row_shr:1 row_mask:0xf bank_mask:0xf bound_ctrl:1
	v_pk_mul_f32 v[132:133], v[132:133], v[100:101] op_sel_hi:[1,0]
	v_pk_fma_f32 v[182:183], v[156:157], v[178:179], v[182:183]
	v_mul_f32_dpp v244, v110, v199 row_shr:1 row_mask:0xf bank_mask:0xf bound_ctrl:1
	v_pk_fma_f32 v[182:183], v[132:133], v[160:161], v[182:183]
	v_mul_f32_dpp v243, v119, v198 row_shr:1 row_mask:0xf bank_mask:0xf bound_ctrl:1
	v_exp_f32_e32 v169, v182
	v_exp_f32_e32 v235, v183
	v_mul_f32_dpp v246, v114, v198 row_shr:1 row_mask:0xf bank_mask:0xf bound_ctrl:1
	v_add_f32_e32 v169, 1.0, v169
	v_rcp_f32_e32 v234, v169
	v_add_f32_e32 v169, 1.0, v235
	v_rcp_f32_e32 v235, v169
	v_pk_mul_f32 v[236:237], v[128:129], v[100:101] op_sel_hi:[1,0]
	v_pk_add_f32 v[128:129], v[174:175], v[238:239]
	v_mul_f32_dpp v245, v111, v199 row_shr:1 row_mask:0xf bank_mask:0xf bound_ctrl:1
	v_pk_mul_f32 v[174:175], v[182:183], v[234:235]
	v_pk_add_f32 v[182:183], v[184:185], v[242:243]
	v_pk_add_f32 v[180:181], v[180:181], v[244:245]
	v_pk_fma_f32 v[182:183], v[154:155], v[182:183], v[166:167]
	v_pk_mul_f32 v[134:135], v[134:135], v[100:101] op_sel_hi:[1,0]
	v_pk_fma_f32 v[182:183], v[158:159], v[180:181], v[182:183]
	v_pk_add_f32 v[170:171], v[170:171], v[240:241]
	v_pk_fma_f32 v[182:183], v[134:135], v[162:163], v[182:183]
	v_pk_fma_f32 v[128:129], v[136:137], v[128:129], v[148:149]
	v_exp_f32_e32 v169, v182
	v_exp_f32_e32 v185, v183
	v_add_f32_e32 v169, 1.0, v169
	v_pk_fma_f32 v[128:129], v[140:141], v[170:171], v[128:129]
	v_rcp_f32_e32 v184, v169
	v_add_f32_e32 v169, 1.0, v185
	v_mul_f32_dpp v247, v115, v198 row_shr:1 row_mask:0xf bank_mask:0xf bound_ctrl:1
	v_pk_fma_f32 v[128:129], v[236:237], v[144:145], v[128:129]
	v_rcp_f32_e32 v185, v169
	v_mul_f32_dpp v249, v107, v199 row_shr:1 row_mask:0xf bank_mask:0xf bound_ctrl:1
	v_pk_mul_f32 v[128:129], v[128:129], v[174:175]
	v_pk_add_f32 v[174:175], v[176:177], v[246:247]
	v_pk_add_f32 v[172:173], v[172:173], v[248:249]
	v_pk_fma_f32 v[174:175], v[138:139], v[174:175], v[150:151]
	s_lshl_b32 s16, s44, 7
	v_pk_mul_f32 v[130:131], v[130:131], v[100:101] op_sel_hi:[1,0]
	v_pk_fma_f32 v[174:175], v[142:143], v[172:173], v[174:175]
	v_add_u32_e32 v232, s16, v202
	v_pk_mul_f32 v[176:177], v[182:183], v[184:185]
	v_pk_fma_f32 v[174:175], v[130:131], v[146:147], v[174:175]
	v_ashrrev_i32_e32 v233, 31, v232
	v_pk_mul_f32 v[174:175], v[174:175], v[176:177]
	v_pk_fma_f32 v[178:179], v[152:153], v[178:179], v[164:165]
	v_cvt_pk_bf16_f32 v177, v174, v175
	v_lshlrev_b64 v[174:175], 1, v[232:233]
	v_mov_b32_e32 v232, v101
	v_pk_mul_f32 v[124:125], v[124:125], v[232:233] op_sel_hi:[1,0]
	v_pk_fma_f32 v[178:179], v[132:133], v[156:157], v[178:179]
	v_mov_b64_e32 v[182:183], s[20:21]
	v_pk_fma_f32 v[178:179], v[124:125], v[160:161], v[178:179]
	v_cvt_pk_bf16_f32 v176, v128, v129
	v_exp_f32_e32 v169, v178
	v_exp_f32_e32 v233, v179
	v_mad_i64_i32 v[128:129], s[0:1], v231, s74, v[182:183]
	v_lshl_add_u64 v[184:185], v[128:129], 0, v[174:175]
	v_add_f32_e32 v169, 1.0, v169
	global_store_dwordx2 v[184:185], v[176:177], off
	v_rcp_f32_e32 v176, v169
	v_add_f32_e32 v169, 1.0, v233
	v_rcp_f32_e32 v177, v169
	v_pk_mul_f32 v[184:185], v[126:127], v[232:233] op_sel_hi:[1,0]
	v_pk_fma_f32 v[132:133], v[132:133], v[152:153], v[164:165]
	v_pk_fma_f32 v[170:171], v[136:137], v[170:171], v[148:149]
	v_pk_mul_f32 v[126:127], v[178:179], v[176:177]
	v_pk_fma_f32 v[176:177], v[154:155], v[180:181], v[166:167]
	v_pk_mul_f32 v[116:117], v[116:117], v[102:103] op_sel_hi:[1,0]
	v_pk_fma_f32 v[176:177], v[134:135], v[158:159], v[176:177]
	v_pk_fma_f32 v[132:133], v[124:125], v[156:157], v[132:133]
	v_pk_fma_f32 v[176:177], v[184:185], v[162:163], v[176:177]
	v_pk_mul_f32 v[120:121], v[120:121], v[232:233] op_sel_hi:[1,0]
	v_exp_f32_e32 v169, v176
	v_exp_f32_e32 v179, v177
	v_pk_fma_f32 v[170:171], v[236:237], v[140:141], v[170:171]
	v_add_f32_e32 v169, 1.0, v169
	v_rcp_f32_e32 v178, v169
	v_add_f32_e32 v169, 1.0, v179
	v_rcp_f32_e32 v179, v169
	v_pk_fma_f32 v[132:133], v[116:117], v[160:161], v[132:133]
	v_pk_fma_f32 v[170:171], v[120:121], v[144:145], v[170:171]
	v_pk_fma_f32 v[172:173], v[138:139], v[172:173], v[150:151]
	v_pk_mul_f32 v[122:123], v[122:123], v[232:233] op_sel_hi:[1,0]
	v_pk_mul_f32 v[126:127], v[170:171], v[126:127]
; __device__ __forceinline__ unsigned pk2(float lo, float hi) { f32x2_t v = {lo, hi}; bf16x2_t b = __builtin_convertvector(v, bf16x2_t); return __builtin_bit_cast(unsigned, b); }
; __device__ __forceinline__ float sigmoidf_(float v) { return fast_rcp(1.0f + fast_exp2(-v * LOG2E)); }
;     __device__ __forceinline__ void run(const f32x4 (&acc)[2][2][4][2], const Unit& u, const Unit& nxt, bool has_next, int ui, int wr, int wc, int fr_in, int fq_in) const {
;     ...
;             for (int ai = 0; ai < 2; ++ai) {
;                 const int grp = 2 * ai + wr;
;                 f32x4 hg2 = {0.f, 0.f, 0.f, 0.f}, hg3 = hg2, hv2 = hg2, hv3 = hg2;
;                 if (grp > 0 && fr == 0) { const PG8_LAS float* xp = xr + ((grp - 1) * 2) * 256 + cl;
;                     hg2 = *(const PG8_LAS f32x4*)(xp); hg3 = *(const PG8_LAS f32x4*)(xp + 256); hv2 = *(const PG8_LAS f32x4*)(xp + 128); hv3 = *(const PG8_LAS f32x4*)(xp + 256 + 128); }
;                 f32x4 pg2, pg1, pv2, pv1;
;                 {
;                     const f32x4 g2 = acc[ai][0][2][n] * rs[ai][2], g3 = acc[ai][0][3][n] * rs[ai][3], v2 = acc[ai][1][2][n] * rs[ai][2], v3 = acc[ai][1][3][n] * rs[ai][3];
; #pragma unroll
;                     for (int i = 0; i < 4; ++i) {
;                         float a0 = g2[i], a1 = g3[i], a2 = v2[i], a3 = v3[i];
;                         asm volatile("" : "+v"(a0), "+v"(a1), "+v"(a2), "+v"(a3));
;                         const float t0 = DPPF(a0, 0x111), t1 = DPPF(a1, 0x111), t2 = DPPF(a2, 0x111), t3 = DPPF(a3, 0x111);
;                         pg2[i] = t0 + hg2[i]; pg1[i] = t1 + hg3[i]; pv2[i] = t2 + hv2[i]; pv1[i] = t3 + hv3[i]; }
;                 }
; #pragma unroll
;                 for (int m = 0; m < 4; ++m) {
;                     const f32x4 gc = acc[ai][0][m][n] * rs[ai][m], vc = acc[ai][1][m][n] * rs[ai][m];
;                     const f32x4 cgt = bg + wg0 * pg2 + wg1 * pg1 + wg2 * gc, cvl = bv + wv0 * pv2 + wv1 * pv1 + wv2 * vc;
;                     float a[4];
; #pragma unroll
;                     for (int i = 0; i < 4; ++i) a[i] = cgt[i] * sigmoidf_(cgt[i]) * cvl[i];
;                     u32x2 w; w.x = pk2(a[0], a[1]); w.y = pk2(a[2], a[3]);
;                     *(u32x2*)(A + (size_t)(u.pm * BM + ai * 128 + wr * 64 + 4 * fr + m) * DFF + ch) = w;
;                     pg2 = pg1; pg1 = gc; pv2 = pv1; pv1 = vc;
;                 }
	v_pk_mul_f32 v[170:171], v[176:177], v[178:179]
	v_pk_fma_f32 v[172:173], v[130:131], v[142:143], v[172:173]
	v_exp_f32_e32 v169, v132
	v_pk_fma_f32 v[172:173], v[122:123], v[146:147], v[172:173]
	v_exp_f32_e32 v176, v133
	v_pk_mul_f32 v[170:171], v[172:173], v[170:171]
	v_cvt_pk_bf16_f32 v172, v126, v127
	v_or_b32_e32 v126, 1, v231
	v_mad_i64_i32 v[126:127], s[0:1], v126, s74, v[182:183]
	v_cvt_pk_bf16_f32 v173, v170, v171
	v_lshl_add_u64 v[170:171], v[126:127], 0, v[174:175]
	v_add_f32_e32 v169, 1.0, v169
	global_store_dwordx2 v[170:171], v[172:173], off
	v_rcp_f32_e32 v170, v169
	v_add_f32_e32 v169, 1.0, v176
	v_rcp_f32_e32 v171, v169
	v_pk_fma_f32 v[134:135], v[134:135], v[154:155], v[166:167]
	v_pk_mul_f32 v[118:119], v[118:119], v[102:103] op_sel_hi:[1,0]
	v_pk_fma_f32 v[134:135], v[184:185], v[158:159], v[134:135]
	v_pk_mul_f32 v[132:133], v[132:133], v[170:171]
	v_pk_fma_f32 v[134:135], v[118:119], v[162:163], v[134:135]
	v_pk_mul_f32 v[112:113], v[112:113], v[102:103] op_sel_hi:[1,0]
	v_exp_f32_e32 v173, v135
	v_pk_fma_f32 v[170:171], v[236:237], v[136:137], v[148:149]
	v_pk_fma_f32 v[124:125], v[124:125], v[152:153], v[164:165]
	v_pk_fma_f32 v[170:171], v[120:121], v[140:141], v[170:171]
	v_pk_fma_f32 v[116:117], v[116:117], v[156:157], v[124:125]
	v_pk_fma_f32 v[170:171], v[112:113], v[144:145], v[170:171]
	v_pk_mul_f32 v[132:133], v[170:171], v[132:133]
	v_mov_b32_e32 v170, v103
	v_pk_mul_f32 v[108:109], v[108:109], v[170:171] op_sel_hi:[1,0]
	v_pk_mul_f32 v[110:111], v[110:111], v[170:171] op_sel_hi:[1,0]
	v_pk_fma_f32 v[108:109], v[108:109], v[160:161], v[116:117]
	v_exp_f32_e32 v169, v134
	v_exp_f32_e32 v116, v108
	v_exp_f32_e32 v117, v109
	v_add_f32_e32 v169, 1.0, v169
	v_rcp_f32_e32 v172, v169
	v_add_f32_e32 v116, 1.0, v116
	v_add_f32_e32 v117, 1.0, v117
	v_rcp_f32_e32 v116, v116
	v_rcp_f32_e32 v117, v117
	v_add_f32_e32 v169, 1.0, v173
	v_rcp_f32_e32 v173, v169
	v_pk_mul_f32 v[104:105], v[104:105], v[170:171] op_sel_hi:[1,0]
	v_pk_mul_f32 v[108:109], v[108:109], v[116:117]
	v_pk_fma_f32 v[116:117], v[184:185], v[154:155], v[166:167]
	v_pk_mul_f32 v[114:115], v[114:115], v[102:103] op_sel_hi:[1,0]
	v_pk_fma_f32 v[116:117], v[118:119], v[158:159], v[116:117]
	v_pk_fma_f32 v[130:131], v[130:131], v[138:139], v[150:151]
	v_pk_fma_f32 v[110:111], v[110:111], v[162:163], v[116:117]
	v_pk_fma_f32 v[130:131], v[122:123], v[142:143], v[130:131]
	v_exp_f32_e32 v118, v110
	v_exp_f32_e32 v119, v111
	v_pk_fma_f32 v[116:117], v[120:121], v[136:137], v[148:149]
	v_add_f32_e32 v118, 1.0, v118
	v_rcp_f32_e32 v118, v118
	v_add_f32_e32 v119, 1.0, v119
	v_rcp_f32_e32 v119, v119
	v_pk_fma_f32 v[112:113], v[112:113], v[140:141], v[116:117]
	v_pk_mul_f32 v[106:107], v[106:107], v[170:171] op_sel_hi:[1,0]
	v_pk_fma_f32 v[104:105], v[104:105], v[144:145], v[112:113]
	v_pk_mul_f32 v[134:135], v[134:135], v[172:173]
	v_pk_mul_f32 v[104:105], v[104:105], v[108:109]
	v_pk_mul_f32 v[108:109], v[110:111], v[118:119]
	v_pk_fma_f32 v[110:111], v[122:123], v[138:139], v[150:151]
	v_pk_fma_f32 v[130:131], v[114:115], v[146:147], v[130:131]
	v_pk_fma_f32 v[110:111], v[114:115], v[142:143], v[110:111]
	v_pk_mul_f32 v[130:131], v[130:131], v[134:135]
	v_pk_fma_f32 v[106:107], v[106:107], v[146:147], v[110:111]
	v_cvt_pk_bf16_f32 v135, v130, v131
	v_pk_mul_f32 v[106:107], v[106:107], v[108:109]
	v_or_b32_e32 v130, 2, v231
	v_cvt_pk_bf16_f32 v104, v104, v105
	v_cvt_pk_bf16_f32 v105, v106, v107
	v_or_b32_e32 v106, 3, v231
	v_cvt_pk_bf16_f32 v134, v132, v133
	v_mad_i64_i32 v[132:133], s[0:1], v130, s74, v[182:183]
	v_mad_i64_i32 v[172:173], s[0:1], v106, s74, v[182:183]
	v_lshl_add_u64 v[130:131], v[132:133], 0, v[174:175]
	v_lshl_add_u64 v[106:107], v[172:173], 0, v[174:175]
	global_store_dwordx2 v[130:131], v[134:135], off
	global_store_dwordx2 v[106:107], v[104:105], off
	s_and_b64 s[14:15], s[30:31], s[14:15]
	v_mov_b32_e32 v169, 0
	v_mov_b32_e32 v170, 0
	v_mov_b32_e32 v171, 0
	v_mov_b32_e32 v104, 0
	v_mov_b32_e32 v105, 0
	v_mov_b32_e32 v106, 0
	v_mov_b32_e32 v107, 0
	v_mov_b32_e32 v108, 0
	v_mov_b32_e32 v109, 0
	v_mov_b32_e32 v110, 0
	v_mov_b32_e32 v111, 0
	v_mov_b32_e32 v112, 0
	v_mov_b32_e32 v113, 0
	v_mov_b32_e32 v114, 0
	v_mov_b32_e32 v115, 0
	s_and_saveexec_b64 s[0:1], s[14:15]
	s_cbranch_execz .LBB0_721
	ds_read_b128 v[112:115], v230 offset:2048
	ds_read_b128 v[104:107], v230 offset:2560
	ds_read_b128 v[108:111], v230 offset:3072
	ds_read_b128 v[168:171], v230 offset:3584
; __device__ __forceinline__ unsigned pk2(float lo, float hi) { f32x2_t v = {lo, hi}; bf16x2_t b = __builtin_convertvector(v, bf16x2_t); return __builtin_bit_cast(unsigned, b); }
; __device__ __forceinline__ float sigmoidf_(float v) { return fast_rcp(1.0f + fast_exp2(-v * LOG2E)); }
;     __device__ __forceinline__ void run(const f32x4 (&acc)[2][2][4][2], const Unit& u, const Unit& nxt, bool has_next, int ui, int wr, int wc, int fr_in, int fq_in) const {
;     ...
;             for (int ai = 0; ai < 2; ++ai) {
;                 const int grp = 2 * ai + wr;
;                 f32x4 hg2 = {0.f, 0.f, 0.f, 0.f}, hg3 = hg2, hv2 = hg2, hv3 = hg2;
;                 if (grp > 0 && fr == 0) { const PG8_LAS float* xp = xr + ((grp - 1) * 2) * 256 + cl;
;                     hg2 = *(const PG8_LAS f32x4*)(xp); hg3 = *(const PG8_LAS f32x4*)(xp + 256); hv2 = *(const PG8_LAS f32x4*)(xp + 128); hv3 = *(const PG8_LAS f32x4*)(xp + 256 + 128); }
;                 f32x4 pg2, pg1, pv2, pv1;
;                 {
;                     const f32x4 g2 = acc[ai][0][2][n] * rs[ai][2], g3 = acc[ai][0][3][n] * rs[ai][3], v2 = acc[ai][1][2][n] * rs[ai][2], v3 = acc[ai][1][3][n] * rs[ai][3];
; #pragma unroll
;                     for (int i = 0; i < 4; ++i) {
;                         float a0 = g2[i], a1 = g3[i], a2 = v2[i], a3 = v3[i];
;                         asm volatile("" : "+v"(a0), "+v"(a1), "+v"(a2), "+v"(a3));
;                         const float t0 = DPPF(a0, 0x111), t1 = DPPF(a1, 0x111), t2 = DPPF(a2, 0x111), t3 = DPPF(a3, 0x111);
;                         pg2[i] = t0 + hg2[i]; pg1[i] = t1 + hg3[i]; pv2[i] = t2 + hv2[i]; pv1[i] = t3 + hv3[i]; }
;                 }
; #pragma unroll
;                 for (int m = 0; m < 4; ++m) {
;                     const f32x4 gc = acc[ai][0][m][n] * rs[ai][m], vc = acc[ai][1][m][n] * rs[ai][m];
;                     const f32x4 cgt = bg + wg0 * pg2 + wg1 * pg1 + wg2 * gc, cvl = bv + wv0 * pv2 + wv1 * pv1 + wv2 * vc;
;                     float a[4];
; #pragma unroll
;                     for (int i = 0; i < 4; ++i) a[i] = cgt[i] * sigmoidf_(cgt[i]) * cvl[i];
;                     u32x2 w; w.x = pk2(a[0], a[1]); w.y = pk2(a[2], a[3]);
;                     *(u32x2*)(A + (size_t)(u.pm * BM + ai * 128 + wr * 64 + 4 * fr + m) * DFF + ch) = w;
;                     pg2 = pg1; pg1 = gc; pv2 = pv1; pv1 = vc;
;                 }
.LBB0_721:
	s_or_b64 exec, exec, s[0:1]
	v_mul_f32_dpp v118, v68, v201 row_shr:1 row_mask:0xf bank_mask:0xf bound_ctrl:1
	v_mul_f32_dpp v120, v76, v200 row_shr:1 row_mask:0xf bank_mask:0xf bound_ctrl:1
	v_mul_f32_dpp v122, v64, v201 row_shr:1 row_mask:0xf bank_mask:0xf bound_ctrl:1
	v_mul_f32_dpp v116, v80, v200 row_shr:1 row_mask:0xf bank_mask:0xf bound_ctrl:1
	v_pk_mul_f32 v[96:97], v[96:97], v[72:73] op_sel_hi:[1,0]
	v_mul_f32_dpp v117, v81, v200 row_shr:1 row_mask:0xf bank_mask:0xf bound_ctrl:1
	s_waitcnt lgkmcnt(0)
	v_pk_add_f32 v[112:113], v[112:113], v[116:117]
	v_mul_f32_dpp v119, v69, v201 row_shr:1 row_mask:0xf bank_mask:0xf bound_ctrl:1
	v_pk_add_f32 v[108:109], v[108:109], v[118:119]
	v_pk_fma_f32 v[112:113], v[152:153], v[112:113], v[164:165]
	v_pk_fma_f32 v[112:113], v[156:157], v[108:109], v[112:113]
	v_pk_fma_f32 v[112:113], v[96:97], v[160:161], v[112:113]
	v_exp_f32_e32 v116, v112
	v_exp_f32_e32 v117, v113
	v_mul_f32_dpp v121, v77, v200 row_shr:1 row_mask:0xf bank_mask:0xf bound_ctrl:1
	v_mul_f32_dpp v123, v65, v201 row_shr:1 row_mask:0xf bank_mask:0xf bound_ctrl:1
	v_mul_f32_dpp v130, v70, v201 row_shr:1 row_mask:0xf bank_mask:0xf bound_ctrl:1
	v_mul_f32_dpp v134, v78, v200 row_shr:1 row_mask:0xf bank_mask:0xf bound_ctrl:1
	v_mul_f32_dpp v178, v66, v201 row_shr:1 row_mask:0xf bank_mask:0xf bound_ctrl:1
	v_mul_f32_dpp v124, v82, v200 row_shr:1 row_mask:0xf bank_mask:0xf bound_ctrl:1
	v_add_f32_e32 v116, 1.0, v116
	v_add_f32_e32 v117, 1.0, v117
	v_mul_f32_dpp v125, v83, v200 row_shr:1 row_mask:0xf bank_mask:0xf bound_ctrl:1
	v_rcp_f32_e32 v116, v116
	v_rcp_f32_e32 v117, v117
	v_mul_f32_dpp v131, v71, v201 row_shr:1 row_mask:0xf bank_mask:0xf bound_ctrl:1
	v_pk_add_f32 v[114:115], v[114:115], v[124:125]
	v_pk_add_f32 v[110:111], v[110:111], v[130:131]
	v_pk_fma_f32 v[114:115], v[154:155], v[114:115], v[166:167]
	v_pk_mul_f32 v[98:99], v[98:99], v[72:73] op_sel_hi:[1,0]
	v_pk_fma_f32 v[114:115], v[158:159], v[110:111], v[114:115]
	v_pk_mul_f32 v[112:113], v[112:113], v[116:117]
	v_pk_fma_f32 v[114:115], v[98:99], v[162:163], v[114:115]
	v_pk_add_f32 v[104:105], v[104:105], v[120:121]
	v_exp_f32_e32 v116, v114
	v_exp_f32_e32 v117, v115
	v_pk_add_f32 v[118:119], v[168:169], v[122:123]
	v_add_f32_e32 v116, 1.0, v116
	v_add_f32_e32 v117, 1.0, v117
	v_rcp_f32_e32 v116, v116
	v_rcp_f32_e32 v117, v117
	v_pk_fma_f32 v[104:105], v[136:137], v[104:105], v[148:149]
	v_mul_f32_dpp v135, v79, v200 row_shr:1 row_mask:0xf bank_mask:0xf bound_ctrl:1
	v_pk_mul_f32 v[92:93], v[92:93], v[72:73] op_sel_hi:[1,0]
	v_pk_fma_f32 v[104:105], v[140:141], v[118:119], v[104:105]
	v_mul_f32_dpp v179, v67, v201 row_shr:1 row_mask:0xf bank_mask:0xf bound_ctrl:1
	v_pk_fma_f32 v[104:105], v[92:93], v[144:145], v[104:105]
	v_pk_add_f32 v[106:107], v[106:107], v[134:135]
	v_pk_mul_f32 v[114:115], v[114:115], v[116:117]
	v_mov_b32_e32 v116, v73
	v_pk_fma_f32 v[108:109], v[152:153], v[108:109], v[164:165]
	v_pk_mul_f32 v[104:105], v[104:105], v[112:113]
	v_pk_add_f32 v[112:113], v[170:171], v[178:179]
	v_pk_fma_f32 v[106:107], v[138:139], v[106:107], v[150:151]
	v_pk_mul_f32 v[88:89], v[88:89], v[116:117] op_sel_hi:[1,0]
	v_pk_fma_f32 v[108:109], v[96:97], v[156:157], v[108:109]
	v_pk_mul_f32 v[94:95], v[94:95], v[72:73] op_sel_hi:[1,0]
	v_pk_fma_f32 v[106:107], v[142:143], v[112:113], v[106:107]
	v_pk_fma_f32 v[108:109], v[88:89], v[160:161], v[108:109]
	v_pk_fma_f32 v[106:107], v[94:95], v[146:147], v[106:107]
	v_pk_mul_f32 v[106:107], v[106:107], v[114:115]
	v_exp_f32_e32 v117, v108
	v_exp_f32_e32 v120, v109
	v_add_u32_e32 v177, 0x80, v231
	v_cvt_pk_bf16_f32 v104, v104, v105
	v_cvt_pk_bf16_f32 v105, v106, v107
	v_mov_b64_e32 v[106:107], s[20:21]
	v_mad_i64_i32 v[122:123], s[0:1], v177, s74, v[106:107]
	v_lshl_add_u64 v[114:115], v[122:123], 0, v[174:175]
	global_store_dwordx2 v[114:115], v[104:105], off
	v_add_f32_e32 v104, 1.0, v117
	v_add_f32_e32 v105, 1.0, v120
	v_rcp_f32_e32 v104, v104
	v_rcp_f32_e32 v105, v105
	v_pk_mul_f32 v[90:91], v[90:91], v[116:117] op_sel_hi:[1,0]
	v_pk_mul_f32 v[84:85], v[84:85], v[116:117] op_sel_hi:[1,0]
	v_pk_fma_f32 v[96:97], v[96:97], v[152:153], v[164:165]
	v_pk_mul_f32 v[104:105], v[108:109], v[104:105]
	v_pk_fma_f32 v[108:109], v[154:155], v[110:111], v[166:167]
	v_pk_mul_f32 v[86:87], v[86:87], v[116:117] op_sel_hi:[1,0]
	v_pk_fma_f32 v[108:109], v[98:99], v[158:159], v[108:109]
	v_pk_mul_f32 v[80:81], v[80:81], v[74:75] op_sel_hi:[1,0]
	v_pk_fma_f32 v[108:109], v[90:91], v[162:163], v[108:109]
	v_pk_fma_f32 v[96:97], v[88:89], v[156:157], v[96:97]
	v_exp_f32_e32 v114, v108
	v_exp_f32_e32 v115, v109
	v_pk_fma_f32 v[110:111], v[136:137], v[118:119], v[148:149]
	v_add_f32_e32 v114, 1.0, v114
	v_rcp_f32_e32 v114, v114
	v_add_f32_e32 v115, 1.0, v115
	v_rcp_f32_e32 v115, v115
	v_pk_fma_f32 v[110:111], v[92:93], v[140:141], v[110:111]
	v_pk_fma_f32 v[96:97], v[80:81], v[160:161], v[96:97]
	v_pk_fma_f32 v[110:111], v[84:85], v[144:145], v[110:111]
	v_pk_mul_f32 v[108:109], v[108:109], v[114:115]
	v_pk_mul_f32 v[104:105], v[110:111], v[104:105]
	v_pk_fma_f32 v[110:111], v[138:139], v[112:113], v[150:151]
	v_cvt_pk_bf16_f32 v104, v104, v105
	v_pk_fma_f32 v[110:111], v[94:95], v[142:143], v[110:111]
	v_pk_fma_f32 v[98:99], v[98:99], v[154:155], v[166:167]
	v_pk_fma_f32 v[110:111], v[86:87], v[146:147], v[110:111]
	v_pk_mul_f32 v[82:83], v[82:83], v[74:75] op_sel_hi:[1,0]
	v_pk_mul_f32 v[108:109], v[110:111], v[108:109]
	v_exp_f32_e32 v110, v96
	v_exp_f32_e32 v111, v97
	v_cvt_pk_bf16_f32 v105, v108, v109
	v_add_u32_e32 v108, 0x81, v231
	v_mad_i64_i32 v[124:125], s[0:1], v108, s74, v[106:107]
	v_lshl_add_u64 v[108:109], v[124:125], 0, v[174:175]
;     __device__ __forceinline__ void run(const f32x4 (&acc)[2][2][4][2], const Unit& u, const Unit& nxt, bool has_next, int ui, int wr, int wc, int fr_in, int fq_in) const {
;     ...
;         for (int n = 0; n < 2; ++n) {
;             const int cl = wc * 32 + n * 16 + 4 * fq, ch = u.pn * 128 + cl;
;             const PG8_LAS float* pp = prm + slot * 1024 + cl;
;             const f32x4 wg0 = *(const PG8_LAS f32x4*)(pp), wg1 = *(const PG8_LAS f32x4*)(pp + 128), wg2 = *(const PG8_LAS f32x4*)(pp + 256), bg = *(const PG8_LAS f32x4*)(pp + 384);
;             const f32x4 wv0 = *(const PG8_LAS f32x4*)(pp + 512), wv1 = *(const PG8_LAS f32x4*)(pp + 640), wv2 = *(const PG8_LAS f32x4*)(pp + 768), bv = *(const PG8_LAS f32x4*)(pp + 896);
; #pragma unroll
;             for (int ai = 0; ai < 2; ++ai) {
;                 const int grp = 2 * ai + wr;
;                 f32x4 hg2 = {0.f, 0.f, 0.f, 0.f}, hg3 = hg2, hv2 = hg2, hv3 = hg2;
;                 if (grp > 0 && fr == 0) { const PG8_LAS float* xp = xr + ((grp - 1) * 2) * 256 + cl;
;                     hg2 = *(const PG8_LAS f32x4*)(xp); hg3 = *(const PG8_LAS f32x4*)(xp + 256); hv2 = *(const PG8_LAS f32x4*)(xp + 128); hv3 = *(const PG8_LAS f32x4*)(xp + 256 + 128); }
;                 f32x4 pg2, pg1, pv2, pv1;
;                 {
;                     const f32x4 g2 = acc[ai][0][2][n] * rs[ai][2], g3 = acc[ai][0][3][n] * rs[ai][3], v2 = acc[ai][1][2][n] * rs[ai][2], v3 = acc[ai][1][3][n] * rs[ai][3];
; #pragma unroll
;                     for (int i = 0; i < 4; ++i) {
;                         float a0 = g2[i], a1 = g3[i], a2 = v2[i], a3 = v3[i];
;                         asm volatile("" : "+v"(a0), "+v"(a1), "+v"(a2), "+v"(a3));
;                         const float t0 = DPPF(a0, 0x111), t1 = DPPF(a1, 0x111), t2 = DPPF(a2, 0x111), t3 = DPPF(a3, 0x111);
;                         pg2[i] = t0 + hg2[i]; pg1[i] = t1 + hg3[i]; pv2[i] = t2 + hv2[i]; pv1[i] = t3 + hv3[i]; }
;                 }
; #pragma unroll
;                 for (int m = 0; m < 4; ++m) {
;                     const f32x4 gc = acc[ai][0][m][n] * rs[ai][m], vc = acc[ai][1][m][n] * rs[ai][m];
;                     const f32x4 cgt = bg + wg0 * pg2 + wg1 * pg1 + wg2 * gc, cvl = bv + wv0 * pv2 + wv1 * pv1 + wv2 * vc;
;                     float a[4];
; #pragma unroll
;                     for (int i = 0; i < 4; ++i) a[i] = cgt[i] * sigmoidf_(cgt[i]) * cvl[i];
	global_store_dwordx2 v[108:109], v[104:105], off
	v_add_f32_e32 v104, 1.0, v110
	v_add_f32_e32 v105, 1.0, v111
	v_rcp_f32_e32 v104, v104
	v_rcp_f32_e32 v105, v105
	v_pk_fma_f32 v[98:99], v[90:91], v[158:159], v[98:99]
	v_pk_fma_f32 v[92:93], v[92:93], v[136:137], v[148:149]
	v_pk_fma_f32 v[98:99], v[82:83], v[162:163], v[98:99]
	v_pk_mul_f32 v[96:97], v[96:97], v[104:105]
	v_exp_f32_e32 v104, v98
	v_exp_f32_e32 v105, v99
	v_pk_mul_f32 v[76:77], v[76:77], v[74:75] op_sel_hi:[1,0]
	v_pk_fma_f32 v[92:93], v[84:85], v[140:141], v[92:93]
	v_add_f32_e32 v104, 1.0, v104
	v_add_f32_e32 v105, 1.0, v105
	v_rcp_f32_e32 v104, v104
	v_rcp_f32_e32 v105, v105
	v_pk_fma_f32 v[94:95], v[94:95], v[138:139], v[150:151]
	v_pk_mul_f32 v[78:79], v[78:79], v[74:75] op_sel_hi:[1,0]
	v_pk_fma_f32 v[92:93], v[76:77], v[144:145], v[92:93]
	v_pk_fma_f32 v[94:95], v[86:87], v[142:143], v[94:95]
	v_pk_mul_f32 v[92:93], v[92:93], v[96:97]
	v_pk_mul_f32 v[96:97], v[98:99], v[104:105]
	v_pk_fma_f32 v[94:95], v[78:79], v[146:147], v[94:95]
	v_pk_fma_f32 v[88:89], v[152:153], v[88:89], v[164:165]
	v_pk_mul_f32 v[94:95], v[94:95], v[96:97]
	v_mov_b32_e32 v96, v75
	v_pk_mul_f32 v[68:69], v[68:69], v[96:97] op_sel_hi:[1,0]
	v_pk_fma_f32 v[80:81], v[156:157], v[80:81], v[88:89]
	v_pk_mul_f32 v[70:71], v[70:71], v[96:97] op_sel_hi:[1,0]
	v_pk_fma_f32 v[68:69], v[160:161], v[68:69], v[80:81]
	v_pk_mul_f32 v[64:65], v[64:65], v[96:97] op_sel_hi:[1,0]
	v_exp_f32_e32 v80, v68
	v_exp_f32_e32 v81, v69
	v_pk_mul_f32 v[66:67], v[66:67], v[96:97] op_sel_hi:[1,0]
	v_cvt_pk_bf16_f32 v92, v92, v93
	v_add_f32_e32 v80, 1.0, v80
	v_add_f32_e32 v81, 1.0, v81
	v_rcp_f32_e32 v80, v80
	v_rcp_f32_e32 v81, v81
	v_cvt_pk_bf16_f32 v93, v94, v95
	v_add_u32_e32 v94, 0x82, v231
	v_mad_i64_i32 v[130:131], s[0:1], v94, s74, v[106:107]
	v_pk_mul_f32 v[68:69], v[68:69], v[80:81]
	v_pk_fma_f32 v[80:81], v[154:155], v[90:91], v[166:167]
	v_lshl_add_u64 v[94:95], v[130:131], 0, v[174:175]
	v_pk_fma_f32 v[80:81], v[158:159], v[82:83], v[80:81]
	global_store_dwordx2 v[94:95], v[92:93], off
	v_pk_fma_f32 v[70:71], v[162:163], v[70:71], v[80:81]
	v_add_u32_e32 v176, 16, v202
	v_exp_f32_e32 v82, v70
	v_exp_f32_e32 v83, v71
	v_pk_fma_f32 v[80:81], v[84:85], v[136:137], v[148:149]
	v_add_f32_e32 v82, 1.0, v82
	v_rcp_f32_e32 v82, v82
	v_add_f32_e32 v83, 1.0, v83
	v_rcp_f32_e32 v83, v83
	v_pk_fma_f32 v[76:77], v[76:77], v[140:141], v[80:81]
	v_mov_b32_e32 v104, 0
	v_pk_fma_f32 v[64:65], v[64:65], v[144:145], v[76:77]
	v_mov_b32_e32 v108, 0
	v_pk_mul_f32 v[64:65], v[64:65], v[68:69]
	v_pk_mul_f32 v[68:69], v[70:71], v[82:83]
	v_pk_fma_f32 v[70:71], v[86:87], v[138:139], v[150:151]
	v_cvt_pk_bf16_f32 v64, v64, v65
	v_pk_fma_f32 v[70:71], v[78:79], v[142:143], v[70:71]
	v_mov_b32_e32 v109, 0
	v_pk_fma_f32 v[66:67], v[66:67], v[146:147], v[70:71]
	v_mov_b32_e32 v110, 0
	v_pk_mul_f32 v[66:67], v[66:67], v[68:69]
	v_mov_b32_e32 v111, 0
	v_cvt_pk_bf16_f32 v65, v66, v67
	v_add_u32_e32 v66, 0x83, v231
	v_mad_i64_i32 v[134:135], s[0:1], v66, s74, v[106:107]
	v_lshl_add_u64 v[66:67], v[134:135], 0, v[174:175]
	global_store_dwordx2 v[66:67], v[64:65], off
	ds_read_b128 v[84:87], v203 offset:64
	ds_read_b128 v[88:91], v203 offset:576
	ds_read_b128 v[92:95], v203 offset:1088
	ds_read_b128 v[96:99], v203 offset:1600
	ds_read_b128 v[64:67], v203 offset:2112
	ds_read_b128 v[68:71], v203 offset:2624
	ds_read_b128 v[76:79], v203 offset:3136
	ds_read_b128 v[80:83], v203 offset:3648
	v_mov_b32_e32 v106, 0
	v_mov_b32_e32 v107, 0
	v_mov_b32_e32 v112, 0
	v_mov_b32_e32 v113, 0
	v_mov_b32_e32 v114, 0
	v_mov_b32_e32 v115, 0
	v_mov_b32_e32 v116, 0
	v_mov_b32_e32 v117, 0
	v_mov_b32_e32 v118, 0
	v_mov_b32_e32 v119, 0
	v_mov_b32_e32 v120, 0
	v_mov_b32_e32 v121, 0
	s_and_saveexec_b64 s[0:1], s[4:5]
	s_cbranch_execz .LBB0_723
	v_lshl_add_u32 v105, v176, 2, s71
	ds_read_b128 v[118:121], v105
	ds_read_b128 v[110:113], v105 offset:512
	ds_read_b128 v[114:117], v105 offset:1024
	ds_read_b128 v[106:109], v105 offset:1536
.LBB0_723:
	s_or_b64 exec, exec, s[0:1]
	v_mul_f32_dpp v146, v44, v198 row_shr:1 row_mask:0xf bank_mask:0xf bound_ctrl:1
	s_nop 0
	v_mul_f32_dpp v152, v32, v199 row_shr:1 row_mask:0xf bank_mask:0xf bound_ctrl:1
	v_mul_f32_dpp v150, v40, v198 row_shr:1 row_mask:0xf bank_mask:0xf bound_ctrl:1
	v_mul_f32_dpp v148, v36, v199 row_shr:1 row_mask:0xf bank_mask:0xf bound_ctrl:1
	v_mul_f32_dpp v149, v37, v199 row_shr:1 row_mask:0xf bank_mask:0xf bound_ctrl:1
	v_mul_f32_dpp v147, v45, v198 row_shr:1 row_mask:0xf bank_mask:0xf bound_ctrl:1
	v_mul_f32_dpp v151, v41, v198 row_shr:1 row_mask:0xf bank_mask:0xf bound_ctrl:1
	v_mul_f32_dpp v153, v33, v199 row_shr:1 row_mask:0xf bank_mask:0xf bound_ctrl:1
	v_mul_f32_dpp v154, v46, v198 row_shr:1 row_mask:0xf bank_mask:0xf bound_ctrl:1
	v_mul_f32_dpp v160, v34, v199 row_shr:1 row_mask:0xf bank_mask:0xf bound_ctrl:1
	s_waitcnt lgkmcnt(0)
; __device__ __forceinline__ unsigned pk2(float lo, float hi) { f32x2_t v = {lo, hi}; bf16x2_t b = __builtin_convertvector(v, bf16x2_t); return __builtin_bit_cast(unsigned, b); }
; #define DPPF(v, ctrl) __builtin_bit_cast(float, __builtin_amdgcn_update_dpp(0, __builtin_bit_cast(int, (v)), (ctrl), 0xf, 0xf, false))
; __device__ __forceinline__ float sigmoidf_(float v) { return fast_rcp(1.0f + fast_exp2(-v * LOG2E)); }
;     __device__ __forceinline__ void run(const f32x4 (&acc)[2][2][4][2], const Unit& u, const Unit& nxt, bool has_next, int ui, int wr, int wc, int fr_in, int fq_in) const {
;     ...
;                     const f32x4 g2 = acc[ai][0][2][n] * rs[ai][2], g3 = acc[ai][0][3][n] * rs[ai][3], v2 = acc[ai][1][2][n] * rs[ai][2], v3 = acc[ai][1][3][n] * rs[ai][3];
; #pragma unroll
;                     for (int i = 0; i < 4; ++i) {
;                         float a0 = g2[i], a1 = g3[i], a2 = v2[i], a3 = v3[i];
;                         asm volatile("" : "+v"(a0), "+v"(a1), "+v"(a2), "+v"(a3));
;                         const float t0 = DPPF(a0, 0x111), t1 = DPPF(a1, 0x111), t2 = DPPF(a2, 0x111), t3 = DPPF(a3, 0x111);
;                         pg2[i] = t0 + hg2[i]; pg1[i] = t1 + hg3[i]; pv2[i] = t2 + hv2[i]; pv1[i] = t3 + hv3[i]; }
;                 }
; #pragma unroll
;                 for (int m = 0; m < 4; ++m) {
;                     const f32x4 gc = acc[ai][0][m][n] * rs[ai][m], vc = acc[ai][1][m][n] * rs[ai][m];
;                     const f32x4 cgt = bg + wg0 * pg2 + wg1 * pg1 + wg2 * gc, cvl = bv + wv0 * pv2 + wv1 * pv1 + wv2 * vc;
;                     float a[4];
; #pragma unroll
;                     for (int i = 0; i < 4; ++i) a[i] = cgt[i] * sigmoidf_(cgt[i]) * cvl[i];
;                     u32x2 w; w.x = pk2(a[0], a[1]); w.y = pk2(a[2], a[3]);
;                     *(u32x2*)(A + (size_t)(u.pm * BM + ai * 128 + wr * 64 + 4 * fr + m) * DFF + ch) = w;
	v_pk_add_f32 v[118:119], v[118:119], v[146:147]
	v_mov_b32_e32 v140, v100
	v_mov_b32_e32 v141, v100
	v_mul_f32_dpp v158, v42, v198 row_shr:1 row_mask:0xf bank_mask:0xf bound_ctrl:1
	v_pk_add_f32 v[114:115], v[114:115], v[148:149]
	v_pk_fma_f32 v[118:119], v[84:85], v[118:119], v[96:97]
	v_mul_f32_dpp v157, v39, v199 row_shr:1 row_mask:0xf bank_mask:0xf bound_ctrl:1
	v_pk_mul_f32 v[60:61], v[60:61], v[140:141]
	v_pk_fma_f32 v[118:119], v[88:89], v[114:115], v[118:119]
	v_mul_f32_dpp v159, v43, v198 row_shr:1 row_mask:0xf bank_mask:0xf bound_ctrl:1
	v_pk_fma_f32 v[118:119], v[60:61], v[92:93], v[118:119]
	v_mul_f32_dpp v156, v38, v199 row_shr:1 row_mask:0xf bank_mask:0xf bound_ctrl:1
	v_mul_f32_dpp v161, v35, v199 row_shr:1 row_mask:0xf bank_mask:0xf bound_ctrl:1
	v_mov_b32_e32 v162, v100
	v_mov_b32_e32 v163, v100
	v_mul_f32_dpp v155, v47, v198 row_shr:1 row_mask:0xf bank_mask:0xf bound_ctrl:1
	v_exp_f32_e32 v100, v118
	v_exp_f32_e32 v105, v119
	v_pk_mul_f32 v[140:141], v[56:57], v[140:141]
	v_add_f32_e32 v100, 1.0, v100
	v_rcp_f32_e32 v146, v100
	v_add_f32_e32 v100, 1.0, v105
	v_rcp_f32_e32 v147, v100
	v_pk_add_f32 v[56:57], v[110:111], v[150:151]
	v_pk_add_f32 v[116:117], v[116:117], v[156:157]
	v_pk_mul_f32 v[62:63], v[62:63], v[162:163]
	v_pk_mul_f32 v[110:111], v[118:119], v[146:147]
	v_pk_add_f32 v[118:119], v[120:121], v[154:155]
	v_pk_add_f32 v[106:107], v[106:107], v[152:153]
	v_pk_fma_f32 v[118:119], v[86:87], v[118:119], v[98:99]
	v_pk_fma_f32 v[56:57], v[64:65], v[56:57], v[80:81]
	v_pk_fma_f32 v[118:119], v[90:91], v[116:117], v[118:119]
	v_pk_fma_f32 v[56:57], v[68:69], v[106:107], v[56:57]
	v_pk_fma_f32 v[118:119], v[62:63], v[94:95], v[118:119]
	v_pk_fma_f32 v[56:57], v[140:141], v[76:77], v[56:57]
	v_exp_f32_e32 v100, v118
	v_exp_f32_e32 v105, v119
	v_pk_mul_f32 v[56:57], v[56:57], v[110:111]
	v_add_f32_e32 v100, 1.0, v100
	v_rcp_f32_e32 v120, v100
	v_add_f32_e32 v100, 1.0, v105
	v_rcp_f32_e32 v121, v100
	v_pk_add_f32 v[110:111], v[112:113], v[158:159]
	v_pk_add_f32 v[108:109], v[108:109], v[160:161]
	v_pk_fma_f32 v[110:111], v[66:67], v[110:111], v[82:83]
	v_add_u32_e32 v144, s16, v176
	v_pk_mul_f32 v[58:59], v[58:59], v[162:163]
	v_pk_fma_f32 v[110:111], v[70:71], v[108:109], v[110:111]
	v_ashrrev_i32_e32 v145, 31, v144
	v_pk_mul_f32 v[112:113], v[118:119], v[120:121]
	v_pk_fma_f32 v[110:111], v[58:59], v[78:79], v[110:111]
	v_mov_b32_e32 v142, v101
	v_pk_mul_f32 v[110:111], v[110:111], v[112:113]
	v_cvt_pk_bf16_f32 v112, v56, v57
	v_lshlrev_b64 v[56:57], 1, v[144:145]
	v_cvt_pk_bf16_f32 v113, v110, v111
	v_lshl_add_u64 v[110:111], v[128:129], 0, v[56:57]
	v_mov_b32_e32 v143, v101
	global_store_dwordx2 v[110:111], v[112:113], off
	v_pk_fma_f32 v[110:111], v[84:85], v[114:115], v[96:97]
	v_pk_mul_f32 v[52:53], v[52:53], v[142:143]
	v_pk_fma_f32 v[110:111], v[60:61], v[88:89], v[110:111]
	v_pk_fma_f32 v[106:107], v[64:65], v[106:107], v[80:81]
	v_pk_fma_f32 v[110:111], v[52:53], v[92:93], v[110:111]
	v_pk_mul_f32 v[48:49], v[48:49], v[142:143]
	v_exp_f32_e32 v105, v110
	v_exp_f32_e32 v113, v111
	v_mov_b32_e32 v100, v101
	v_add_f32_e32 v105, 1.0, v105
	v_rcp_f32_e32 v112, v105
	v_add_f32_e32 v105, 1.0, v113
	v_rcp_f32_e32 v113, v105
	v_pk_mul_f32 v[54:55], v[54:55], v[100:101]
	v_pk_mul_f32 v[50:51], v[50:51], v[100:101]
	v_pk_fma_f32 v[106:107], v[140:141], v[68:69], v[106:107]
	v_pk_mul_f32 v[100:101], v[110:111], v[112:113]
	v_pk_fma_f32 v[110:111], v[86:87], v[116:117], v[98:99]
	v_pk_fma_f32 v[108:109], v[66:67], v[108:109], v[82:83]
	v_pk_fma_f32 v[110:111], v[62:63], v[90:91], v[110:111]
	v_pk_fma_f32 v[106:107], v[48:49], v[76:77], v[106:107]
	v_pk_fma_f32 v[110:111], v[54:55], v[94:95], v[110:111]
	v_pk_fma_f32 v[108:109], v[58:59], v[70:71], v[108:109]
	v_exp_f32_e32 v105, v110
	v_exp_f32_e32 v113, v111
	v_mov_b32_e32 v138, v102
	v_add_f32_e32 v105, 1.0, v105
	v_rcp_f32_e32 v112, v105
	v_add_f32_e32 v105, 1.0, v113
	v_rcp_f32_e32 v113, v105
	v_mov_b32_e32 v139, v102
	v_pk_mul_f32 v[100:101], v[106:107], v[100:101]
	v_pk_fma_f32 v[108:109], v[50:51], v[78:79], v[108:109]
	v_pk_mul_f32 v[106:107], v[110:111], v[112:113]
	v_pk_fma_f32 v[60:61], v[60:61], v[84:85], v[96:97]
	v_pk_mul_f32 v[106:107], v[108:109], v[106:107]
	v_pk_mul_f32 v[44:45], v[44:45], v[138:139]
	v_pk_fma_f32 v[60:61], v[52:53], v[88:89], v[60:61]
	v_cvt_pk_bf16_f32 v100, v100, v101
	v_cvt_pk_bf16_f32 v101, v106, v107
	v_lshl_add_u64 v[106:107], v[126:127], 0, v[56:57]
	v_pk_fma_f32 v[60:61], v[44:45], v[92:93], v[60:61]
	v_mov_b32_e32 v136, v103
	v_mov_b32_e32 v137, v103
	global_store_dwordx2 v[106:107], v[100:101], off
	v_pk_fma_f32 v[52:53], v[52:53], v[84:85], v[96:97]
	v_exp_f32_e32 v105, v60
	v_pk_mul_f32 v[36:37], v[36:37], v[136:137]
	v_pk_fma_f32 v[44:45], v[44:45], v[88:89], v[52:53]
	v_exp_f32_e32 v107, v61
	v_pk_fma_f32 v[36:37], v[36:37], v[92:93], v[44:45]
	v_mov_b32_e32 v100, v102
	v_mov_b32_e32 v101, v102
	v_pk_fma_f32 v[62:63], v[62:63], v[86:87], v[98:99]
	v_pk_mul_f32 v[46:47], v[46:47], v[100:101]
	v_pk_fma_f32 v[62:63], v[54:55], v[90:91], v[62:63]
	v_exp_f32_e32 v44, v36
	v_exp_f32_e32 v45, v37
	v_add_f32_e32 v102, 1.0, v105
	v_pk_fma_f32 v[62:63], v[46:47], v[94:95], v[62:63]
	v_rcp_f32_e32 v106, v102
	v_add_f32_e32 v102, 1.0, v107
	v_pk_mul_f32 v[42:43], v[42:43], v[100:101]
	v_rcp_f32_e32 v107, v102
	v_exp_f32_e32 v102, v62
	v_exp_f32_e32 v105, v63
	v_add_f32_e32 v44, 1.0, v44
	v_add_f32_e32 v45, 1.0, v45
	v_rcp_f32_e32 v44, v44
	v_rcp_f32_e32 v45, v45
	v_add_f32_e32 v102, 1.0, v102
	v_pk_mul_f32 v[60:61], v[60:61], v[106:107]
	v_rcp_f32_e32 v106, v102
	v_add_f32_e32 v102, 1.0, v105
	v_rcp_f32_e32 v107, v102
; __device__ __forceinline__ unsigned pk2(float lo, float hi) { f32x2_t v = {lo, hi}; bf16x2_t b = __builtin_convertvector(v, bf16x2_t); return __builtin_bit_cast(unsigned, b); }
; #define DPPF(v, ctrl) __builtin_bit_cast(float, __builtin_amdgcn_update_dpp(0, __builtin_bit_cast(int, (v)), (ctrl), 0xf, 0xf, false))
; __device__ __forceinline__ float sigmoidf_(float v) { return fast_rcp(1.0f + fast_exp2(-v * LOG2E)); }
; #define PG8_LAS __attribute__((address_space(3)))
;     __device__ __forceinline__ void run(const f32x4 (&acc)[2][2][4][2], const Unit& u, const Unit& nxt, bool has_next, int ui, int wr, int wc, int fr_in, int fq_in) const {
;     ...
;                 if (grp > 0 && fr == 0) { const PG8_LAS float* xp = xr + ((grp - 1) * 2) * 256 + cl;
;                     hg2 = *(const PG8_LAS f32x4*)(xp); hg3 = *(const PG8_LAS f32x4*)(xp + 256); hv2 = *(const PG8_LAS f32x4*)(xp + 128); hv3 = *(const PG8_LAS f32x4*)(xp + 256 + 128); }
;                 f32x4 pg2, pg1, pv2, pv1;
;                 {
;                     const f32x4 g2 = acc[ai][0][2][n] * rs[ai][2], g3 = acc[ai][0][3][n] * rs[ai][3], v2 = acc[ai][1][2][n] * rs[ai][2], v3 = acc[ai][1][3][n] * rs[ai][3];
; #pragma unroll
;                     for (int i = 0; i < 4; ++i) {
;                         float a0 = g2[i], a1 = g3[i], a2 = v2[i], a3 = v3[i];
;                         asm volatile("" : "+v"(a0), "+v"(a1), "+v"(a2), "+v"(a3));
;                         const float t0 = DPPF(a0, 0x111), t1 = DPPF(a1, 0x111), t2 = DPPF(a2, 0x111), t3 = DPPF(a3, 0x111);
;                         pg2[i] = t0 + hg2[i]; pg1[i] = t1 + hg3[i]; pv2[i] = t2 + hv2[i]; pv1[i] = t3 + hv3[i]; }
;                 }
; #pragma unroll
;                 for (int m = 0; m < 4; ++m) {
;                     const f32x4 gc = acc[ai][0][m][n] * rs[ai][m], vc = acc[ai][1][m][n] * rs[ai][m];
;                     const f32x4 cgt = bg + wg0 * pg2 + wg1 * pg1 + wg2 * gc, cvl = bv + wv0 * pv2 + wv1 * pv1 + wv2 * vc;
;                     float a[4];
; #pragma unroll
;                     for (int i = 0; i < 4; ++i) a[i] = cgt[i] * sigmoidf_(cgt[i]) * cvl[i];
;                     u32x2 w; w.x = pk2(a[0], a[1]); w.y = pk2(a[2], a[3]);
;                     *(u32x2*)(A + (size_t)(u.pm * BM + ai * 128 + wr * 64 + 4 * fr + m) * DFF + ch) = w;
	v_mov_b32_e32 v102, v103
	v_pk_mul_f32 v[36:37], v[36:37], v[44:45]
	v_pk_fma_f32 v[44:45], v[54:55], v[86:87], v[98:99]
	v_pk_mul_f32 v[38:39], v[38:39], v[102:103]
	v_pk_fma_f32 v[44:45], v[46:47], v[90:91], v[44:45]
	v_pk_fma_f32 v[100:101], v[140:141], v[64:65], v[80:81]
	v_pk_fma_f32 v[38:39], v[38:39], v[94:95], v[44:45]
	v_pk_mul_f32 v[40:41], v[40:41], v[138:139]
	v_exp_f32_e32 v46, v38
	v_exp_f32_e32 v47, v39
	v_pk_fma_f32 v[100:101], v[48:49], v[68:69], v[100:101]
	v_add_f32_e32 v46, 1.0, v46
	v_rcp_f32_e32 v46, v46
	v_add_f32_e32 v47, 1.0, v47
	v_rcp_f32_e32 v47, v47
	v_pk_fma_f32 v[44:45], v[48:49], v[64:65], v[80:81]
	v_pk_fma_f32 v[100:101], v[40:41], v[76:77], v[100:101]
	v_pk_mul_f32 v[32:33], v[32:33], v[136:137]
	v_pk_fma_f32 v[40:41], v[40:41], v[68:69], v[44:45]
	v_pk_fma_f32 v[58:59], v[58:59], v[66:67], v[82:83]
	v_pk_fma_f32 v[32:33], v[32:33], v[76:77], v[40:41]
	v_pk_fma_f32 v[58:59], v[50:51], v[70:71], v[58:59]
	v_pk_mul_f32 v[32:33], v[32:33], v[36:37]
	v_pk_mul_f32 v[36:37], v[38:39], v[46:47]
	v_pk_fma_f32 v[38:39], v[50:51], v[66:67], v[82:83]
	v_pk_mul_f32 v[34:35], v[34:35], v[102:103]
	v_pk_fma_f32 v[38:39], v[42:43], v[70:71], v[38:39]
	v_pk_mul_f32 v[62:63], v[62:63], v[106:107]
	v_pk_fma_f32 v[58:59], v[42:43], v[78:79], v[58:59]
	v_pk_fma_f32 v[34:35], v[34:35], v[78:79], v[38:39]
	v_pk_mul_f32 v[60:61], v[100:101], v[60:61]
	v_pk_mul_f32 v[58:59], v[58:59], v[62:63]
	v_pk_mul_f32 v[34:35], v[34:35], v[36:37]
	v_cvt_pk_bf16_f32 v60, v60, v61
	v_cvt_pk_bf16_f32 v61, v58, v59
	v_lshl_add_u64 v[58:59], v[132:133], 0, v[56:57]
	v_cvt_pk_bf16_f32 v32, v32, v33
	v_cvt_pk_bf16_f32 v33, v34, v35
	v_lshl_add_u64 v[34:35], v[172:173], 0, v[56:57]
	global_store_dwordx2 v[58:59], v[60:61], off
	global_store_dwordx2 v[34:35], v[32:33], off
	v_mov_b32_e32 v105, 0
	v_mov_b32_e32 v106, 0
	v_mov_b32_e32 v107, 0
	v_mov_b32_e32 v32, 0
	v_mov_b32_e32 v33, 0
	v_mov_b32_e32 v34, 0
	v_mov_b32_e32 v35, 0
	v_mov_b32_e32 v36, 0
	v_mov_b32_e32 v37, 0
	v_mov_b32_e32 v38, 0
	v_mov_b32_e32 v39, 0
	v_mov_b32_e32 v40, 0
	v_mov_b32_e32 v41, 0
	v_mov_b32_e32 v42, 0
	v_mov_b32_e32 v43, 0
	s_and_saveexec_b64 s[0:1], s[14:15]
	s_cbranch_execz .LBB0_725
	ds_read_b128 v[40:43], v230 offset:2112
	ds_read_b128 v[32:35], v230 offset:2624
	ds_read_b128 v[36:39], v230 offset:3136
	ds_read_b128 v[104:107], v230 offset:3648
.LBB0_725:
	s_or_b64 exec, exec, s[0:1]
	v_mul_f32_dpp v54, v4, v201 row_shr:1 row_mask:0xf bank_mask:0xf bound_ctrl:1
	v_mul_f32_dpp v58, v8, v200 row_shr:1 row_mask:0xf bank_mask:0xf bound_ctrl:1
	v_mul_f32_dpp v60, v0, v201 row_shr:1 row_mask:0xf bank_mask:0xf bound_ctrl:1
	v_mul_f32_dpp v52, v12, v200 row_shr:1 row_mask:0xf bank_mask:0xf bound_ctrl:1
	v_mov_b32_e32 v48, v72
	v_mov_b32_e32 v49, v72
	v_mul_f32_dpp v53, v13, v200 row_shr:1 row_mask:0xf bank_mask:0xf bound_ctrl:1
	s_waitcnt lgkmcnt(0)
	v_pk_add_f32 v[40:41], v[40:41], v[52:53]
	v_pk_mul_f32 v[28:29], v[28:29], v[48:49]
	v_mul_f32_dpp v55, v5, v201 row_shr:1 row_mask:0xf bank_mask:0xf bound_ctrl:1
	v_pk_add_f32 v[36:37], v[36:37], v[54:55]
	v_pk_fma_f32 v[40:41], v[84:85], v[40:41], v[96:97]
	v_pk_fma_f32 v[40:41], v[88:89], v[36:37], v[40:41]
	v_pk_fma_f32 v[40:41], v[28:29], v[92:93], v[40:41]
	v_mul_f32_dpp v59, v9, v200 row_shr:1 row_mask:0xf bank_mask:0xf bound_ctrl:1
	v_exp_f32_e32 v52, v40
	v_exp_f32_e32 v53, v41
	v_mul_f32_dpp v61, v1, v201 row_shr:1 row_mask:0xf bank_mask:0xf bound_ctrl:1
	v_mul_f32_dpp v100, v6, v201 row_shr:1 row_mask:0xf bank_mask:0xf bound_ctrl:1
	v_mul_f32_dpp v102, v10, v200 row_shr:1 row_mask:0xf bank_mask:0xf bound_ctrl:1
	v_mul_f32_dpp v108, v2, v201 row_shr:1 row_mask:0xf bank_mask:0xf bound_ctrl:1
	v_mul_f32_dpp v62, v14, v200 row_shr:1 row_mask:0xf bank_mask:0xf bound_ctrl:1
	v_add_f32_e32 v52, 1.0, v52
	v_add_f32_e32 v53, 1.0, v53
	v_mul_f32_dpp v63, v15, v200 row_shr:1 row_mask:0xf bank_mask:0xf bound_ctrl:1
	v_rcp_f32_e32 v52, v52
	v_rcp_f32_e32 v53, v53
	v_mul_f32_dpp v101, v7, v201 row_shr:1 row_mask:0xf bank_mask:0xf bound_ctrl:1
	v_pk_add_f32 v[42:43], v[42:43], v[62:63]
	v_mov_b32_e32 v111, v72
	v_mul_f32_dpp v103, v11, v200 row_shr:1 row_mask:0xf bank_mask:0xf bound_ctrl:1
	v_pk_add_f32 v[38:39], v[38:39], v[100:101]
	v_pk_fma_f32 v[42:43], v[86:87], v[42:43], v[98:99]
	v_mul_f32_dpp v109, v3, v201 row_shr:1 row_mask:0xf bank_mask:0xf bound_ctrl:1
	v_mov_b32_e32 v110, v72
	v_pk_mul_f32 v[30:31], v[30:31], v[110:111]
	v_pk_fma_f32 v[42:43], v[90:91], v[38:39], v[42:43]
	v_pk_mul_f32 v[40:41], v[40:41], v[52:53]
	v_pk_fma_f32 v[42:43], v[30:31], v[94:95], v[42:43]
	v_pk_add_f32 v[32:33], v[32:33], v[58:59]
	v_exp_f32_e32 v52, v42
	v_exp_f32_e32 v53, v43
	v_pk_mul_f32 v[24:25], v[24:25], v[48:49]
	v_pk_add_f32 v[48:49], v[104:105], v[60:61]
	v_pk_fma_f32 v[32:33], v[64:65], v[32:33], v[80:81]
	v_add_f32_e32 v52, 1.0, v52
	v_add_f32_e32 v53, 1.0, v53
	v_pk_fma_f32 v[32:33], v[68:69], v[48:49], v[32:33]
	v_rcp_f32_e32 v52, v52
	v_rcp_f32_e32 v53, v53
	v_pk_fma_f32 v[32:33], v[24:25], v[76:77], v[32:33]
	v_pk_add_f32 v[34:35], v[34:35], v[102:103]
	v_pk_mul_f32 v[32:33], v[32:33], v[40:41]
	v_pk_add_f32 v[40:41], v[106:107], v[108:109]
	v_pk_fma_f32 v[34:35], v[66:67], v[34:35], v[82:83]
	v_pk_mul_f32 v[26:27], v[26:27], v[110:111]
	v_pk_fma_f32 v[34:35], v[70:71], v[40:41], v[34:35]
; __device__ __forceinline__ unsigned pk2(float lo, float hi) { f32x2_t v = {lo, hi}; bf16x2_t b = __builtin_convertvector(v, bf16x2_t); return __builtin_bit_cast(unsigned, b); }
; __device__ __forceinline__ float fast_rsq(float x) { return __builtin_amdgcn_rsqf(x); }
; __device__ __forceinline__ float sigmoidf_(float v) { return fast_rcp(1.0f + fast_exp2(-v * LOG2E)); }
;     __device__ __forceinline__ void run(const f32x4 (&acc)[2][2][4][2], const Unit& u, const Unit& nxt, bool has_next, int ui, int wr, int wc, int fr_in, int fq_in) const {
;     ...
;                 for (int m = 0; m < 4; ++m) {
;                     const f32x4 gc = acc[ai][0][m][n] * rs[ai][m], vc = acc[ai][1][m][n] * rs[ai][m];
;                     const f32x4 cgt = bg + wg0 * pg2 + wg1 * pg1 + wg2 * gc, cvl = bv + wv0 * pv2 + wv1 * pv1 + wv2 * vc;
;                     float a[4];
; #pragma unroll
;                     for (int i = 0; i < 4; ++i) a[i] = cgt[i] * sigmoidf_(cgt[i]) * cvl[i];
;                     u32x2 w; w.x = pk2(a[0], a[1]); w.y = pk2(a[2], a[3]);
;                     *(u32x2*)(A + (size_t)(u.pm * BM + ai * 128 + wr * 64 + 4 * fr + m) * DFF + ch) = w;
;                     pg2 = pg1; pg1 = gc; pv2 = pv1; pv1 = vc;
;                 }
;                 asm volatile("" ::: "memory");
;             }
;         }
;         if (has_next) {
;             prm[(slot ^ 1) * 1024 + tid] = nx0; prm[(slot ^ 1) * 1024 + tid + 512] = nx1;
;             if (tid < 256) rsd[(slot ^ 1) * 256 + tid] = fast_rsq(nrs * (1.0f / DM) + EPS);
;         }
	v_pk_mul_f32 v[42:43], v[42:43], v[52:53]
	v_pk_fma_f32 v[34:35], v[26:27], v[78:79], v[34:35]
	v_cvt_pk_bf16_f32 v32, v32, v33
	v_pk_mul_f32 v[34:35], v[34:35], v[42:43]
	v_mov_b32_e32 v50, v73
	v_cvt_pk_bf16_f32 v33, v34, v35
	v_lshl_add_u64 v[34:35], v[122:123], 0, v[56:57]
	v_mov_b32_e32 v51, v73
	global_store_dwordx2 v[34:35], v[32:33], off
	v_pk_fma_f32 v[32:33], v[84:85], v[36:37], v[96:97]
	v_pk_mul_f32 v[20:21], v[20:21], v[50:51]
	v_pk_fma_f32 v[32:33], v[28:29], v[88:89], v[32:33]
	v_mov_b32_e32 v72, v73
	v_pk_fma_f32 v[32:33], v[20:21], v[92:93], v[32:33]
	v_pk_mul_f32 v[22:23], v[22:23], v[72:73]
	v_exp_f32_e32 v34, v32
	v_exp_f32_e32 v35, v33
	v_mov_b32_e32 v46, v74
	v_mov_b32_e32 v47, v74
	v_add_f32_e32 v34, 1.0, v34
	v_add_f32_e32 v35, 1.0, v35
	v_rcp_f32_e32 v34, v34
	v_rcp_f32_e32 v35, v35
	v_pk_fma_f32 v[28:29], v[28:29], v[84:85], v[96:97]
	v_mov_b32_e32 v44, v75
	v_mov_b32_e32 v45, v75
	v_pk_mul_f32 v[32:33], v[32:33], v[34:35]
	v_pk_fma_f32 v[34:35], v[86:87], v[38:39], v[98:99]
	v_pk_mul_f32 v[12:13], v[12:13], v[46:47]
	v_pk_fma_f32 v[34:35], v[30:31], v[90:91], v[34:35]
	v_pk_fma_f32 v[28:29], v[20:21], v[88:89], v[28:29]
	v_pk_fma_f32 v[34:35], v[22:23], v[94:95], v[34:35]
	v_pk_fma_f32 v[20:21], v[20:21], v[84:85], v[96:97]
	v_exp_f32_e32 v38, v34
	v_exp_f32_e32 v39, v35
	v_pk_fma_f32 v[28:29], v[12:13], v[92:93], v[28:29]
	v_pk_mul_f32 v[4:5], v[4:5], v[44:45]
	v_pk_fma_f32 v[12:13], v[12:13], v[88:89], v[20:21]
	v_pk_fma_f32 v[36:37], v[64:65], v[48:49], v[80:81]
	v_add_f32_e32 v38, 1.0, v38
	v_add_f32_e32 v39, 1.0, v39
	v_pk_fma_f32 v[4:5], v[4:5], v[92:93], v[12:13]
	v_pk_mul_f32 v[16:17], v[16:17], v[50:51]
	v_rcp_f32_e32 v38, v38
	v_rcp_f32_e32 v39, v39
	v_pk_fma_f32 v[36:37], v[24:25], v[68:69], v[36:37]
	v_pk_fma_f32 v[36:37], v[16:17], v[76:77], v[36:37]
	v_exp_f32_e32 v12, v4
	v_exp_f32_e32 v13, v5
	v_pk_mul_f32 v[32:33], v[36:37], v[32:33]
	v_pk_fma_f32 v[36:37], v[66:67], v[40:41], v[82:83]
	v_pk_mul_f32 v[18:19], v[18:19], v[72:73]
	v_pk_fma_f32 v[36:37], v[26:27], v[70:71], v[36:37]
	v_pk_mul_f32 v[34:35], v[34:35], v[38:39]
	v_pk_fma_f32 v[36:37], v[18:19], v[78:79], v[36:37]
	v_add_f32_e32 v12, 1.0, v12
	v_pk_mul_f32 v[34:35], v[36:37], v[34:35]
	v_add_f32_e32 v13, 1.0, v13
	v_cvt_pk_bf16_f32 v32, v32, v33
	v_cvt_pk_bf16_f32 v33, v34, v35
	v_lshl_add_u64 v[34:35], v[124:125], 0, v[56:57]
	v_rcp_f32_e32 v12, v12
	v_rcp_f32_e32 v13, v13
	global_store_dwordx2 v[34:35], v[32:33], off
	v_exp_f32_e32 v34, v28
	v_mov_b32_e32 v32, v74
	v_exp_f32_e32 v35, v29
	v_mov_b32_e32 v33, v74
	v_pk_mul_f32 v[14:15], v[14:15], v[32:33]
	v_mov_b32_e32 v74, v75
	v_pk_mul_f32 v[4:5], v[4:5], v[12:13]
	v_pk_fma_f32 v[12:13], v[22:23], v[86:87], v[98:99]
	v_pk_mul_f32 v[6:7], v[6:7], v[74:75]
	v_pk_fma_f32 v[12:13], v[14:15], v[90:91], v[12:13]
	v_pk_fma_f32 v[30:31], v[30:31], v[86:87], v[98:99]
	v_pk_fma_f32 v[6:7], v[6:7], v[94:95], v[12:13]
	v_pk_fma_f32 v[30:31], v[22:23], v[90:91], v[30:31]
	v_pk_fma_f32 v[30:31], v[14:15], v[94:95], v[30:31]
	v_exp_f32_e32 v14, v6
	v_exp_f32_e32 v15, v7
	v_pk_mul_f32 v[10:11], v[10:11], v[32:33]
	v_exp_f32_e32 v32, v30
	v_exp_f32_e32 v33, v31
	v_add_f32_e32 v14, 1.0, v14
	v_add_f32_e32 v15, 1.0, v15
	v_add_f32_e32 v34, 1.0, v34
	v_add_f32_e32 v35, 1.0, v35
	v_pk_fma_f32 v[24:25], v[24:25], v[64:65], v[80:81]
	v_rcp_f32_e32 v14, v14
	v_rcp_f32_e32 v15, v15
	v_rcp_f32_e32 v34, v34
	v_rcp_f32_e32 v35, v35
	v_pk_mul_f32 v[8:9], v[8:9], v[46:47]
	v_add_f32_e32 v32, 1.0, v32
	v_add_f32_e32 v33, 1.0, v33
	v_pk_fma_f32 v[24:25], v[16:17], v[68:69], v[24:25]
	v_pk_fma_f32 v[12:13], v[16:17], v[64:65], v[80:81]
	v_rcp_f32_e32 v32, v32
	v_rcp_f32_e32 v33, v33
	v_pk_fma_f32 v[24:25], v[8:9], v[76:77], v[24:25]
	v_pk_mul_f32 v[0:1], v[0:1], v[44:45]
	v_pk_fma_f32 v[8:9], v[8:9], v[68:69], v[12:13]
	v_pk_fma_f32 v[26:27], v[26:27], v[66:67], v[82:83]
	v_pk_fma_f32 v[0:1], v[0:1], v[76:77], v[8:9]
	v_pk_mul_f32 v[28:29], v[28:29], v[34:35]
	v_pk_mul_f32 v[0:1], v[0:1], v[4:5]
	v_pk_mul_f32 v[4:5], v[6:7], v[14:15]
	v_pk_fma_f32 v[6:7], v[18:19], v[66:67], v[82:83]
	v_pk_fma_f32 v[26:27], v[18:19], v[70:71], v[26:27]
	v_pk_mul_f32 v[2:3], v[2:3], v[74:75]
	v_pk_fma_f32 v[6:7], v[10:11], v[70:71], v[6:7]
	v_pk_mul_f32 v[24:25], v[24:25], v[28:29]
	v_pk_mul_f32 v[28:29], v[30:31], v[32:33]
	v_pk_fma_f32 v[26:27], v[10:11], v[78:79], v[26:27]
	v_pk_fma_f32 v[2:3], v[2:3], v[78:79], v[6:7]
	v_pk_mul_f32 v[26:27], v[26:27], v[28:29]
	v_pk_mul_f32 v[2:3], v[2:3], v[4:5]
	v_cvt_pk_bf16_f32 v24, v24, v25
	v_cvt_pk_bf16_f32 v25, v26, v27
	v_lshl_add_u64 v[26:27], v[130:131], 0, v[56:57]
	v_cvt_pk_bf16_f32 v0, v0, v1
	v_cvt_pk_bf16_f32 v1, v2, v3
	v_lshl_add_u64 v[2:3], v[134:135], 0, v[56:57]
	global_store_dwordx2 v[26:27], v[24:25], off
	global_store_dwordx2 v[2:3], v[0:1], off
	s_and_b64 vcc, exec, s[10:11]
	s_mov_b64 s[0:1], -1
	s_cbranch_vccnz .LBB0_681
	s_xor_b32 s4, s35, 0x400
	v_lshlrev_b32_e32 v0, 2, v226
	v_lshl_add_u32 v0, s4, 2, v0
	v_add_u32_e32 v0, 0x22040, v0
	v_cmp_gt_i32_e32 vcc, s65, v226
	s_waitcnt vmcnt(0)
	v_mul_f32_e32 v228, 0xbfb8aa3b, v228
	v_mul_f32_e32 v227, 0xbf317218, v227
	ds_write2st64_b32 v0, v228, v227 offset1:8
	s_and_saveexec_b64 s[0:1], vcc
	s_cbranch_execz .LBB0_728
	v_rsq_f32_e32 v0, v229
	v_lshl_add_u32 v1, v226, 2, s4
	v_add_u32_e32 v1, 0x24040, v1
	ds_write_b32 v1, v0

; template <class Epi, class Sched, bool ALIGN_EPI = false, bool SP2 = false>
; __device__ __forceinline__ void gemm_phase(PG8_LAS unsigned char* lds, const Gemm g, const Sched& S, const Epi& E, const int tid_arg) {
;     ...
; #pragma unroll
;         for (int a = 0; a < 2; ++a)
; #pragma unroll
;             for (int b = 0; b < 2; ++b)
; #pragma unroll
;                 for (int m = 0; m < 4; ++m)
; #pragma unroll
;                     for (int n = 0; n < 2; ++n) acc[a][b][m][n] = (f32x4){0.f, 0.f, 0.f, 0.f};
.LBB0_870:
	s_add_u32 s55, s22, 0x100
	v_mov_b32_e32 v0, 0
	s_addc_u32 s56, s23, 0
	s_mov_b32 s57, -2
	v_mov_b32_e32 v1, v0
	v_mov_b64_e32 v[2:3], 0
	v_mov_b64_e32 v[4:5], 0
	v_mov_b64_e32 v[6:7], 0
	v_mov_b64_e32 v[16:17], 0
	v_mov_b64_e32 v[18:19], 0
	v_mov_b64_e32 v[20:21], 0
	v_mov_b64_e32 v[22:23], 0
	v_mov_b64_e32 v[32:33], 0
	v_mov_b64_e32 v[34:35], 0
	v_mov_b64_e32 v[36:37], 0
	v_mov_b64_e32 v[38:39], 0
	v_mov_b64_e32 v[48:49], 0
	v_mov_b64_e32 v[50:51], 0
	v_mov_b64_e32 v[52:53], 0
	v_mov_b64_e32 v[54:55], 0
	v_mov_b64_e32 v[8:9], 0
	v_mov_b64_e32 v[10:11], 0
	v_mov_b64_e32 v[12:13], 0
	v_mov_b64_e32 v[14:15], 0
	v_mov_b64_e32 v[24:25], 0
	v_mov_b64_e32 v[26:27], 0
	v_mov_b64_e32 v[28:29], 0
	v_mov_b64_e32 v[30:31], 0
	v_mov_b64_e32 v[40:41], 0
	v_mov_b64_e32 v[42:43], 0
	v_mov_b64_e32 v[44:45], 0
	v_mov_b64_e32 v[46:47], 0
	v_mov_b64_e32 v[56:57], 0
	v_mov_b64_e32 v[58:59], 0
	v_mov_b64_e32 v[60:61], 0
	v_mov_b64_e32 v[62:63], 0
	v_mov_b64_e32 v[64:65], 0
	v_mov_b64_e32 v[66:67], 0
	v_mov_b64_e32 v[68:69], 0
	v_mov_b64_e32 v[70:71], 0
	v_mov_b64_e32 v[80:81], 0
	v_mov_b64_e32 v[82:83], 0
	v_mov_b64_e32 v[84:85], 0
	v_mov_b64_e32 v[86:87], 0
	v_mov_b64_e32 v[96:97], 0
	v_mov_b64_e32 v[98:99], 0
	v_mov_b64_e32 v[100:101], 0
	v_mov_b64_e32 v[102:103], 0
	v_mov_b64_e32 v[112:113], 0
	v_mov_b64_e32 v[114:115], 0
	v_mov_b64_e32 v[116:117], 0
	v_mov_b64_e32 v[118:119], 0
	v_mov_b64_e32 v[72:73], 0
	v_mov_b64_e32 v[74:75], 0
	v_mov_b64_e32 v[76:77], 0
	v_mov_b64_e32 v[78:79], 0
	v_mov_b64_e32 v[88:89], 0
	v_mov_b64_e32 v[90:91], 0
	v_mov_b64_e32 v[92:93], 0
	v_mov_b64_e32 v[94:95], 0
	v_mov_b64_e32 v[104:105], 0
	v_mov_b64_e32 v[106:107], 0
	v_mov_b64_e32 v[108:109], 0
	v_mov_b64_e32 v[110:111], 0
	v_mov_b64_e32 v[120:121], 0
	v_mov_b64_e32 v[122:123], 0
	v_mov_b64_e32 v[124:125], 0
	v_mov_b64_e32 v[126:127], 0

; template <class Epi, class Sched, bool ALIGN_EPI = false, bool SP2 = false>
; __device__ __forceinline__ void gemm_phase(PG8_LAS unsigned char* lds, const Gemm g, const Sched& S, const Epi& E, const int tid_arg) {
;     ...
;         const char* nA = has_next ? (const char*)g.A + (size_t)nxt.pm * tstep : cA; const char* nB = has_next ? (const char*)g.Bt + (size_t)nxt.pn * tstep : cB;
;         for (int t = 0; t < nt; t += 2) {
;             const bool last = (t == nt - 2);
;             const char* a1 = cA + (size_t)(t + 1) * kstep;
;             const char* a2 = last ? nA : cA + (size_t)(t + 2) * kstep; const char* b2 = last ? nB : cB + (size_t)(t + 2) * kstep;
;             const char* a3 = a2 + kstep; const char* b3 = b2 + kstep;
;     ...
; #pragma unroll
;         for (int a = 0; a < 2; ++a)
; #pragma unroll
;             for (int b = 0; b < 2; ++b)
; #pragma unroll
;                 for (int m = 0; m < 4; ++m)
; #pragma unroll
;                     for (int n = 0; n < 2; ++n) acc[a][b][m][n] = (f32x4){0.f, 0.f, 0.f, 0.f};
.LBB0_964:
	s_ashr_i32 s35, s34, 31
	s_lshl_b64 s[0:1], s[34:35], 19
	s_add_u32 s36, s3, s0
	s_addc_u32 s37, s33, s1
	s_and_b64 s[0:1], s[10:11], exec
	s_cselect_b32 s35, s37, s43
	s_cselect_b32 s68, s36, s42
	s_ashr_i32 s31, s30, 31
	s_lshl_b64 s[0:1], s[30:31], 19
	s_add_u32 s38, s44, s0
	s_addc_u32 s39, s45, s1
	s_and_b64 s[0:1], s[10:11], exec
	s_cselect_b32 s31, s39, s41
	s_cselect_b32 s69, s38, s40
	s_add_u32 s70, s40, 0x100
	s_addc_u32 s71, s41, 0
	s_add_u32 s40, s42, 0x40080
	v_mov_b32_e32 v0, 0
	s_addc_u32 s41, s43, 0
	s_mov_b32 s72, -2
	v_mov_b32_e32 v1, v0
	v_mov_b64_e32 v[2:3], 0
	v_mov_b64_e32 v[4:5], 0
	v_mov_b64_e32 v[6:7], 0
	v_mov_b64_e32 v[16:17], 0
	v_mov_b64_e32 v[18:19], 0
	v_mov_b64_e32 v[20:21], 0
	v_mov_b64_e32 v[22:23], 0
	v_mov_b64_e32 v[32:33], 0
	v_mov_b64_e32 v[34:35], 0
	v_mov_b64_e32 v[36:37], 0
	v_mov_b64_e32 v[38:39], 0
	v_mov_b64_e32 v[48:49], 0
	v_mov_b64_e32 v[50:51], 0
	v_mov_b64_e32 v[52:53], 0
	v_mov_b64_e32 v[54:55], 0
	v_mov_b64_e32 v[8:9], 0
	v_mov_b64_e32 v[10:11], 0
	v_mov_b64_e32 v[12:13], 0
	v_mov_b64_e32 v[14:15], 0
	v_mov_b64_e32 v[24:25], 0
	v_mov_b64_e32 v[26:27], 0
	v_mov_b64_e32 v[28:29], 0
	v_mov_b64_e32 v[30:31], 0
	v_mov_b64_e32 v[40:41], 0
	v_mov_b64_e32 v[42:43], 0
	v_mov_b64_e32 v[44:45], 0
	v_mov_b64_e32 v[46:47], 0
	v_mov_b64_e32 v[56:57], 0
	v_mov_b64_e32 v[58:59], 0
	v_mov_b64_e32 v[60:61], 0
	v_mov_b64_e32 v[62:63], 0
	v_mov_b64_e32 v[64:65], 0
	v_mov_b64_e32 v[66:67], 0
	v_mov_b64_e32 v[68:69], 0
	v_mov_b64_e32 v[70:71], 0
	v_mov_b64_e32 v[80:81], 0
	v_mov_b64_e32 v[82:83], 0
	v_mov_b64_e32 v[84:85], 0
	v_mov_b64_e32 v[86:87], 0
	v_mov_b64_e32 v[96:97], 0
	v_mov_b64_e32 v[98:99], 0
	v_mov_b64_e32 v[100:101], 0
	v_mov_b64_e32 v[102:103], 0
	v_mov_b64_e32 v[112:113], 0
	v_mov_b64_e32 v[114:115], 0
	v_mov_b64_e32 v[116:117], 0
	v_mov_b64_e32 v[118:119], 0
	v_mov_b64_e32 v[72:73], 0
	v_mov_b64_e32 v[74:75], 0
	v_mov_b64_e32 v[76:77], 0
	v_mov_b64_e32 v[78:79], 0
	v_mov_b64_e32 v[88:89], 0
	v_mov_b64_e32 v[90:91], 0
	v_mov_b64_e32 v[92:93], 0
	v_mov_b64_e32 v[94:95], 0
	v_mov_b64_e32 v[104:105], 0
	v_mov_b64_e32 v[106:107], 0
	v_mov_b64_e32 v[108:109], 0
	v_mov_b64_e32 v[110:111], 0
	v_mov_b64_e32 v[120:121], 0
	v_mov_b64_e32 v[122:123], 0
	v_mov_b64_e32 v[124:125], 0
	v_mov_b64_e32 v[126:127], 0

; template <class Epi, class Sched, bool ALIGN_EPI = false, bool SP2 = false>
; __device__ __forceinline__ void gemm_phase(PG8_LAS unsigned char* lds, const Gemm g, const Sched& S, const Epi& E, const int tid_arg) {
;     ...
;     f32x4 acc[2][2][4][2];
; #pragma unroll
;     for (int a = 0; a < 2; ++a)
; #pragma unroll
;         for (int b = 0; b < 2; ++b)
; #pragma unroll
;             for (int m = 0; m < 4; ++m)
; #pragma unroll
;                 for (int n = 0; n < 2; ++n) acc[a][b][m][n] = (f32x4){0.f, 0.f, 0.f, 0.f};
;     ...
; #pragma unroll
;         for (int a = 0; a < 2; ++a)
; #pragma unroll
;             for (int b = 0; b < 2; ++b)
; #pragma unroll
;                 for (int m = 0; m < 4; ++m)
; #pragma unroll
;                     for (int n = 0; n < 2; ++n) acc[a][b][m][n] = (f32x4){0.f, 0.f, 0.f, 0.f};
.LBB0_1044:
	v_mov_b32_e32 v127, 0
	s_and_b64 vcc, exec, s[10:11]
	v_mov_b32_e32 v126, v127
	v_mov_b64_e32 v[124:125], 0
	v_mov_b64_e32 v[122:123], 0
	v_mov_b64_e32 v[120:121], 0
	v_mov_b64_e32 v[110:111], 0
	v_mov_b64_e32 v[108:109], 0
	v_mov_b64_e32 v[106:107], 0
	v_mov_b64_e32 v[104:105], 0
	v_mov_b64_e32 v[94:95], 0
	v_mov_b64_e32 v[92:93], 0
	v_mov_b64_e32 v[90:91], 0
	v_mov_b64_e32 v[88:89], 0
	v_mov_b64_e32 v[78:79], 0
	v_mov_b64_e32 v[76:77], 0
	v_mov_b64_e32 v[74:75], 0
	v_mov_b64_e32 v[72:73], 0
	v_mov_b64_e32 v[118:119], 0
	v_mov_b64_e32 v[116:117], 0
	v_mov_b64_e32 v[114:115], 0
	v_mov_b64_e32 v[112:113], 0
	v_mov_b64_e32 v[102:103], 0
	v_mov_b64_e32 v[100:101], 0
	v_mov_b64_e32 v[98:99], 0
	v_mov_b64_e32 v[96:97], 0
	v_mov_b64_e32 v[86:87], 0
	v_mov_b64_e32 v[84:85], 0
	v_mov_b64_e32 v[82:83], 0
	v_mov_b64_e32 v[80:81], 0
	v_mov_b64_e32 v[70:71], 0
	v_mov_b64_e32 v[68:69], 0
	v_mov_b64_e32 v[66:67], 0
	v_mov_b64_e32 v[64:65], 0
	v_mov_b64_e32 v[62:63], 0
	v_mov_b64_e32 v[60:61], 0
	v_mov_b64_e32 v[58:59], 0
	v_mov_b64_e32 v[56:57], 0
	v_mov_b64_e32 v[46:47], 0
	v_mov_b64_e32 v[44:45], 0
	v_mov_b64_e32 v[42:43], 0
	v_mov_b64_e32 v[40:41], 0
	v_mov_b64_e32 v[30:31], 0
	v_mov_b64_e32 v[28:29], 0
	v_mov_b64_e32 v[26:27], 0
	v_mov_b64_e32 v[24:25], 0
	v_mov_b64_e32 v[14:15], 0
	v_mov_b64_e32 v[12:13], 0
	v_mov_b64_e32 v[10:11], 0
	v_mov_b64_e32 v[8:9], 0
	v_mov_b64_e32 v[54:55], 0
	v_mov_b64_e32 v[52:53], 0
	v_mov_b64_e32 v[50:51], 0
	v_mov_b64_e32 v[48:49], 0
	v_mov_b64_e32 v[38:39], 0
	v_mov_b64_e32 v[36:37], 0
	v_mov_b64_e32 v[34:35], 0
	v_mov_b64_e32 v[32:33], 0
	v_mov_b64_e32 v[22:23], 0
	v_mov_b64_e32 v[20:21], 0
	v_mov_b64_e32 v[18:19], 0
	v_mov_b64_e32 v[16:17], 0
	v_mov_b64_e32 v[6:7], 0
	v_mov_b64_e32 v[4:5], 0
	v_mov_b64_e32 v[2:3], 0
	v_mov_b64_e32 v[0:1], 0
	s_cbranch_vccnz .LBB0_1047
	s_add_u32 s60, s4, 0x100
	s_addc_u32 s61, s5, 0
	s_add_u32 s4, s30, 0x80
	v_mov_b32_e32 v0, 0
	s_addc_u32 s5, s31, 0
	s_mov_b32 s0, 0
	v_mov_b32_e32 v1, v0
	v_mov_b64_e32 v[2:3], 0
	v_mov_b64_e32 v[4:5], 0
	v_mov_b64_e32 v[6:7], 0
	v_mov_b64_e32 v[16:17], 0
	v_mov_b64_e32 v[18:19], 0
	v_mov_b64_e32 v[20:21], 0
	v_mov_b64_e32 v[22:23], 0
	v_mov_b64_e32 v[32:33], 0
	v_mov_b64_e32 v[34:35], 0
	v_mov_b64_e32 v[36:37], 0
	v_mov_b64_e32 v[38:39], 0
	v_mov_b64_e32 v[48:49], 0
	v_mov_b64_e32 v[50:51], 0
	v_mov_b64_e32 v[52:53], 0
	v_mov_b64_e32 v[54:55], 0
	v_mov_b64_e32 v[8:9], 0
	v_mov_b64_e32 v[10:11], 0
	v_mov_b64_e32 v[12:13], 0
	v_mov_b64_e32 v[14:15], 0
	v_mov_b64_e32 v[24:25], 0
	v_mov_b64_e32 v[26:27], 0
	v_mov_b64_e32 v[28:29], 0
	v_mov_b64_e32 v[30:31], 0
	v_mov_b64_e32 v[40:41], 0
	v_mov_b64_e32 v[42:43], 0
	v_mov_b64_e32 v[44:45], 0
	v_mov_b64_e32 v[46:47], 0
	v_mov_b64_e32 v[56:57], 0
	v_mov_b64_e32 v[58:59], 0
	v_mov_b64_e32 v[60:61], 0
	v_mov_b64_e32 v[62:63], 0
	v_mov_b64_e32 v[64:65], 0
	v_mov_b64_e32 v[66:67], 0
	v_mov_b64_e32 v[68:69], 0
	v_mov_b64_e32 v[70:71], 0
	v_mov_b64_e32 v[80:81], 0
	v_mov_b64_e32 v[82:83], 0
	v_mov_b64_e32 v[84:85], 0
	v_mov_b64_e32 v[86:87], 0
	v_mov_b64_e32 v[96:97], 0
	v_mov_b64_e32 v[98:99], 0
	v_mov_b64_e32 v[100:101], 0
	v_mov_b64_e32 v[102:103], 0
	v_mov_b64_e32 v[112:113], 0
	v_mov_b64_e32 v[114:115], 0
	v_mov_b64_e32 v[116:117], 0
	v_mov_b64_e32 v[118:119], 0
	v_mov_b64_e32 v[72:73], 0
	v_mov_b64_e32 v[74:75], 0
	v_mov_b64_e32 v[76:77], 0
	v_mov_b64_e32 v[78:79], 0
	v_mov_b64_e32 v[88:89], 0
	v_mov_b64_e32 v[90:91], 0
	v_mov_b64_e32 v[92:93], 0
	v_mov_b64_e32 v[94:95], 0
	v_mov_b64_e32 v[104:105], 0
	v_mov_b64_e32 v[106:107], 0
	v_mov_b64_e32 v[108:109], 0
	v_mov_b64_e32 v[110:111], 0
	v_mov_b64_e32 v[120:121], 0
	v_mov_b64_e32 v[122:123], 0
	v_mov_b64_e32 v[124:125], 0
	v_mov_b64_e32 v[126:127], 0

; template <class Epi, class Sched, bool ALIGN_EPI = false, bool SP2 = false>
; __device__ __forceinline__ void gemm_phase(PG8_LAS unsigned char* lds, const Gemm g, const Sched& S, const Epi& E, const int tid_arg) {
;     ...
;         const char* nA = has_next ? (const char*)g.A + (size_t)nxt.pm * tstep : cA; const char* nB = has_next ? (const char*)g.Bt + (size_t)nxt.pn * tstep : cB;
;         for (int t = 0; t < nt; t += 2) {
;             const bool last = (t == nt - 2);
;             const char* a1 = cA + (size_t)(t + 1) * kstep;
;             const char* a2 = last ? nA : cA + (size_t)(t + 2) * kstep; const char* b2 = last ? nB : cB + (size_t)(t + 2) * kstep;
;             const char* a3 = a2 + kstep; const char* b3 = b2 + kstep;
;     ...
; #pragma unroll
;         for (int a = 0; a < 2; ++a)
; #pragma unroll
;             for (int b = 0; b < 2; ++b)
; #pragma unroll
;                 for (int m = 0; m < 4; ++m)
; #pragma unroll
;                     for (int n = 0; n < 2; ++n) acc[a][b][m][n] = (f32x4){0.f, 0.f, 0.f, 0.f};
.LBB0_1178:
	s_ashr_i32 s25, s24, 31
	s_lshl_b64 s[0:1], s[24:25], 19
	s_add_u32 s26, s2, s0
	s_addc_u32 s27, s3, s1
	s_and_b64 s[0:1], s[6:7], exec
	s_cselect_b32 s25, s27, s11
	s_cselect_b32 s36, s26, s10
	s_ashr_i32 s23, s22, 31
	s_lshl_b64 s[0:1], s[22:23], 19
	s_add_u32 s28, s33, s0
	s_addc_u32 s29, s38, s1
	s_and_b64 s[0:1], s[6:7], exec
	s_cselect_b32 s23, s29, s5
	s_cselect_b32 s37, s28, s4
	s_add_u32 s66, s4, 0x100
	s_addc_u32 s67, s5, 0
	s_add_u32 s4, s10, 0x40080
	v_mov_b32_e32 v0, 0
	s_addc_u32 s5, s11, 0
	s_mov_b32 s68, -2
	v_mov_b32_e32 v1, v0
	v_mov_b32_e32 v2, v0
	v_mov_b32_e32 v3, v0
	v_mov_b32_e32 v4, v0
	v_mov_b32_e32 v5, v0
	v_mov_b32_e32 v6, v0
	v_mov_b32_e32 v7, v0
	s_waitcnt vmcnt(0)
	v_mov_b64_e32 v[16:17], 0
	v_mov_b64_e32 v[18:19], 0
	v_mov_b64_e32 v[20:21], 0
	v_mov_b64_e32 v[22:23], 0
	v_mov_b64_e32 v[32:33], 0
	v_mov_b64_e32 v[34:35], 0
	v_mov_b64_e32 v[36:37], 0
	v_mov_b64_e32 v[38:39], 0
	v_mov_b64_e32 v[48:49], 0
	v_mov_b64_e32 v[50:51], 0
	v_mov_b64_e32 v[52:53], 0
	v_mov_b64_e32 v[54:55], 0
	v_mov_b64_e32 v[8:9], 0
	v_mov_b64_e32 v[10:11], 0
	v_mov_b64_e32 v[12:13], 0
	v_mov_b64_e32 v[14:15], 0
	v_mov_b64_e32 v[24:25], 0
	v_mov_b64_e32 v[26:27], 0
	v_mov_b64_e32 v[28:29], 0
	v_mov_b64_e32 v[30:31], 0
	v_mov_b64_e32 v[40:41], 0
	v_mov_b64_e32 v[42:43], 0
	v_mov_b64_e32 v[44:45], 0
	v_mov_b64_e32 v[46:47], 0
	v_mov_b64_e32 v[56:57], 0
	v_mov_b64_e32 v[58:59], 0
	v_mov_b64_e32 v[60:61], 0
	v_mov_b64_e32 v[62:63], 0
	v_mov_b64_e32 v[64:65], 0
	v_mov_b64_e32 v[66:67], 0
	v_mov_b64_e32 v[68:69], 0
	v_mov_b64_e32 v[70:71], 0
	v_mov_b64_e32 v[80:81], 0
	v_mov_b64_e32 v[82:83], 0
	v_mov_b64_e32 v[84:85], 0
	v_mov_b64_e32 v[86:87], 0
	v_mov_b64_e32 v[96:97], 0
	v_mov_b64_e32 v[98:99], 0
	v_mov_b64_e32 v[100:101], 0
	v_mov_b64_e32 v[102:103], 0
	v_mov_b64_e32 v[112:113], 0
	v_mov_b64_e32 v[114:115], 0
	v_mov_b64_e32 v[116:117], 0
	v_mov_b64_e32 v[118:119], 0
	v_mov_b64_e32 v[72:73], 0
	v_mov_b64_e32 v[74:75], 0
	v_mov_b64_e32 v[76:77], 0
	v_mov_b64_e32 v[78:79], 0
	v_mov_b64_e32 v[88:89], 0
	v_mov_b64_e32 v[90:91], 0
	v_mov_b64_e32 v[92:93], 0
	v_mov_b64_e32 v[94:95], 0
	v_mov_b64_e32 v[104:105], 0
	v_mov_b64_e32 v[106:107], 0
	v_mov_b64_e32 v[108:109], 0
	v_mov_b64_e32 v[110:111], 0
	v_mov_b64_e32 v[120:121], 0
	v_mov_b64_e32 v[122:123], 0
	v_mov_b64_e32 v[124:125], 0
	v_mov_b64_e32 v[126:127], 0

; #define PG8_STAGE(bufoff, gbase, voff) do { _Pragma("unroll") for (int _i = 0; _i < 2; ++_i) \
;         __builtin_amdgcn_global_load_lds((const unsigned*)((const char*)(gbase) + (voff)[_i]), (PG8_LAS unsigned*)(lds + (bufoff) + ldsw + _i * 8192), 16, 0, 0); } while (0)
; #define PG8_WAIT_V(n) asm volatile("s_waitcnt vmcnt(" #n ")" ::: "memory")
; #define PG8_BAR __builtin_amdgcn_s_barrier()
; template <class Epi, class Sched, bool ALIGN_EPI = false, bool SP2 = false>
; __device__ __forceinline__ void gemm_phase(PG8_LAS unsigned char* lds, const Gemm g, const Sched& S, const Epi& E, const int tid_arg) {
;     ...
;     for (int i = 0; i < 2; ++i) { int R, C; stage_rc(tid * 16 + i * 8192, R, C); const int Rb = Epi::PERM ? ((R & ~31) + perm32(R & 31)) : R;
;         const int Ra = Epi::PERMA ? ((R & ~63) + 4 * (R & 15) + ((R >> 4) & 3)) : R;
;         voffA[i] = (unsigned)(Ra * K + C) * 2u; voffB[i] = (unsigned)(Rb * K + C) * 2u; }
;     const size_t kstep = (size_t)(BK * 2);
;     const size_t hstep = (size_t)HALF * K * 2;
;     const size_t tstep = 2 * hstep;
;     const unsigned ldsw = (unsigned)wid * 1024u;
;     const int aoff = lds_byte(wr * 64 + fr, fq * 8), boff = lds_byte(wc * 32 + fr, fq * 8);
;     ...
;         PG8_STAGE(PG8_SB(0, 0), cB, voffB); PG8_STAGE(PG8_SB(0, 1), cB + hstep, voffB); PG8_STAGE(PG8_SA(0, 0), cA, voffA); PG8_STAGE(PG8_SA(0, 1), cA + hstep, voffA);
;         if (wr == 1) PG8_BAR;
;         PG8_WAIT_V(2); PG8_BAR;
;         PG8_STAGE(PG8_SB(1, 0), cB + kstep, voffB); PG8_STAGE(PG8_SA(1, 0), cA + kstep, voffA); PG8_STAGE(PG8_SB(1, 1), cB + hstep + kstep, voffB);
;         PG8_WAIT_V(6); PG8_BAR;
.LBB0_1541:
	s_waitcnt lgkmcnt(0)
	s_add_u32 s16, s16, 0x9804000
	s_addc_u32 s17, s17, 0
	s_add_u32 s52, s18, 0x10800
	s_addc_u32 s53, s19, 0
	s_add_u32 s54, s10, 0x5800
	s_addc_u32 s55, s11, 0
	s_add_u32 s56, s8, 0x17984000
	s_addc_u32 s57, s9, 0
	s_add_u32 s18, s0, 0x1c504000
	s_addc_u32 s19, s1, 0
	s_and_b32 s8, s20, 3
	s_add_i32 s60, s46, 0x18000
	s_mov_b64 s[20:21], 0x80
	v_lshl_add_u64 v[6:7], v[6:7], 0, s[20:21]
	s_mov_b32 m0, s60
	s_add_i32 s61, s46, 0x1a000
	s_lshl_b32 s58, s26, 6
	s_lshl_b32 s9, s26, 13
	s_lshl_b32 s59, s8, 5
	s_lshl_b32 s10, s8, 12
	s_waitcnt vmcnt(2)
	s_barrier
	global_load_lds_dwordx4 v[6:7], off
	v_lshl_add_u64 v[4:5], v[4:5], 0, s[20:21]
	s_mov_b32 m0, s61
	s_add_i32 s62, s46, 0x8000
	s_add_i32 s63, s46, 0xa000
	global_load_lds_dwordx4 v[4:5], off
	v_lshl_add_u64 v[0:1], v[0:1], 0, s[20:21]
	s_mov_b32 m0, s62
	s_add_u32 s0, s6, 0x40080
	global_load_lds_dwordx4 v[0:1], off
	v_lshl_add_u64 v[0:1], v[2:3], 0, s[20:21]
	s_mov_b32 m0, s63
	s_addc_u32 s1, s7, 0
	s_add_i32 s64, s46, 0x1c000
	global_load_lds_dwordx4 v[0:1], off
	v_lshl_add_u64 v[0:1], s[0:1], 0, v[188:189]
	s_mov_b32 m0, s64
	s_add_i32 s65, s46, 0x1e000
	global_load_lds_dwordx4 v[0:1], off
	v_lshl_add_u64 v[0:1], s[0:1], 0, v[192:193]
	s_mov_b32 m0, s65
	v_bfe_u32 v205, v8, 4, 2
	global_load_lds_dwordx4 v[0:1], off
	v_and_b32_e32 v204, 15, v8
	v_lshlrev_b32_e32 v0, 4, v205
	v_lshlrev_b32_e32 v1, 2, v8
	v_lshl_or_b32 v0, v204, 6, v0
	v_and_b32_e32 v1, 32, v1
	v_bitop3_b32 v206, v0, s9, v1 bitop3:0xde
	v_bitop3_b32 v2, v0, s10, v1 bitop3:0xde
	v_and_b32_e32 v1, 1, v14
	v_add3_u32 v0, v16, v17, v18
	v_lshlrev_b32_e32 v1, 6, v1
	v_lshl_or_b32 v0, v0, 11, v1
	s_mov_b64 s[0:1], 0x40080
	s_cmpk_lt_u32 s24, 0x100
	v_lshl_add_u32 v0, v15, 1, v0
	v_mov_b32_e32 v1, v189
	s_cselect_b64 s[22:23], -1, 0
	s_and_b32 s67, s24, 0xffffff00
	s_lshl_b32 s8, s8, 6
	v_lshl_add_u64 v[194:195], v[0:1], 0, s[0:1]
	v_and_b32_e32 v1, 1, v9
	s_or_b32 s66, s8, s67
	s_lshl_b32 s69, s26, 11
	v_add3_u32 v0, v11, v12, v13
	v_lshlrev_b32_e32 v1, 6, v1
	s_waitcnt vmcnt(6)
	s_cmp_gt_i32 s26, 0
	v_lshl_or_b32 v0, v0, 11, v1
	s_cselect_b64 s[24:25], -1, 0
	s_cmp_gt_i32 s26, -2
	v_lshl_add_u32 v0, v10, 1, v0
	v_mov_b32_e32 v1, v189
	s_movk_i32 s33, 0x100
	s_mov_b32 s12, 0
	s_cselect_b64 s[26:27], -1, 0
	s_add_i32 s67, s67, 0x24040
	s_add_i32 s68, s69, 0x20000
	s_add_i32 s69, s69, 0x1f800
	v_lshl_add_u64 v[196:197], v[0:1], 0, s[0:1]
	s_movk_i32 s70, 0x161
	v_or_b32_e32 v207, 0x10000, v2
	v_add_u32_e32 v208, 0x10400, v2
	v_add_u32_e32 v209, 0x10800, v2
	v_add_u32_e32 v210, 0x10c00, v2
	v_or_b32_e32 v211, 0x14000, v2
	v_add_u32_e32 v212, 0x14400, v2
	v_add_u32_e32 v213, 0x14800, v2
	v_add_u32_e32 v214, 0x14c00, v2
	s_add_i32 s71, s46, 0xc000
	s_add_i32 s72, s46, 0xe000
	v_or_b32_e32 v215, 0x18000, v2
	v_add_u32_e32 v216, 0x18400, v2
	v_add_u32_e32 v217, 0x18800, v2
	v_add_u32_e32 v218, 0x18c00, v2
	v_or_b32_e32 v219, 0x1c000, v2
	v_add_u32_e32 v220, 0x1c400, v2
	v_add_u32_e32 v221, 0x1c800, v2
	v_add_u32_e32 v222, 0x1cc00, v2
	s_movk_i32 s73, 0x1600
	v_mov_b32_e32 v223, 0x358637bd
	v_mov_b32_e32 v224, 0x22040
	v_mov_b32_e32 v225, 0x24040
	s_barrier
	s_branch .LBB0_1544

;     __host__ __device__ bool next(int i, Unit& u) const {
;         const long L = (long)i * G + c; if (L >= nwg) return false;
;         int wgid = (int)L; { const int q = nwg / NXCD, r = nwg % NXCD, xcd = wgid % NXCD, off = wgid / NXCD; wgid = (xcd < r ? xcd * (q + 1) : r * (q + 1) + (xcd - r) * q) + off; }
;         const int nig = WGM * nN, gid = wgid / nig, fm = gid * WGM, gsz = (nM - fm) < WGM ? (nM - fm) : WGM;
;         u.pm = fm + ((wgid % nig) % gsz); u.pn = (wgid % nig) / gsz; return true;
; template <class Epi, class Sched, bool ALIGN_EPI = false, bool SP2 = false>
; __device__ __forceinline__ void gemm_phase(PG8_LAS unsigned char* lds, const Gemm g, const Sched& S, const Epi& E, const int tid_arg) {
;     ...
;         const bool has_next = S.next(ui + 1, nxt);
;         const char* nA = has_next ? (const char*)g.A + (size_t)nxt.pm * tstep : cA; const char* nB = has_next ? (const char*)g.Bt + (size_t)nxt.pn * tstep : cB;
;         for (int t = 0; t < nt; t += 2) {
;             const bool last = (t == nt - 2);
;             const char* a1 = cA + (size_t)(t + 1) * kstep;
;             const char* a2 = last ? nA : cA + (size_t)(t + 2) * kstep; const char* b2 = last ? nB : cB + (size_t)(t + 2) * kstep;
;     ...
; #pragma unroll
;         for (int a = 0; a < 2; ++a)
; #pragma unroll
;             for (int b = 0; b < 2; ++b)
; #pragma unroll
;                 for (int m = 0; m < 4; ++m)
; #pragma unroll
;                     for (int n = 0; n < 2; ++n) acc[a][b][m][n] = (f32x4){0.f, 0.f, 0.f, 0.f};
.LBB0_1544:
	s_add_i32 s74, s12, 1
	s_mul_i32 s0, s74, s90
	s_mul_hi_u32 s1, s74, s91
	s_add_i32 s1, s1, s0
	s_mul_i32 s0, s74, s91
	s_add_u32 s0, s0, s86
	s_addc_u32 s1, s1, s87
	v_mov_b64_e32 v[198:199], 0xb00
	v_mov_b64_e32 v[200:201], 0xaff
	v_cmp_gt_i64_e32 vcc, s[0:1], v[200:201]
	v_cmp_lt_i64_e64 s[8:9], s[0:1], v[198:199]
	s_cbranch_vccnz .LBB0_1546
	s_ashr_i32 s1, s0, 31
	s_lshr_b32 s1, s1, 29
	s_add_i32 s1, s0, s1
	s_ashr_i32 s10, s1, 3
	s_and_b32 s1, s1, -8
	s_sub_i32 s0, s0, s1
	s_cmp_lt_i32 s0, 0
	s_cselect_b32 s1, s70, 0x160
	s_mul_i32 s0, s1, s0
	s_add_i32 s0, s0, s10
	s_mul_hi_i32 s1, s0, 0x2e8ba2e9
	s_lshr_b32 s10, s1, 31
	s_ashr_i32 s1, s1, 5
	s_add_i32 s1, s1, s10
	s_lshl_b32 s10, s1, 3
	s_sub_i32 s11, 0x80, s10
	s_min_i32 s11, s11, 8
	s_abs_i32 s13, s11
	v_cvt_f32_u32_e32 v0, s13
	s_sub_i32 s29, 0, s13
	s_mulk_i32 s1, 0xb0
	s_sub_i32 s0, s0, s1
	v_rcp_iflag_f32_e32 v0, v0
	s_abs_i32 s1, s0
	s_xor_b32 s28, s0, s11
	s_ashr_i32 s28, s28, 31
	v_mul_f32_e32 v0, 0x4f7ffffe, v0
	v_cvt_u32_f32_e32 v0, v0
	s_nop 0
	v_readfirstlane_b32 s30, v0
	s_mul_i32 s29, s29, s30
	s_mul_hi_u32 s29, s30, s29
	s_add_i32 s30, s30, s29
	s_mul_hi_u32 s29, s1, s30
	s_mul_i32 s30, s29, s13
	s_sub_i32 s1, s1, s30
	s_add_i32 s31, s29, 1
	s_sub_i32 s30, s1, s13
	s_cmp_ge_u32 s1, s13
	s_cselect_b32 s29, s31, s29
	s_cselect_b32 s1, s30, s1
	s_add_i32 s30, s29, 1
	s_cmp_ge_u32 s1, s13
	s_cselect_b32 s1, s30, s29
	s_xor_b32 s1, s1, s28
	s_sub_i32 s28, s1, s28
	s_mul_i32 s1, s28, s11
	s_sub_i32 s0, s0, s1
	s_add_i32 s30, s0, s10
.LBB0_1546:
	s_ashr_i32 s31, s30, 31
	s_lshl_b64 s[0:1], s[30:31], 19
	s_add_u32 s34, s2, s0
	s_addc_u32 s35, s3, s1
	s_and_b64 s[0:1], s[8:9], exec
	s_cselect_b32 s13, s35, s5
	s_cselect_b32 s31, s34, s4
	s_ashr_i32 s29, s28, 31
	s_lshl_b64 s[0:1], s[28:29], 19
	s_add_u32 s36, s44, s0
	s_addc_u32 s37, s45, s1
	s_and_b64 s[0:1], s[8:9], exec
	s_cselect_b32 s29, s37, s7
	s_cselect_b32 s42, s36, s6
	s_add_u32 s43, s6, 0x100
	v_mov_b32_e32 v0, 0
	s_addc_u32 s75, s7, 0
	s_mov_b32 s78, -2
	v_mov_b32_e32 v1, v0
	v_mov_b32_e32 v2, v0
	v_mov_b32_e32 v3, v0
	v_mov_b32_e32 v64, v0
	v_mov_b32_e32 v65, v0
	v_mov_b32_e32 v66, v0
	v_mov_b32_e32 v67, v0
	v_mov_b32_e32 v8, v0
	v_mov_b32_e32 v9, v0
	v_mov_b32_e32 v10, v0
	v_mov_b32_e32 v11, v0
	v_mov_b32_e32 v76, v0
	v_mov_b32_e32 v77, v0
	v_mov_b32_e32 v78, v0
	v_mov_b32_e32 v79, v0
	v_mov_b32_e32 v16, v0
	v_mov_b32_e32 v17, v0
	v_mov_b32_e32 v18, v0
	v_mov_b32_e32 v19, v0
	s_waitcnt vmcnt(0)
	v_mov_b64_e32 v[84:85], 0
	v_mov_b64_e32 v[86:87], 0
	v_mov_b64_e32 v[24:25], 0
	v_mov_b64_e32 v[26:27], 0
	v_mov_b64_e32 v[92:93], 0
	v_mov_b64_e32 v[94:95], 0
	v_mov_b64_e32 v[4:5], 0
	v_mov_b64_e32 v[6:7], 0
	v_mov_b64_e32 v[68:69], 0
	v_mov_b64_e32 v[70:71], 0
	v_mov_b64_e32 v[12:13], 0
	v_mov_b64_e32 v[14:15], 0
	v_mov_b64_e32 v[80:81], 0
	v_mov_b64_e32 v[82:83], 0
	v_mov_b64_e32 v[20:21], 0
	v_mov_b64_e32 v[22:23], 0
	v_mov_b64_e32 v[88:89], 0
	v_mov_b64_e32 v[90:91], 0
	v_mov_b64_e32 v[28:29], 0
	v_mov_b64_e32 v[30:31], 0
	v_mov_b64_e32 v[96:97], 0
	v_mov_b64_e32 v[98:99], 0
	v_mov_b64_e32 v[32:33], 0
	v_mov_b64_e32 v[34:35], 0
	v_mov_b64_e32 v[104:105], 0
	v_mov_b64_e32 v[106:107], 0
	v_mov_b64_e32 v[40:41], 0
	v_mov_b64_e32 v[42:43], 0
	v_mov_b64_e32 v[112:113], 0
	v_mov_b64_e32 v[114:115], 0
	v_mov_b64_e32 v[48:49], 0
	v_mov_b64_e32 v[50:51], 0
	v_mov_b64_e32 v[120:121], 0
	v_mov_b64_e32 v[122:123], 0
	v_mov_b64_e32 v[56:57], 0
	v_mov_b64_e32 v[58:59], 0
	v_mov_b64_e32 v[128:129], 0
	v_mov_b64_e32 v[130:131], 0
	v_mov_b64_e32 v[36:37], 0
	v_mov_b64_e32 v[38:39], 0
	v_mov_b64_e32 v[108:109], 0
	v_mov_b64_e32 v[110:111], 0
	v_mov_b64_e32 v[44:45], 0
	v_mov_b64_e32 v[46:47], 0
	v_mov_b64_e32 v[116:117], 0
	v_mov_b64_e32 v[118:119], 0
	v_mov_b64_e32 v[52:53], 0
	v_mov_b64_e32 v[54:55], 0
	v_mov_b64_e32 v[124:125], 0
	v_mov_b64_e32 v[126:127], 0
	v_mov_b64_e32 v[60:61], 0
	v_mov_b64_e32 v[62:63], 0
	v_mov_b64_e32 v[132:133], 0
	v_mov_b64_e32 v[134:135], 0

; #define DPPF(v, ctrl) __builtin_bit_cast(float, __builtin_amdgcn_update_dpp(0, __builtin_bit_cast(int, (v)), (ctrl), 0xf, 0xf, false))
;     __device__ __forceinline__ void run(const f32x4 (&acc)[2][2][4][2], const Unit& u, const Unit& nxt, bool has_next, int ui, int wr, int wc, int fr_in, int fq_in) const {
;     ...
;                     const f32x4 g2 = acc[ai][0][2][n] * rs[ai][2], g3 = acc[ai][0][3][n] * rs[ai][3], v2 = acc[ai][1][2][n] * rs[ai][2], v3 = acc[ai][1][3][n] * rs[ai][3];
; #pragma unroll
;                     for (int i = 0; i < 4; ++i) {
;                         float a0 = g2[i], a1 = g3[i], a2 = v2[i], a3 = v3[i];
;                         asm volatile("" : "+v"(a0), "+v"(a1), "+v"(a2), "+v"(a3));
;                         const float t0 = DPPF(a0, 0x111), t1 = DPPF(a1, 0x111), t2 = DPPF(a2, 0x111), t3 = DPPF(a3, 0x111);
;                         pg2[i] = t0 + hg2[i]; pg1[i] = t1 + hg3[i]; pv2[i] = t2 + hv2[i]; pv1[i] = t3 + hv3[i]; }
.LBB0_1581:
	s_or_b64 exec, exec, s[0:1]
	s_lshl_b32 s0, s38, 8
	s_add_i32 s0, s0, s58
	v_lshl_add_u32 v231, v169, 2, s0
	v_mov_b32_dpp v198, v102 row_shr:1 row_mask:0xf bank_mask:0xf bound_ctrl:1
	v_mov_b32_dpp v199, v103 row_shr:1 row_mask:0xf bank_mask:0xf bound_ctrl:1
	v_mov_b32_dpp v200, v74 row_shr:1 row_mask:0xf bank_mask:0xf bound_ctrl:1
	v_mov_b32_dpp v201, v75 row_shr:1 row_mask:0xf bank_mask:0xf bound_ctrl:1
	v_mul_f32_dpp v234, v116, v198 row_shr:1 row_mask:0xf bank_mask:0xf bound_ctrl:1
	s_nop 0
	v_mul_f32_dpp v240, v104, v199 row_shr:1 row_mask:0xf bank_mask:0xf bound_ctrl:1
	v_mul_f32_dpp v236, v108, v199 row_shr:1 row_mask:0xf bank_mask:0xf bound_ctrl:1
	v_mul_f32_dpp v238, v112, v198 row_shr:1 row_mask:0xf bank_mask:0xf bound_ctrl:1
	v_mul_f32_dpp v235, v117, v198 row_shr:1 row_mask:0xf bank_mask:0xf bound_ctrl:1
	v_mul_f32_dpp v237, v109, v199 row_shr:1 row_mask:0xf bank_mask:0xf bound_ctrl:1
	v_mul_f32_dpp v239, v113, v198 row_shr:1 row_mask:0xf bank_mask:0xf bound_ctrl:1
	s_waitcnt lgkmcnt(0)
	v_pk_add_f32 v[182:183], v[182:183], v[234:235]
	v_mul_f32_dpp v241, v105, v199 row_shr:1 row_mask:0xf bank_mask:0xf bound_ctrl:1
	v_pk_add_f32 v[178:179], v[178:179], v[236:237]
	v_pk_fma_f32 v[182:183], v[152:153], v[182:183], v[164:165]
	v_mul_f32_dpp v242, v118, v198 row_shr:1 row_mask:0xf bank_mask:0xf bound_ctrl:1
	v_mul_f32_dpp v248, v106, v199 row_shr:1 row_mask:0xf bank_mask:0xf bound_ctrl:1
	v_pk_mul_f32 v[132:133], v[132:133], v[100:101] op_sel_hi:[1,0]
	v_pk_fma_f32 v[182:183], v[156:157], v[178:179], v[182:183]
	v_mul_f32_dpp v244, v110, v199 row_shr:1 row_mask:0xf bank_mask:0xf bound_ctrl:1
	v_pk_fma_f32 v[182:183], v[132:133], v[160:161], v[182:183]
	v_mul_f32_dpp v243, v119, v198 row_shr:1 row_mask:0xf bank_mask:0xf bound_ctrl:1
	v_exp_f32_e32 v169, v182
	v_exp_f32_e32 v235, v183
	v_mul_f32_dpp v246, v114, v198 row_shr:1 row_mask:0xf bank_mask:0xf bound_ctrl:1
	v_add_f32_e32 v169, 1.0, v169
	v_rcp_f32_e32 v234, v169
	v_add_f32_e32 v169, 1.0, v235
	v_rcp_f32_e32 v235, v169
	v_pk_mul_f32 v[236:237], v[128:129], v[100:101] op_sel_hi:[1,0]
	v_pk_add_f32 v[128:129], v[174:175], v[238:239]
	v_mul_f32_dpp v245, v111, v199 row_shr:1 row_mask:0xf bank_mask:0xf bound_ctrl:1
	v_pk_mul_f32 v[174:175], v[182:183], v[234:235]
	v_pk_add_f32 v[182:183], v[184:185], v[242:243]
	v_pk_add_f32 v[180:181], v[180:181], v[244:245]
	v_pk_fma_f32 v[182:183], v[154:155], v[182:183], v[166:167]
	v_pk_mul_f32 v[134:135], v[134:135], v[100:101] op_sel_hi:[1,0]
	v_pk_fma_f32 v[182:183], v[158:159], v[180:181], v[182:183]
	v_pk_add_f32 v[170:171], v[170:171], v[240:241]
	v_pk_fma_f32 v[182:183], v[134:135], v[162:163], v[182:183]
	v_pk_fma_f32 v[128:129], v[136:137], v[128:129], v[148:149]
	v_exp_f32_e32 v169, v182
	v_exp_f32_e32 v185, v183
	v_add_f32_e32 v169, 1.0, v169
	v_pk_fma_f32 v[128:129], v[140:141], v[170:171], v[128:129]
	v_rcp_f32_e32 v184, v169
	v_add_f32_e32 v169, 1.0, v185
	v_mul_f32_dpp v247, v115, v198 row_shr:1 row_mask:0xf bank_mask:0xf bound_ctrl:1
	v_pk_fma_f32 v[128:129], v[236:237], v[144:145], v[128:129]
	v_rcp_f32_e32 v185, v169
	v_mul_f32_dpp v249, v107, v199 row_shr:1 row_mask:0xf bank_mask:0xf bound_ctrl:1
	v_pk_mul_f32 v[128:129], v[128:129], v[174:175]
	v_pk_add_f32 v[174:175], v[176:177], v[246:247]
	v_pk_add_f32 v[172:173], v[172:173], v[248:249]
	v_pk_fma_f32 v[174:175], v[138:139], v[174:175], v[150:151]
	s_lshl_b32 s12, s40, 7
	v_pk_mul_f32 v[130:131], v[130:131], v[100:101] op_sel_hi:[1,0]
	v_pk_fma_f32 v[174:175], v[142:143], v[172:173], v[174:175]
	v_add_u32_e32 v232, s12, v202
	v_pk_mul_f32 v[176:177], v[182:183], v[184:185]
	v_pk_fma_f32 v[174:175], v[130:131], v[146:147], v[174:175]
	v_ashrrev_i32_e32 v233, 31, v232
	v_pk_mul_f32 v[174:175], v[174:175], v[176:177]
	v_pk_fma_f32 v[178:179], v[152:153], v[178:179], v[164:165]
	v_cvt_pk_bf16_f32 v177, v174, v175
	v_lshlrev_b64 v[174:175], 1, v[232:233]
	v_mov_b32_e32 v232, v101
	v_pk_mul_f32 v[124:125], v[124:125], v[232:233] op_sel_hi:[1,0]
	v_pk_fma_f32 v[178:179], v[132:133], v[156:157], v[178:179]
	v_mov_b64_e32 v[182:183], s[16:17]
	v_pk_fma_f32 v[178:179], v[124:125], v[160:161], v[178:179]
	v_cvt_pk_bf16_f32 v176, v128, v129
	v_exp_f32_e32 v169, v178
	v_exp_f32_e32 v233, v179
	v_mad_i64_i32 v[128:129], s[0:1], v231, s73, v[182:183]
	v_lshl_add_u64 v[184:185], v[128:129], 0, v[174:175]
	v_add_f32_e32 v169, 1.0, v169
	global_store_dwordx2 v[184:185], v[176:177], off
	v_rcp_f32_e32 v176, v169
	v_add_f32_e32 v169, 1.0, v233
	v_rcp_f32_e32 v177, v169
	v_pk_mul_f32 v[184:185], v[126:127], v[232:233] op_sel_hi:[1,0]
	v_pk_fma_f32 v[132:133], v[132:133], v[152:153], v[164:165]
	v_pk_fma_f32 v[170:171], v[136:137], v[170:171], v[148:149]
	v_pk_mul_f32 v[126:127], v[178:179], v[176:177]
	v_pk_fma_f32 v[176:177], v[154:155], v[180:181], v[166:167]
	v_pk_mul_f32 v[116:117], v[116:117], v[102:103] op_sel_hi:[1,0]
	v_pk_fma_f32 v[176:177], v[134:135], v[158:159], v[176:177]
	v_pk_fma_f32 v[132:133], v[124:125], v[156:157], v[132:133]
	v_pk_fma_f32 v[176:177], v[184:185], v[162:163], v[176:177]
	v_pk_mul_f32 v[120:121], v[120:121], v[232:233] op_sel_hi:[1,0]
	v_exp_f32_e32 v169, v176
	v_exp_f32_e32 v179, v177
	v_pk_fma_f32 v[170:171], v[236:237], v[140:141], v[170:171]
	v_add_f32_e32 v169, 1.0, v169
	v_rcp_f32_e32 v178, v169
	v_add_f32_e32 v169, 1.0, v179
	v_rcp_f32_e32 v179, v169
	v_pk_fma_f32 v[132:133], v[116:117], v[160:161], v[132:133]
	v_pk_fma_f32 v[170:171], v[120:121], v[144:145], v[170:171]
	v_pk_fma_f32 v[172:173], v[138:139], v[172:173], v[150:151]
	v_pk_mul_f32 v[122:123], v[122:123], v[232:233] op_sel_hi:[1,0]
	v_pk_mul_f32 v[126:127], v[170:171], v[126:127]
; __device__ __forceinline__ unsigned pk2(float lo, float hi) { f32x2_t v = {lo, hi}; bf16x2_t b = __builtin_convertvector(v, bf16x2_t); return __builtin_bit_cast(unsigned, b); }
; #define DPPF(v, ctrl) __builtin_bit_cast(float, __builtin_amdgcn_update_dpp(0, __builtin_bit_cast(int, (v)), (ctrl), 0xf, 0xf, false))
; __device__ __forceinline__ float sigmoidf_(float v) { return fast_rcp(1.0f + fast_exp2(-v * LOG2E)); }
; #define PG8_LAS __attribute__((address_space(3)))
;     __device__ __forceinline__ void run(const f32x4 (&acc)[2][2][4][2], const Unit& u, const Unit& nxt, bool has_next, int ui, int wr, int wc, int fr_in, int fq_in) const {
;     ...
;                 if (grp > 0 && fr == 0) { const PG8_LAS float* xp = xr + ((grp - 1) * 2) * 256 + cl;
;                     hg2 = *(const PG8_LAS f32x4*)(xp); hg3 = *(const PG8_LAS f32x4*)(xp + 256); hv2 = *(const PG8_LAS f32x4*)(xp + 128); hv3 = *(const PG8_LAS f32x4*)(xp + 256 + 128); }
;                 f32x4 pg2, pg1, pv2, pv1;
;                 {
;                     const f32x4 g2 = acc[ai][0][2][n] * rs[ai][2], g3 = acc[ai][0][3][n] * rs[ai][3], v2 = acc[ai][1][2][n] * rs[ai][2], v3 = acc[ai][1][3][n] * rs[ai][3];
; #pragma unroll
;                     for (int i = 0; i < 4; ++i) {
;                         float a0 = g2[i], a1 = g3[i], a2 = v2[i], a3 = v3[i];
;                         asm volatile("" : "+v"(a0), "+v"(a1), "+v"(a2), "+v"(a3));
;                         const float t0 = DPPF(a0, 0x111), t1 = DPPF(a1, 0x111), t2 = DPPF(a2, 0x111), t3 = DPPF(a3, 0x111);
;                         pg2[i] = t0 + hg2[i]; pg1[i] = t1 + hg3[i]; pv2[i] = t2 + hv2[i]; pv1[i] = t3 + hv3[i]; }
;                 }
; #pragma unroll
;                 for (int m = 0; m < 4; ++m) {
;                     const f32x4 gc = acc[ai][0][m][n] * rs[ai][m], vc = acc[ai][1][m][n] * rs[ai][m];
;                     const f32x4 cgt = bg + wg0 * pg2 + wg1 * pg1 + wg2 * gc, cvl = bv + wv0 * pv2 + wv1 * pv1 + wv2 * vc;
;                     float a[4];
; #pragma unroll
;                     for (int i = 0; i < 4; ++i) a[i] = cgt[i] * sigmoidf_(cgt[i]) * cvl[i];
;                     u32x2 w; w.x = pk2(a[0], a[1]); w.y = pk2(a[2], a[3]);
;                     *(u32x2*)(A + (size_t)(u.pm * BM + ai * 128 + wr * 64 + 4 * fr + m) * DFF + ch) = w;
	v_pk_mul_f32 v[170:171], v[176:177], v[178:179]
	v_pk_fma_f32 v[172:173], v[130:131], v[142:143], v[172:173]
	v_exp_f32_e32 v169, v132
	v_pk_fma_f32 v[172:173], v[122:123], v[146:147], v[172:173]
	v_exp_f32_e32 v176, v133
	v_pk_mul_f32 v[170:171], v[172:173], v[170:171]
	v_cvt_pk_bf16_f32 v172, v126, v127
	v_or_b32_e32 v126, 1, v231
	v_mad_i64_i32 v[126:127], s[0:1], v126, s73, v[182:183]
	v_cvt_pk_bf16_f32 v173, v170, v171
	v_lshl_add_u64 v[170:171], v[126:127], 0, v[174:175]
	v_add_f32_e32 v169, 1.0, v169
	global_store_dwordx2 v[170:171], v[172:173], off
	v_rcp_f32_e32 v170, v169
	v_add_f32_e32 v169, 1.0, v176
	v_rcp_f32_e32 v171, v169
	v_pk_fma_f32 v[134:135], v[134:135], v[154:155], v[166:167]
	v_pk_mul_f32 v[118:119], v[118:119], v[102:103] op_sel_hi:[1,0]
	v_pk_fma_f32 v[134:135], v[184:185], v[158:159], v[134:135]
	v_pk_mul_f32 v[132:133], v[132:133], v[170:171]
	v_pk_fma_f32 v[134:135], v[118:119], v[162:163], v[134:135]
	v_pk_mul_f32 v[112:113], v[112:113], v[102:103] op_sel_hi:[1,0]
	v_exp_f32_e32 v173, v135
	v_pk_fma_f32 v[170:171], v[236:237], v[136:137], v[148:149]
	v_pk_fma_f32 v[124:125], v[124:125], v[152:153], v[164:165]
	v_pk_fma_f32 v[170:171], v[120:121], v[140:141], v[170:171]
	v_pk_fma_f32 v[116:117], v[116:117], v[156:157], v[124:125]
	v_pk_fma_f32 v[170:171], v[112:113], v[144:145], v[170:171]
	v_pk_mul_f32 v[132:133], v[170:171], v[132:133]
	v_mov_b32_e32 v170, v103
	v_pk_mul_f32 v[108:109], v[108:109], v[170:171] op_sel_hi:[1,0]
	v_pk_mul_f32 v[110:111], v[110:111], v[170:171] op_sel_hi:[1,0]
	v_pk_fma_f32 v[108:109], v[108:109], v[160:161], v[116:117]
	v_exp_f32_e32 v169, v134
	v_exp_f32_e32 v116, v108
	v_exp_f32_e32 v117, v109
	v_add_f32_e32 v169, 1.0, v169
	v_rcp_f32_e32 v172, v169
	v_add_f32_e32 v116, 1.0, v116
	v_add_f32_e32 v117, 1.0, v117
	v_rcp_f32_e32 v116, v116
	v_rcp_f32_e32 v117, v117
	v_add_f32_e32 v169, 1.0, v173
	v_rcp_f32_e32 v173, v169
	v_pk_mul_f32 v[104:105], v[104:105], v[170:171] op_sel_hi:[1,0]
	v_pk_mul_f32 v[108:109], v[108:109], v[116:117]
	v_pk_fma_f32 v[116:117], v[184:185], v[154:155], v[166:167]
	v_pk_mul_f32 v[114:115], v[114:115], v[102:103] op_sel_hi:[1,0]
	v_pk_fma_f32 v[116:117], v[118:119], v[158:159], v[116:117]
	v_pk_fma_f32 v[130:131], v[130:131], v[138:139], v[150:151]
	v_pk_fma_f32 v[110:111], v[110:111], v[162:163], v[116:117]
	v_pk_fma_f32 v[130:131], v[122:123], v[142:143], v[130:131]
	v_exp_f32_e32 v118, v110
	v_exp_f32_e32 v119, v111
	v_pk_fma_f32 v[116:117], v[120:121], v[136:137], v[148:149]
	v_add_f32_e32 v118, 1.0, v118
	v_rcp_f32_e32 v118, v118
	v_add_f32_e32 v119, 1.0, v119
	v_rcp_f32_e32 v119, v119
	v_pk_fma_f32 v[112:113], v[112:113], v[140:141], v[116:117]
	v_pk_mul_f32 v[106:107], v[106:107], v[170:171] op_sel_hi:[1,0]
	v_pk_fma_f32 v[104:105], v[104:105], v[144:145], v[112:113]
	v_pk_mul_f32 v[134:135], v[134:135], v[172:173]
	v_pk_mul_f32 v[104:105], v[104:105], v[108:109]
	v_pk_mul_f32 v[108:109], v[110:111], v[118:119]
	v_pk_fma_f32 v[110:111], v[122:123], v[138:139], v[150:151]
	v_pk_fma_f32 v[130:131], v[114:115], v[146:147], v[130:131]
	v_pk_fma_f32 v[110:111], v[114:115], v[142:143], v[110:111]
	v_pk_mul_f32 v[130:131], v[130:131], v[134:135]
	v_pk_fma_f32 v[106:107], v[106:107], v[146:147], v[110:111]
	v_cvt_pk_bf16_f32 v135, v130, v131
	v_pk_mul_f32 v[106:107], v[106:107], v[108:109]
	v_or_b32_e32 v130, 2, v231
	v_cvt_pk_bf16_f32 v104, v104, v105
	v_cvt_pk_bf16_f32 v105, v106, v107
	v_or_b32_e32 v106, 3, v231
	v_cvt_pk_bf16_f32 v134, v132, v133
	v_mad_i64_i32 v[132:133], s[0:1], v130, s73, v[182:183]
	v_mad_i64_i32 v[172:173], s[0:1], v106, s73, v[182:183]
	v_lshl_add_u64 v[130:131], v[132:133], 0, v[174:175]
	v_lshl_add_u64 v[106:107], v[172:173], 0, v[174:175]
	global_store_dwordx2 v[130:131], v[134:135], off
	global_store_dwordx2 v[106:107], v[104:105], off
	s_and_b64 s[10:11], s[26:27], s[10:11]
	v_mov_b32_e32 v169, 0
	v_mov_b32_e32 v170, 0
	v_mov_b32_e32 v171, 0
	v_mov_b32_e32 v104, 0
	v_mov_b32_e32 v105, 0
	v_mov_b32_e32 v106, 0
	v_mov_b32_e32 v107, 0
	v_mov_b32_e32 v108, 0
	v_mov_b32_e32 v109, 0
	v_mov_b32_e32 v110, 0
	v_mov_b32_e32 v111, 0
	v_mov_b32_e32 v112, 0
	v_mov_b32_e32 v113, 0
	v_mov_b32_e32 v114, 0
	v_mov_b32_e32 v115, 0
	s_and_saveexec_b64 s[0:1], s[10:11]
	s_cbranch_execz .LBB0_1583
	ds_read_b128 v[112:115], v230 offset:2048
	ds_read_b128 v[104:107], v230 offset:2560
	ds_read_b128 v[108:111], v230 offset:3072
	ds_read_b128 v[168:171], v230 offset:3584
; __device__ __forceinline__ unsigned pk2(float lo, float hi) { f32x2_t v = {lo, hi}; bf16x2_t b = __builtin_convertvector(v, bf16x2_t); return __builtin_bit_cast(unsigned, b); }
; #define DPPF(v, ctrl) __builtin_bit_cast(float, __builtin_amdgcn_update_dpp(0, __builtin_bit_cast(int, (v)), (ctrl), 0xf, 0xf, false))
; __device__ __forceinline__ float sigmoidf_(float v) { return fast_rcp(1.0f + fast_exp2(-v * LOG2E)); }
; #define PG8_LAS __attribute__((address_space(3)))
;     __device__ __forceinline__ void run(const f32x4 (&acc)[2][2][4][2], const Unit& u, const Unit& nxt, bool has_next, int ui, int wr, int wc, int fr_in, int fq_in) const {
;     ...
;                 if (grp > 0 && fr == 0) { const PG8_LAS float* xp = xr + ((grp - 1) * 2) * 256 + cl;
;                     hg2 = *(const PG8_LAS f32x4*)(xp); hg3 = *(const PG8_LAS f32x4*)(xp + 256); hv2 = *(const PG8_LAS f32x4*)(xp + 128); hv3 = *(const PG8_LAS f32x4*)(xp + 256 + 128); }
;                 f32x4 pg2, pg1, pv2, pv1;
;                 {
;                     const f32x4 g2 = acc[ai][0][2][n] * rs[ai][2], g3 = acc[ai][0][3][n] * rs[ai][3], v2 = acc[ai][1][2][n] * rs[ai][2], v3 = acc[ai][1][3][n] * rs[ai][3];
; #pragma unroll
;                     for (int i = 0; i < 4; ++i) {
;                         float a0 = g2[i], a1 = g3[i], a2 = v2[i], a3 = v3[i];
;                         asm volatile("" : "+v"(a0), "+v"(a1), "+v"(a2), "+v"(a3));
;                         const float t0 = DPPF(a0, 0x111), t1 = DPPF(a1, 0x111), t2 = DPPF(a2, 0x111), t3 = DPPF(a3, 0x111);
;                         pg2[i] = t0 + hg2[i]; pg1[i] = t1 + hg3[i]; pv2[i] = t2 + hv2[i]; pv1[i] = t3 + hv3[i]; }
;                 }
; #pragma unroll
;                 for (int m = 0; m < 4; ++m) {
;                     const f32x4 gc = acc[ai][0][m][n] * rs[ai][m], vc = acc[ai][1][m][n] * rs[ai][m];
;                     const f32x4 cgt = bg + wg0 * pg2 + wg1 * pg1 + wg2 * gc, cvl = bv + wv0 * pv2 + wv1 * pv1 + wv2 * vc;
;                     float a[4];
; #pragma unroll
;                     for (int i = 0; i < 4; ++i) a[i] = cgt[i] * sigmoidf_(cgt[i]) * cvl[i];
;                     u32x2 w; w.x = pk2(a[0], a[1]); w.y = pk2(a[2], a[3]);
;                     *(u32x2*)(A + (size_t)(u.pm * BM + ai * 128 + wr * 64 + 4 * fr + m) * DFF + ch) = w;
.LBB0_1583:
	s_or_b64 exec, exec, s[0:1]
	v_mul_f32_dpp v118, v68, v201 row_shr:1 row_mask:0xf bank_mask:0xf bound_ctrl:1
	v_mul_f32_dpp v120, v76, v200 row_shr:1 row_mask:0xf bank_mask:0xf bound_ctrl:1
	v_mul_f32_dpp v122, v64, v201 row_shr:1 row_mask:0xf bank_mask:0xf bound_ctrl:1
	v_mul_f32_dpp v116, v80, v200 row_shr:1 row_mask:0xf bank_mask:0xf bound_ctrl:1
	v_pk_mul_f32 v[96:97], v[96:97], v[72:73] op_sel_hi:[1,0]
	v_mul_f32_dpp v117, v81, v200 row_shr:1 row_mask:0xf bank_mask:0xf bound_ctrl:1
	s_waitcnt lgkmcnt(0)
	v_pk_add_f32 v[112:113], v[112:113], v[116:117]
	v_mul_f32_dpp v119, v69, v201 row_shr:1 row_mask:0xf bank_mask:0xf bound_ctrl:1
	v_pk_add_f32 v[108:109], v[108:109], v[118:119]
	v_pk_fma_f32 v[112:113], v[152:153], v[112:113], v[164:165]
	v_pk_fma_f32 v[112:113], v[156:157], v[108:109], v[112:113]
	v_pk_fma_f32 v[112:113], v[96:97], v[160:161], v[112:113]
	v_exp_f32_e32 v116, v112
	v_exp_f32_e32 v117, v113
	v_mul_f32_dpp v121, v77, v200 row_shr:1 row_mask:0xf bank_mask:0xf bound_ctrl:1
	v_mul_f32_dpp v123, v65, v201 row_shr:1 row_mask:0xf bank_mask:0xf bound_ctrl:1
	v_mul_f32_dpp v130, v70, v201 row_shr:1 row_mask:0xf bank_mask:0xf bound_ctrl:1
	v_mul_f32_dpp v134, v78, v200 row_shr:1 row_mask:0xf bank_mask:0xf bound_ctrl:1
	v_mul_f32_dpp v178, v66, v201 row_shr:1 row_mask:0xf bank_mask:0xf bound_ctrl:1
	v_mul_f32_dpp v124, v82, v200 row_shr:1 row_mask:0xf bank_mask:0xf bound_ctrl:1
	v_add_f32_e32 v116, 1.0, v116
	v_add_f32_e32 v117, 1.0, v117
	v_mul_f32_dpp v125, v83, v200 row_shr:1 row_mask:0xf bank_mask:0xf bound_ctrl:1
	v_rcp_f32_e32 v116, v116
	v_rcp_f32_e32 v117, v117
	v_mul_f32_dpp v131, v71, v201 row_shr:1 row_mask:0xf bank_mask:0xf bound_ctrl:1
	v_pk_add_f32 v[114:115], v[114:115], v[124:125]
	v_pk_add_f32 v[110:111], v[110:111], v[130:131]
	v_pk_fma_f32 v[114:115], v[154:155], v[114:115], v[166:167]
	v_pk_mul_f32 v[98:99], v[98:99], v[72:73] op_sel_hi:[1,0]
	v_pk_fma_f32 v[114:115], v[158:159], v[110:111], v[114:115]
	v_pk_mul_f32 v[112:113], v[112:113], v[116:117]
	v_pk_fma_f32 v[114:115], v[98:99], v[162:163], v[114:115]
	v_pk_add_f32 v[104:105], v[104:105], v[120:121]
	v_exp_f32_e32 v116, v114
	v_exp_f32_e32 v117, v115
	v_pk_add_f32 v[118:119], v[168:169], v[122:123]
	v_add_f32_e32 v116, 1.0, v116
	v_add_f32_e32 v117, 1.0, v117
	v_rcp_f32_e32 v116, v116
	v_rcp_f32_e32 v117, v117
	v_pk_fma_f32 v[104:105], v[136:137], v[104:105], v[148:149]
	v_mul_f32_dpp v135, v79, v200 row_shr:1 row_mask:0xf bank_mask:0xf bound_ctrl:1
	v_pk_mul_f32 v[92:93], v[92:93], v[72:73] op_sel_hi:[1,0]
	v_pk_fma_f32 v[104:105], v[140:141], v[118:119], v[104:105]
	v_mul_f32_dpp v179, v67, v201 row_shr:1 row_mask:0xf bank_mask:0xf bound_ctrl:1
	v_pk_fma_f32 v[104:105], v[92:93], v[144:145], v[104:105]
	v_pk_add_f32 v[106:107], v[106:107], v[134:135]
	v_pk_mul_f32 v[114:115], v[114:115], v[116:117]
	v_mov_b32_e32 v116, v73
	v_pk_fma_f32 v[108:109], v[152:153], v[108:109], v[164:165]
	v_pk_mul_f32 v[104:105], v[104:105], v[112:113]
	v_pk_add_f32 v[112:113], v[170:171], v[178:179]
	v_pk_fma_f32 v[106:107], v[138:139], v[106:107], v[150:151]
	v_pk_mul_f32 v[88:89], v[88:89], v[116:117] op_sel_hi:[1,0]
	v_pk_fma_f32 v[108:109], v[96:97], v[156:157], v[108:109]
	v_pk_mul_f32 v[94:95], v[94:95], v[72:73] op_sel_hi:[1,0]
	v_pk_fma_f32 v[106:107], v[142:143], v[112:113], v[106:107]
	v_pk_fma_f32 v[108:109], v[88:89], v[160:161], v[108:109]
	v_pk_fma_f32 v[106:107], v[94:95], v[146:147], v[106:107]
	v_pk_mul_f32 v[106:107], v[106:107], v[114:115]
	v_exp_f32_e32 v117, v108
	v_exp_f32_e32 v120, v109
	v_add_u32_e32 v177, 0x80, v231
	v_cvt_pk_bf16_f32 v104, v104, v105
	v_cvt_pk_bf16_f32 v105, v106, v107
	v_mov_b64_e32 v[106:107], s[16:17]
	v_mad_i64_i32 v[122:123], s[0:1], v177, s73, v[106:107]
	v_lshl_add_u64 v[114:115], v[122:123], 0, v[174:175]
	global_store_dwordx2 v[114:115], v[104:105], off
	v_add_f32_e32 v104, 1.0, v117
	v_add_f32_e32 v105, 1.0, v120
	v_rcp_f32_e32 v104, v104
	v_rcp_f32_e32 v105, v105
	v_pk_mul_f32 v[90:91], v[90:91], v[116:117] op_sel_hi:[1,0]
	v_pk_mul_f32 v[84:85], v[84:85], v[116:117] op_sel_hi:[1,0]
	v_pk_fma_f32 v[96:97], v[96:97], v[152:153], v[164:165]
	v_pk_mul_f32 v[104:105], v[108:109], v[104:105]
	v_pk_fma_f32 v[108:109], v[154:155], v[110:111], v[166:167]
	v_pk_mul_f32 v[86:87], v[86:87], v[116:117] op_sel_hi:[1,0]
	v_pk_fma_f32 v[108:109], v[98:99], v[158:159], v[108:109]
	v_pk_mul_f32 v[80:81], v[80:81], v[74:75] op_sel_hi:[1,0]
	v_pk_fma_f32 v[108:109], v[90:91], v[162:163], v[108:109]
	v_pk_fma_f32 v[96:97], v[88:89], v[156:157], v[96:97]
	v_exp_f32_e32 v114, v108
	v_exp_f32_e32 v115, v109
	v_pk_fma_f32 v[110:111], v[136:137], v[118:119], v[148:149]
	v_add_f32_e32 v114, 1.0, v114
	v_rcp_f32_e32 v114, v114
	v_add_f32_e32 v115, 1.0, v115
	v_rcp_f32_e32 v115, v115
	v_pk_fma_f32 v[110:111], v[92:93], v[140:141], v[110:111]
	v_pk_fma_f32 v[96:97], v[80:81], v[160:161], v[96:97]
	v_pk_fma_f32 v[110:111], v[84:85], v[144:145], v[110:111]
	v_pk_mul_f32 v[108:109], v[108:109], v[114:115]
	v_pk_mul_f32 v[104:105], v[110:111], v[104:105]
	v_pk_fma_f32 v[110:111], v[138:139], v[112:113], v[150:151]
	v_cvt_pk_bf16_f32 v104, v104, v105
	v_pk_fma_f32 v[110:111], v[94:95], v[142:143], v[110:111]
	v_pk_fma_f32 v[98:99], v[98:99], v[154:155], v[166:167]
	v_pk_fma_f32 v[110:111], v[86:87], v[146:147], v[110:111]
	v_pk_mul_f32 v[82:83], v[82:83], v[74:75] op_sel_hi:[1,0]
	v_pk_mul_f32 v[108:109], v[110:111], v[108:109]
	v_exp_f32_e32 v110, v96
	v_exp_f32_e32 v111, v97
	v_cvt_pk_bf16_f32 v105, v108, v109
	v_add_u32_e32 v108, 0x81, v231
	v_mad_i64_i32 v[124:125], s[0:1], v108, s73, v[106:107]
	v_lshl_add_u64 v[108:109], v[124:125], 0, v[174:175]
;     __device__ __forceinline__ void run(const f32x4 (&acc)[2][2][4][2], const Unit& u, const Unit& nxt, bool has_next, int ui, int wr, int wc, int fr_in, int fq_in) const {
;     ...
;         for (int n = 0; n < 2; ++n) {
;             const int cl = wc * 32 + n * 16 + 4 * fq, ch = u.pn * 128 + cl;
;             const PG8_LAS float* pp = prm + slot * 1024 + cl;
;             const f32x4 wg0 = *(const PG8_LAS f32x4*)(pp), wg1 = *(const PG8_LAS f32x4*)(pp + 128), wg2 = *(const PG8_LAS f32x4*)(pp + 256), bg = *(const PG8_LAS f32x4*)(pp + 384);
;             const f32x4 wv0 = *(const PG8_LAS f32x4*)(pp + 512), wv1 = *(const PG8_LAS f32x4*)(pp + 640), wv2 = *(const PG8_LAS f32x4*)(pp + 768), bv = *(const PG8_LAS f32x4*)(pp + 896);
; #pragma unroll
;             for (int ai = 0; ai < 2; ++ai) {
;                 const int grp = 2 * ai + wr;
;                 f32x4 hg2 = {0.f, 0.f, 0.f, 0.f}, hg3 = hg2, hv2 = hg2, hv3 = hg2;
;                 if (grp > 0 && fr == 0) { const PG8_LAS float* xp = xr + ((grp - 1) * 2) * 256 + cl;
;                     hg2 = *(const PG8_LAS f32x4*)(xp); hg3 = *(const PG8_LAS f32x4*)(xp + 256); hv2 = *(const PG8_LAS f32x4*)(xp + 128); hv3 = *(const PG8_LAS f32x4*)(xp + 256 + 128); }
;                 f32x4 pg2, pg1, pv2, pv1;
;                 {
;                     const f32x4 g2 = acc[ai][0][2][n] * rs[ai][2], g3 = acc[ai][0][3][n] * rs[ai][3], v2 = acc[ai][1][2][n] * rs[ai][2], v3 = acc[ai][1][3][n] * rs[ai][3];
; #pragma unroll
;                     for (int i = 0; i < 4; ++i) {
;                         float a0 = g2[i], a1 = g3[i], a2 = v2[i], a3 = v3[i];
;                         asm volatile("" : "+v"(a0), "+v"(a1), "+v"(a2), "+v"(a3));
;                         const float t0 = DPPF(a0, 0x111), t1 = DPPF(a1, 0x111), t2 = DPPF(a2, 0x111), t3 = DPPF(a3, 0x111);
;                         pg2[i] = t0 + hg2[i]; pg1[i] = t1 + hg3[i]; pv2[i] = t2 + hv2[i]; pv1[i] = t3 + hv3[i]; }
;                 }
; #pragma unroll
;                 for (int m = 0; m < 4; ++m) {
;                     const f32x4 gc = acc[ai][0][m][n] * rs[ai][m], vc = acc[ai][1][m][n] * rs[ai][m];
;                     const f32x4 cgt = bg + wg0 * pg2 + wg1 * pg1 + wg2 * gc, cvl = bv + wv0 * pv2 + wv1 * pv1 + wv2 * vc;
;                     float a[4];
; #pragma unroll
;                     for (int i = 0; i < 4; ++i) a[i] = cgt[i] * sigmoidf_(cgt[i]) * cvl[i];
	global_store_dwordx2 v[108:109], v[104:105], off
	v_add_f32_e32 v104, 1.0, v110
	v_add_f32_e32 v105, 1.0, v111
	v_rcp_f32_e32 v104, v104
	v_rcp_f32_e32 v105, v105
	v_pk_fma_f32 v[98:99], v[90:91], v[158:159], v[98:99]
	v_pk_fma_f32 v[92:93], v[92:93], v[136:137], v[148:149]
	v_pk_fma_f32 v[98:99], v[82:83], v[162:163], v[98:99]
	v_pk_mul_f32 v[96:97], v[96:97], v[104:105]
	v_exp_f32_e32 v104, v98
	v_exp_f32_e32 v105, v99
	v_pk_mul_f32 v[76:77], v[76:77], v[74:75] op_sel_hi:[1,0]
	v_pk_fma_f32 v[92:93], v[84:85], v[140:141], v[92:93]
	v_add_f32_e32 v104, 1.0, v104
	v_add_f32_e32 v105, 1.0, v105
	v_rcp_f32_e32 v104, v104
	v_rcp_f32_e32 v105, v105
	v_pk_fma_f32 v[94:95], v[94:95], v[138:139], v[150:151]
	v_pk_mul_f32 v[78:79], v[78:79], v[74:75] op_sel_hi:[1,0]
	v_pk_fma_f32 v[92:93], v[76:77], v[144:145], v[92:93]
	v_pk_fma_f32 v[94:95], v[86:87], v[142:143], v[94:95]
	v_pk_mul_f32 v[92:93], v[92:93], v[96:97]
	v_pk_mul_f32 v[96:97], v[98:99], v[104:105]
	v_pk_fma_f32 v[94:95], v[78:79], v[146:147], v[94:95]
	v_pk_fma_f32 v[88:89], v[152:153], v[88:89], v[164:165]
	v_pk_mul_f32 v[94:95], v[94:95], v[96:97]
	v_mov_b32_e32 v96, v75
	v_pk_mul_f32 v[68:69], v[68:69], v[96:97] op_sel_hi:[1,0]
	v_pk_fma_f32 v[80:81], v[156:157], v[80:81], v[88:89]
	v_pk_mul_f32 v[70:71], v[70:71], v[96:97] op_sel_hi:[1,0]
	v_pk_fma_f32 v[68:69], v[160:161], v[68:69], v[80:81]
	v_pk_mul_f32 v[64:65], v[64:65], v[96:97] op_sel_hi:[1,0]
	v_exp_f32_e32 v80, v68
	v_exp_f32_e32 v81, v69
	v_pk_mul_f32 v[66:67], v[66:67], v[96:97] op_sel_hi:[1,0]
	v_cvt_pk_bf16_f32 v92, v92, v93
	v_add_f32_e32 v80, 1.0, v80
	v_add_f32_e32 v81, 1.0, v81
	v_rcp_f32_e32 v80, v80
	v_rcp_f32_e32 v81, v81
	v_cvt_pk_bf16_f32 v93, v94, v95
	v_add_u32_e32 v94, 0x82, v231
	v_mad_i64_i32 v[130:131], s[0:1], v94, s73, v[106:107]
	v_pk_mul_f32 v[68:69], v[68:69], v[80:81]
	v_pk_fma_f32 v[80:81], v[154:155], v[90:91], v[166:167]
	v_lshl_add_u64 v[94:95], v[130:131], 0, v[174:175]
	v_pk_fma_f32 v[80:81], v[158:159], v[82:83], v[80:81]
	global_store_dwordx2 v[94:95], v[92:93], off
	v_pk_fma_f32 v[70:71], v[162:163], v[70:71], v[80:81]
	v_add_u32_e32 v176, 16, v202
	v_exp_f32_e32 v82, v70
	v_exp_f32_e32 v83, v71
	v_pk_fma_f32 v[80:81], v[84:85], v[136:137], v[148:149]
	v_add_f32_e32 v82, 1.0, v82
	v_rcp_f32_e32 v82, v82
	v_add_f32_e32 v83, 1.0, v83
	v_rcp_f32_e32 v83, v83
	v_pk_fma_f32 v[76:77], v[76:77], v[140:141], v[80:81]
	v_mov_b32_e32 v104, 0
	v_pk_fma_f32 v[64:65], v[64:65], v[144:145], v[76:77]
	v_mov_b32_e32 v108, 0
	v_pk_mul_f32 v[64:65], v[64:65], v[68:69]
	v_pk_mul_f32 v[68:69], v[70:71], v[82:83]
	v_pk_fma_f32 v[70:71], v[86:87], v[138:139], v[150:151]
	v_cvt_pk_bf16_f32 v64, v64, v65
	v_pk_fma_f32 v[70:71], v[78:79], v[142:143], v[70:71]
	v_mov_b32_e32 v109, 0
	v_pk_fma_f32 v[66:67], v[66:67], v[146:147], v[70:71]
	v_mov_b32_e32 v110, 0
	v_pk_mul_f32 v[66:67], v[66:67], v[68:69]
	v_mov_b32_e32 v111, 0
	v_cvt_pk_bf16_f32 v65, v66, v67
	v_add_u32_e32 v66, 0x83, v231
	v_mad_i64_i32 v[134:135], s[0:1], v66, s73, v[106:107]
	v_lshl_add_u64 v[66:67], v[134:135], 0, v[174:175]
	global_store_dwordx2 v[66:67], v[64:65], off
	ds_read_b128 v[84:87], v203 offset:64
	ds_read_b128 v[88:91], v203 offset:576
	ds_read_b128 v[92:95], v203 offset:1088
	ds_read_b128 v[96:99], v203 offset:1600
	ds_read_b128 v[64:67], v203 offset:2112
	ds_read_b128 v[68:71], v203 offset:2624
	ds_read_b128 v[76:79], v203 offset:3136
	ds_read_b128 v[80:83], v203 offset:3648
	v_mov_b32_e32 v106, 0
	v_mov_b32_e32 v107, 0
	v_mov_b32_e32 v112, 0
	v_mov_b32_e32 v113, 0
	v_mov_b32_e32 v114, 0
	v_mov_b32_e32 v115, 0
	v_mov_b32_e32 v116, 0
	v_mov_b32_e32 v117, 0
	v_mov_b32_e32 v118, 0
	v_mov_b32_e32 v119, 0
	v_mov_b32_e32 v120, 0
	v_mov_b32_e32 v121, 0
	s_and_saveexec_b64 s[0:1], s[4:5]
	s_cbranch_execz .LBB0_1585
	v_lshl_add_u32 v105, v176, 2, s69
	ds_read_b128 v[118:121], v105
	ds_read_b128 v[110:113], v105 offset:512
	ds_read_b128 v[114:117], v105 offset:1024
	ds_read_b128 v[106:109], v105 offset:1536
.LBB0_1585:
	s_or_b64 exec, exec, s[0:1]
	v_mul_f32_dpp v146, v44, v198 row_shr:1 row_mask:0xf bank_mask:0xf bound_ctrl:1
	s_nop 0
	v_mul_f32_dpp v152, v32, v199 row_shr:1 row_mask:0xf bank_mask:0xf bound_ctrl:1
	v_mul_f32_dpp v150, v40, v198 row_shr:1 row_mask:0xf bank_mask:0xf bound_ctrl:1
	v_mul_f32_dpp v148, v36, v199 row_shr:1 row_mask:0xf bank_mask:0xf bound_ctrl:1
	v_mul_f32_dpp v149, v37, v199 row_shr:1 row_mask:0xf bank_mask:0xf bound_ctrl:1
	v_mul_f32_dpp v147, v45, v198 row_shr:1 row_mask:0xf bank_mask:0xf bound_ctrl:1
	v_mul_f32_dpp v151, v41, v198 row_shr:1 row_mask:0xf bank_mask:0xf bound_ctrl:1
	v_mul_f32_dpp v153, v33, v199 row_shr:1 row_mask:0xf bank_mask:0xf bound_ctrl:1
	v_mul_f32_dpp v154, v46, v198 row_shr:1 row_mask:0xf bank_mask:0xf bound_ctrl:1
	v_mul_f32_dpp v160, v34, v199 row_shr:1 row_mask:0xf bank_mask:0xf bound_ctrl:1
	s_waitcnt lgkmcnt(0)
; __device__ __forceinline__ unsigned pk2(float lo, float hi) { f32x2_t v = {lo, hi}; bf16x2_t b = __builtin_convertvector(v, bf16x2_t); return __builtin_bit_cast(unsigned, b); }
; #define DPPF(v, ctrl) __builtin_bit_cast(float, __builtin_amdgcn_update_dpp(0, __builtin_bit_cast(int, (v)), (ctrl), 0xf, 0xf, false))
; __device__ __forceinline__ float sigmoidf_(float v) { return fast_rcp(1.0f + fast_exp2(-v * LOG2E)); }
;     __device__ __forceinline__ void run(const f32x4 (&acc)[2][2][4][2], const Unit& u, const Unit& nxt, bool has_next, int ui, int wr, int wc, int fr_in, int fq_in) const {
;     ...
;                     const f32x4 g2 = acc[ai][0][2][n] * rs[ai][2], g3 = acc[ai][0][3][n] * rs[ai][3], v2 = acc[ai][1][2][n] * rs[ai][2], v3 = acc[ai][1][3][n] * rs[ai][3];
; #pragma unroll
;                     for (int i = 0; i < 4; ++i) {
;                         float a0 = g2[i], a1 = g3[i], a2 = v2[i], a3 = v3[i];
;                         asm volatile("" : "+v"(a0), "+v"(a1), "+v"(a2), "+v"(a3));
;                         const float t0 = DPPF(a0, 0x111), t1 = DPPF(a1, 0x111), t2 = DPPF(a2, 0x111), t3 = DPPF(a3, 0x111);
;                         pg2[i] = t0 + hg2[i]; pg1[i] = t1 + hg3[i]; pv2[i] = t2 + hv2[i]; pv1[i] = t3 + hv3[i]; }
;                 }
; #pragma unroll
;                 for (int m = 0; m < 4; ++m) {
;                     const f32x4 gc = acc[ai][0][m][n] * rs[ai][m], vc = acc[ai][1][m][n] * rs[ai][m];
;                     const f32x4 cgt = bg + wg0 * pg2 + wg1 * pg1 + wg2 * gc, cvl = bv + wv0 * pv2 + wv1 * pv1 + wv2 * vc;
;                     float a[4];
; #pragma unroll
;                     for (int i = 0; i < 4; ++i) a[i] = cgt[i] * sigmoidf_(cgt[i]) * cvl[i];
;                     u32x2 w; w.x = pk2(a[0], a[1]); w.y = pk2(a[2], a[3]);
;                     *(u32x2*)(A + (size_t)(u.pm * BM + ai * 128 + wr * 64 + 4 * fr + m) * DFF + ch) = w;
	v_pk_add_f32 v[118:119], v[118:119], v[146:147]
	v_mov_b32_e32 v140, v100
	v_mov_b32_e32 v141, v100
	v_mul_f32_dpp v158, v42, v198 row_shr:1 row_mask:0xf bank_mask:0xf bound_ctrl:1
	v_pk_add_f32 v[114:115], v[114:115], v[148:149]
	v_pk_fma_f32 v[118:119], v[84:85], v[118:119], v[96:97]
	v_mul_f32_dpp v157, v39, v199 row_shr:1 row_mask:0xf bank_mask:0xf bound_ctrl:1
	v_pk_mul_f32 v[60:61], v[60:61], v[140:141]
	v_pk_fma_f32 v[118:119], v[88:89], v[114:115], v[118:119]
	v_mul_f32_dpp v159, v43, v198 row_shr:1 row_mask:0xf bank_mask:0xf bound_ctrl:1
	v_pk_fma_f32 v[118:119], v[60:61], v[92:93], v[118:119]
	v_mul_f32_dpp v156, v38, v199 row_shr:1 row_mask:0xf bank_mask:0xf bound_ctrl:1
	v_mul_f32_dpp v161, v35, v199 row_shr:1 row_mask:0xf bank_mask:0xf bound_ctrl:1
	v_mov_b32_e32 v162, v100
	v_mov_b32_e32 v163, v100
	v_mul_f32_dpp v155, v47, v198 row_shr:1 row_mask:0xf bank_mask:0xf bound_ctrl:1
	v_exp_f32_e32 v100, v118
	v_exp_f32_e32 v105, v119
	v_pk_mul_f32 v[140:141], v[56:57], v[140:141]
	v_add_f32_e32 v100, 1.0, v100
	v_rcp_f32_e32 v146, v100
	v_add_f32_e32 v100, 1.0, v105
	v_rcp_f32_e32 v147, v100
	v_pk_add_f32 v[56:57], v[110:111], v[150:151]
	v_pk_add_f32 v[116:117], v[116:117], v[156:157]
	v_pk_mul_f32 v[62:63], v[62:63], v[162:163]
	v_pk_mul_f32 v[110:111], v[118:119], v[146:147]
	v_pk_add_f32 v[118:119], v[120:121], v[154:155]
	v_pk_add_f32 v[106:107], v[106:107], v[152:153]
	v_pk_fma_f32 v[118:119], v[86:87], v[118:119], v[98:99]
	v_pk_fma_f32 v[56:57], v[64:65], v[56:57], v[80:81]
	v_pk_fma_f32 v[118:119], v[90:91], v[116:117], v[118:119]
	v_pk_fma_f32 v[56:57], v[68:69], v[106:107], v[56:57]
	v_pk_fma_f32 v[118:119], v[62:63], v[94:95], v[118:119]
	v_pk_fma_f32 v[56:57], v[140:141], v[76:77], v[56:57]
	v_exp_f32_e32 v100, v118
	v_exp_f32_e32 v105, v119
	v_pk_mul_f32 v[56:57], v[56:57], v[110:111]
	v_add_f32_e32 v100, 1.0, v100
	v_rcp_f32_e32 v120, v100
	v_add_f32_e32 v100, 1.0, v105
	v_rcp_f32_e32 v121, v100
	v_pk_add_f32 v[110:111], v[112:113], v[158:159]
	v_pk_add_f32 v[108:109], v[108:109], v[160:161]
	v_pk_fma_f32 v[110:111], v[66:67], v[110:111], v[82:83]
	v_add_u32_e32 v144, s12, v176
	v_pk_mul_f32 v[58:59], v[58:59], v[162:163]
	v_pk_fma_f32 v[110:111], v[70:71], v[108:109], v[110:111]
	v_ashrrev_i32_e32 v145, 31, v144
	v_pk_mul_f32 v[112:113], v[118:119], v[120:121]
	v_pk_fma_f32 v[110:111], v[58:59], v[78:79], v[110:111]
	v_mov_b32_e32 v142, v101
	v_pk_mul_f32 v[110:111], v[110:111], v[112:113]
	v_cvt_pk_bf16_f32 v112, v56, v57
	v_lshlrev_b64 v[56:57], 1, v[144:145]
	v_cvt_pk_bf16_f32 v113, v110, v111
	v_lshl_add_u64 v[110:111], v[128:129], 0, v[56:57]
	v_mov_b32_e32 v143, v101
	global_store_dwordx2 v[110:111], v[112:113], off
	v_pk_fma_f32 v[110:111], v[84:85], v[114:115], v[96:97]
	v_pk_mul_f32 v[52:53], v[52:53], v[142:143]
	v_pk_fma_f32 v[110:111], v[60:61], v[88:89], v[110:111]
	v_pk_fma_f32 v[106:107], v[64:65], v[106:107], v[80:81]
	v_pk_fma_f32 v[110:111], v[52:53], v[92:93], v[110:111]
	v_pk_mul_f32 v[48:49], v[48:49], v[142:143]
	v_exp_f32_e32 v105, v110
	v_exp_f32_e32 v113, v111
	v_mov_b32_e32 v100, v101
	v_add_f32_e32 v105, 1.0, v105
	v_rcp_f32_e32 v112, v105
	v_add_f32_e32 v105, 1.0, v113
	v_rcp_f32_e32 v113, v105
	v_pk_mul_f32 v[54:55], v[54:55], v[100:101]
	v_pk_mul_f32 v[50:51], v[50:51], v[100:101]
	v_pk_fma_f32 v[106:107], v[140:141], v[68:69], v[106:107]
	v_pk_mul_f32 v[100:101], v[110:111], v[112:113]
	v_pk_fma_f32 v[110:111], v[86:87], v[116:117], v[98:99]
	v_pk_fma_f32 v[108:109], v[66:67], v[108:109], v[82:83]
	v_pk_fma_f32 v[110:111], v[62:63], v[90:91], v[110:111]
	v_pk_fma_f32 v[106:107], v[48:49], v[76:77], v[106:107]
	v_pk_fma_f32 v[110:111], v[54:55], v[94:95], v[110:111]
	v_pk_fma_f32 v[108:109], v[58:59], v[70:71], v[108:109]
	v_exp_f32_e32 v105, v110
	v_exp_f32_e32 v113, v111
	v_mov_b32_e32 v138, v102
	v_add_f32_e32 v105, 1.0, v105
	v_rcp_f32_e32 v112, v105
	v_add_f32_e32 v105, 1.0, v113
	v_rcp_f32_e32 v113, v105
	v_mov_b32_e32 v139, v102
	v_pk_mul_f32 v[100:101], v[106:107], v[100:101]
	v_pk_fma_f32 v[108:109], v[50:51], v[78:79], v[108:109]
	v_pk_mul_f32 v[106:107], v[110:111], v[112:113]
	v_pk_fma_f32 v[60:61], v[60:61], v[84:85], v[96:97]
	v_pk_mul_f32 v[106:107], v[108:109], v[106:107]
	v_pk_mul_f32 v[44:45], v[44:45], v[138:139]
	v_pk_fma_f32 v[60:61], v[52:53], v[88:89], v[60:61]
	v_cvt_pk_bf16_f32 v100, v100, v101
	v_cvt_pk_bf16_f32 v101, v106, v107
	v_lshl_add_u64 v[106:107], v[126:127], 0, v[56:57]
	v_pk_fma_f32 v[60:61], v[44:45], v[92:93], v[60:61]
	v_mov_b32_e32 v136, v103
	v_mov_b32_e32 v137, v103
	global_store_dwordx2 v[106:107], v[100:101], off
	v_pk_fma_f32 v[52:53], v[52:53], v[84:85], v[96:97]
	v_exp_f32_e32 v105, v60
	v_pk_mul_f32 v[36:37], v[36:37], v[136:137]
	v_pk_fma_f32 v[44:45], v[44:45], v[88:89], v[52:53]
	v_exp_f32_e32 v107, v61
	v_pk_fma_f32 v[36:37], v[36:37], v[92:93], v[44:45]
	v_mov_b32_e32 v100, v102
	v_mov_b32_e32 v101, v102
	v_pk_fma_f32 v[62:63], v[62:63], v[86:87], v[98:99]
	v_pk_mul_f32 v[46:47], v[46:47], v[100:101]
	v_pk_fma_f32 v[62:63], v[54:55], v[90:91], v[62:63]
	v_exp_f32_e32 v44, v36
	v_exp_f32_e32 v45, v37
	v_add_f32_e32 v102, 1.0, v105
	v_pk_fma_f32 v[62:63], v[46:47], v[94:95], v[62:63]
	v_rcp_f32_e32 v106, v102
	v_add_f32_e32 v102, 1.0, v107
	v_pk_mul_f32 v[42:43], v[42:43], v[100:101]
	v_rcp_f32_e32 v107, v102
	v_exp_f32_e32 v102, v62
	v_exp_f32_e32 v105, v63
	v_add_f32_e32 v44, 1.0, v44
	v_add_f32_e32 v45, 1.0, v45
	v_rcp_f32_e32 v44, v44
	v_rcp_f32_e32 v45, v45
	v_add_f32_e32 v102, 1.0, v102
	v_pk_mul_f32 v[60:61], v[60:61], v[106:107]
	v_rcp_f32_e32 v106, v102
	v_add_f32_e32 v102, 1.0, v105
	v_rcp_f32_e32 v107, v102
; __device__ __forceinline__ unsigned pk2(float lo, float hi) { f32x2_t v = {lo, hi}; bf16x2_t b = __builtin_convertvector(v, bf16x2_t); return __builtin_bit_cast(unsigned, b); }
; #define DPPF(v, ctrl) __builtin_bit_cast(float, __builtin_amdgcn_update_dpp(0, __builtin_bit_cast(int, (v)), (ctrl), 0xf, 0xf, false))
; __device__ __forceinline__ float sigmoidf_(float v) { return fast_rcp(1.0f + fast_exp2(-v * LOG2E)); }
; #define PG8_LAS __attribute__((address_space(3)))
;     __device__ __forceinline__ void run(const f32x4 (&acc)[2][2][4][2], const Unit& u, const Unit& nxt, bool has_next, int ui, int wr, int wc, int fr_in, int fq_in) const {
;     ...
;                 if (grp > 0 && fr == 0) { const PG8_LAS float* xp = xr + ((grp - 1) * 2) * 256 + cl;
;                     hg2 = *(const PG8_LAS f32x4*)(xp); hg3 = *(const PG8_LAS f32x4*)(xp + 256); hv2 = *(const PG8_LAS f32x4*)(xp + 128); hv3 = *(const PG8_LAS f32x4*)(xp + 256 + 128); }
;                 f32x4 pg2, pg1, pv2, pv1;
;                 {
;                     const f32x4 g2 = acc[ai][0][2][n] * rs[ai][2], g3 = acc[ai][0][3][n] * rs[ai][3], v2 = acc[ai][1][2][n] * rs[ai][2], v3 = acc[ai][1][3][n] * rs[ai][3];
; #pragma unroll
;                     for (int i = 0; i < 4; ++i) {
;                         float a0 = g2[i], a1 = g3[i], a2 = v2[i], a3 = v3[i];
;                         asm volatile("" : "+v"(a0), "+v"(a1), "+v"(a2), "+v"(a3));
;                         const float t0 = DPPF(a0, 0x111), t1 = DPPF(a1, 0x111), t2 = DPPF(a2, 0x111), t3 = DPPF(a3, 0x111);
;                         pg2[i] = t0 + hg2[i]; pg1[i] = t1 + hg3[i]; pv2[i] = t2 + hv2[i]; pv1[i] = t3 + hv3[i]; }
;                 }
; #pragma unroll
;                 for (int m = 0; m < 4; ++m) {
;                     const f32x4 gc = acc[ai][0][m][n] * rs[ai][m], vc = acc[ai][1][m][n] * rs[ai][m];
;                     const f32x4 cgt = bg + wg0 * pg2 + wg1 * pg1 + wg2 * gc, cvl = bv + wv0 * pv2 + wv1 * pv1 + wv2 * vc;
;                     float a[4];
; #pragma unroll
;                     for (int i = 0; i < 4; ++i) a[i] = cgt[i] * sigmoidf_(cgt[i]) * cvl[i];
;                     u32x2 w; w.x = pk2(a[0], a[1]); w.y = pk2(a[2], a[3]);
;                     *(u32x2*)(A + (size_t)(u.pm * BM + ai * 128 + wr * 64 + 4 * fr + m) * DFF + ch) = w;
	v_mov_b32_e32 v102, v103
	v_pk_mul_f32 v[36:37], v[36:37], v[44:45]
	v_pk_fma_f32 v[44:45], v[54:55], v[86:87], v[98:99]
	v_pk_mul_f32 v[38:39], v[38:39], v[102:103]
	v_pk_fma_f32 v[44:45], v[46:47], v[90:91], v[44:45]
	v_pk_fma_f32 v[100:101], v[140:141], v[64:65], v[80:81]
	v_pk_fma_f32 v[38:39], v[38:39], v[94:95], v[44:45]
	v_pk_mul_f32 v[40:41], v[40:41], v[138:139]
	v_exp_f32_e32 v46, v38
	v_exp_f32_e32 v47, v39
	v_pk_fma_f32 v[100:101], v[48:49], v[68:69], v[100:101]
	v_add_f32_e32 v46, 1.0, v46
	v_rcp_f32_e32 v46, v46
	v_add_f32_e32 v47, 1.0, v47
	v_rcp_f32_e32 v47, v47
	v_pk_fma_f32 v[44:45], v[48:49], v[64:65], v[80:81]
	v_pk_fma_f32 v[100:101], v[40:41], v[76:77], v[100:101]
	v_pk_mul_f32 v[32:33], v[32:33], v[136:137]
	v_pk_fma_f32 v[40:41], v[40:41], v[68:69], v[44:45]
	v_pk_fma_f32 v[58:59], v[58:59], v[66:67], v[82:83]
	v_pk_fma_f32 v[32:33], v[32:33], v[76:77], v[40:41]
	v_pk_fma_f32 v[58:59], v[50:51], v[70:71], v[58:59]
	v_pk_mul_f32 v[32:33], v[32:33], v[36:37]
	v_pk_mul_f32 v[36:37], v[38:39], v[46:47]
	v_pk_fma_f32 v[38:39], v[50:51], v[66:67], v[82:83]
	v_pk_mul_f32 v[34:35], v[34:35], v[102:103]
	v_pk_fma_f32 v[38:39], v[42:43], v[70:71], v[38:39]
	v_pk_mul_f32 v[62:63], v[62:63], v[106:107]
	v_pk_fma_f32 v[58:59], v[42:43], v[78:79], v[58:59]
	v_pk_fma_f32 v[34:35], v[34:35], v[78:79], v[38:39]
	v_pk_mul_f32 v[60:61], v[100:101], v[60:61]
	v_pk_mul_f32 v[58:59], v[58:59], v[62:63]
	v_pk_mul_f32 v[34:35], v[34:35], v[36:37]
	v_cvt_pk_bf16_f32 v60, v60, v61
	v_cvt_pk_bf16_f32 v61, v58, v59
	v_lshl_add_u64 v[58:59], v[132:133], 0, v[56:57]
	v_cvt_pk_bf16_f32 v32, v32, v33
	v_cvt_pk_bf16_f32 v33, v34, v35
	v_lshl_add_u64 v[34:35], v[172:173], 0, v[56:57]
	global_store_dwordx2 v[58:59], v[60:61], off
	global_store_dwordx2 v[34:35], v[32:33], off
	v_mov_b32_e32 v105, 0
	v_mov_b32_e32 v106, 0
	v_mov_b32_e32 v107, 0
	v_mov_b32_e32 v32, 0
	v_mov_b32_e32 v33, 0
	v_mov_b32_e32 v34, 0
	v_mov_b32_e32 v35, 0
	v_mov_b32_e32 v36, 0
	v_mov_b32_e32 v37, 0
	v_mov_b32_e32 v38, 0
	v_mov_b32_e32 v39, 0
	v_mov_b32_e32 v40, 0
	v_mov_b32_e32 v41, 0
	v_mov_b32_e32 v42, 0
	v_mov_b32_e32 v43, 0
	s_and_saveexec_b64 s[0:1], s[10:11]
	s_cbranch_execz .LBB0_1587
	ds_read_b128 v[40:43], v230 offset:2112
	ds_read_b128 v[32:35], v230 offset:2624
	ds_read_b128 v[36:39], v230 offset:3136
	ds_read_b128 v[104:107], v230 offset:3648
.LBB0_1587:
	s_or_b64 exec, exec, s[0:1]
	v_mul_f32_dpp v54, v4, v201 row_shr:1 row_mask:0xf bank_mask:0xf bound_ctrl:1
	v_mul_f32_dpp v58, v8, v200 row_shr:1 row_mask:0xf bank_mask:0xf bound_ctrl:1
	v_mul_f32_dpp v60, v0, v201 row_shr:1 row_mask:0xf bank_mask:0xf bound_ctrl:1
	v_mul_f32_dpp v52, v12, v200 row_shr:1 row_mask:0xf bank_mask:0xf bound_ctrl:1
	v_mov_b32_e32 v48, v72
	v_mov_b32_e32 v49, v72
	v_mul_f32_dpp v53, v13, v200 row_shr:1 row_mask:0xf bank_mask:0xf bound_ctrl:1
	s_waitcnt lgkmcnt(0)
	v_pk_add_f32 v[40:41], v[40:41], v[52:53]
	v_pk_mul_f32 v[28:29], v[28:29], v[48:49]
	v_mul_f32_dpp v55, v5, v201 row_shr:1 row_mask:0xf bank_mask:0xf bound_ctrl:1
	v_pk_add_f32 v[36:37], v[36:37], v[54:55]
	v_pk_fma_f32 v[40:41], v[84:85], v[40:41], v[96:97]
	v_pk_fma_f32 v[40:41], v[88:89], v[36:37], v[40:41]
	v_pk_fma_f32 v[40:41], v[28:29], v[92:93], v[40:41]
	v_mul_f32_dpp v59, v9, v200 row_shr:1 row_mask:0xf bank_mask:0xf bound_ctrl:1
	v_exp_f32_e32 v52, v40
	v_exp_f32_e32 v53, v41
	v_mul_f32_dpp v61, v1, v201 row_shr:1 row_mask:0xf bank_mask:0xf bound_ctrl:1
	v_mul_f32_dpp v100, v6, v201 row_shr:1 row_mask:0xf bank_mask:0xf bound_ctrl:1
	v_mul_f32_dpp v102, v10, v200 row_shr:1 row_mask:0xf bank_mask:0xf bound_ctrl:1
	v_mul_f32_dpp v108, v2, v201 row_shr:1 row_mask:0xf bank_mask:0xf bound_ctrl:1
	v_mul_f32_dpp v62, v14, v200 row_shr:1 row_mask:0xf bank_mask:0xf bound_ctrl:1
	v_add_f32_e32 v52, 1.0, v52
	v_add_f32_e32 v53, 1.0, v53
	v_mul_f32_dpp v63, v15, v200 row_shr:1 row_mask:0xf bank_mask:0xf bound_ctrl:1
	v_rcp_f32_e32 v52, v52
	v_rcp_f32_e32 v53, v53
	v_mul_f32_dpp v101, v7, v201 row_shr:1 row_mask:0xf bank_mask:0xf bound_ctrl:1
	v_pk_add_f32 v[42:43], v[42:43], v[62:63]
	v_mov_b32_e32 v111, v72
	v_mul_f32_dpp v103, v11, v200 row_shr:1 row_mask:0xf bank_mask:0xf bound_ctrl:1
	v_pk_add_f32 v[38:39], v[38:39], v[100:101]
	v_pk_fma_f32 v[42:43], v[86:87], v[42:43], v[98:99]
	v_mul_f32_dpp v109, v3, v201 row_shr:1 row_mask:0xf bank_mask:0xf bound_ctrl:1
	v_mov_b32_e32 v110, v72
	v_pk_mul_f32 v[30:31], v[30:31], v[110:111]
	v_pk_fma_f32 v[42:43], v[90:91], v[38:39], v[42:43]
	v_pk_mul_f32 v[40:41], v[40:41], v[52:53]
	v_pk_fma_f32 v[42:43], v[30:31], v[94:95], v[42:43]
	v_pk_add_f32 v[32:33], v[32:33], v[58:59]
	v_exp_f32_e32 v52, v42
	v_exp_f32_e32 v53, v43
	v_pk_mul_f32 v[24:25], v[24:25], v[48:49]
	v_pk_add_f32 v[48:49], v[104:105], v[60:61]
	v_pk_fma_f32 v[32:33], v[64:65], v[32:33], v[80:81]
	v_add_f32_e32 v52, 1.0, v52
	v_add_f32_e32 v53, 1.0, v53
	v_pk_fma_f32 v[32:33], v[68:69], v[48:49], v[32:33]
	v_rcp_f32_e32 v52, v52
	v_rcp_f32_e32 v53, v53
	v_pk_fma_f32 v[32:33], v[24:25], v[76:77], v[32:33]
	v_pk_add_f32 v[34:35], v[34:35], v[102:103]
	v_pk_mul_f32 v[32:33], v[32:33], v[40:41]
	v_pk_add_f32 v[40:41], v[106:107], v[108:109]
	v_pk_fma_f32 v[34:35], v[66:67], v[34:35], v[82:83]
	v_pk_mul_f32 v[26:27], v[26:27], v[110:111]
	v_pk_fma_f32 v[34:35], v[70:71], v[40:41], v[34:35]
; __device__ __forceinline__ unsigned pk2(float lo, float hi) { f32x2_t v = {lo, hi}; bf16x2_t b = __builtin_convertvector(v, bf16x2_t); return __builtin_bit_cast(unsigned, b); }
; __device__ __forceinline__ float fast_rsq(float x) { return __builtin_amdgcn_rsqf(x); }
; __device__ __forceinline__ float sigmoidf_(float v) { return fast_rcp(1.0f + fast_exp2(-v * LOG2E)); }
;     __device__ __forceinline__ void run(const f32x4 (&acc)[2][2][4][2], const Unit& u, const Unit& nxt, bool has_next, int ui, int wr, int wc, int fr_in, int fq_in) const {
;     ...
;                 for (int m = 0; m < 4; ++m) {
;                     const f32x4 gc = acc[ai][0][m][n] * rs[ai][m], vc = acc[ai][1][m][n] * rs[ai][m];
;                     const f32x4 cgt = bg + wg0 * pg2 + wg1 * pg1 + wg2 * gc, cvl = bv + wv0 * pv2 + wv1 * pv1 + wv2 * vc;
;                     float a[4];
; #pragma unroll
;                     for (int i = 0; i < 4; ++i) a[i] = cgt[i] * sigmoidf_(cgt[i]) * cvl[i];
;                     u32x2 w; w.x = pk2(a[0], a[1]); w.y = pk2(a[2], a[3]);
;                     *(u32x2*)(A + (size_t)(u.pm * BM + ai * 128 + wr * 64 + 4 * fr + m) * DFF + ch) = w;
;                     pg2 = pg1; pg1 = gc; pv2 = pv1; pv1 = vc;
;                 }
;                 asm volatile("" ::: "memory");
;             }
;         }
;         if (has_next) {
;             prm[(slot ^ 1) * 1024 + tid] = nx0; prm[(slot ^ 1) * 1024 + tid + 512] = nx1;
;             if (tid < 256) rsd[(slot ^ 1) * 256 + tid] = fast_rsq(nrs * (1.0f / DM) + EPS);
;         }
	v_pk_mul_f32 v[42:43], v[42:43], v[52:53]
	v_pk_fma_f32 v[34:35], v[26:27], v[78:79], v[34:35]
	v_cvt_pk_bf16_f32 v32, v32, v33
	v_pk_mul_f32 v[34:35], v[34:35], v[42:43]
	v_mov_b32_e32 v50, v73
	v_cvt_pk_bf16_f32 v33, v34, v35
	v_lshl_add_u64 v[34:35], v[122:123], 0, v[56:57]
	v_mov_b32_e32 v51, v73
	global_store_dwordx2 v[34:35], v[32:33], off
	v_pk_fma_f32 v[32:33], v[84:85], v[36:37], v[96:97]
	v_pk_mul_f32 v[20:21], v[20:21], v[50:51]
	v_pk_fma_f32 v[32:33], v[28:29], v[88:89], v[32:33]
	v_mov_b32_e32 v72, v73
	v_pk_fma_f32 v[32:33], v[20:21], v[92:93], v[32:33]
	v_pk_mul_f32 v[22:23], v[22:23], v[72:73]
	v_exp_f32_e32 v34, v32
	v_exp_f32_e32 v35, v33
	v_mov_b32_e32 v46, v74
	v_mov_b32_e32 v47, v74
	v_add_f32_e32 v34, 1.0, v34
	v_add_f32_e32 v35, 1.0, v35
	v_rcp_f32_e32 v34, v34
	v_rcp_f32_e32 v35, v35
	v_pk_fma_f32 v[28:29], v[28:29], v[84:85], v[96:97]
	v_mov_b32_e32 v44, v75
	v_mov_b32_e32 v45, v75
	v_pk_mul_f32 v[32:33], v[32:33], v[34:35]
	v_pk_fma_f32 v[34:35], v[86:87], v[38:39], v[98:99]
	v_pk_mul_f32 v[12:13], v[12:13], v[46:47]
	v_pk_fma_f32 v[34:35], v[30:31], v[90:91], v[34:35]
	v_pk_fma_f32 v[28:29], v[20:21], v[88:89], v[28:29]
	v_pk_fma_f32 v[34:35], v[22:23], v[94:95], v[34:35]
	v_pk_fma_f32 v[20:21], v[20:21], v[84:85], v[96:97]
	v_exp_f32_e32 v38, v34
	v_exp_f32_e32 v39, v35
	v_pk_fma_f32 v[28:29], v[12:13], v[92:93], v[28:29]
	v_pk_mul_f32 v[4:5], v[4:5], v[44:45]
	v_pk_fma_f32 v[12:13], v[12:13], v[88:89], v[20:21]
	v_pk_fma_f32 v[36:37], v[64:65], v[48:49], v[80:81]
	v_add_f32_e32 v38, 1.0, v38
	v_add_f32_e32 v39, 1.0, v39
	v_pk_fma_f32 v[4:5], v[4:5], v[92:93], v[12:13]
	v_pk_mul_f32 v[16:17], v[16:17], v[50:51]
	v_rcp_f32_e32 v38, v38
	v_rcp_f32_e32 v39, v39
	v_pk_fma_f32 v[36:37], v[24:25], v[68:69], v[36:37]
	v_pk_fma_f32 v[36:37], v[16:17], v[76:77], v[36:37]
	v_exp_f32_e32 v12, v4
	v_exp_f32_e32 v13, v5
	v_pk_mul_f32 v[32:33], v[36:37], v[32:33]
	v_pk_fma_f32 v[36:37], v[66:67], v[40:41], v[82:83]
	v_pk_mul_f32 v[18:19], v[18:19], v[72:73]
	v_pk_fma_f32 v[36:37], v[26:27], v[70:71], v[36:37]
	v_pk_mul_f32 v[34:35], v[34:35], v[38:39]
	v_pk_fma_f32 v[36:37], v[18:19], v[78:79], v[36:37]
	v_add_f32_e32 v12, 1.0, v12
	v_pk_mul_f32 v[34:35], v[36:37], v[34:35]
	v_add_f32_e32 v13, 1.0, v13
	v_cvt_pk_bf16_f32 v32, v32, v33
	v_cvt_pk_bf16_f32 v33, v34, v35
	v_lshl_add_u64 v[34:35], v[124:125], 0, v[56:57]
	v_rcp_f32_e32 v12, v12
	v_rcp_f32_e32 v13, v13
	global_store_dwordx2 v[34:35], v[32:33], off
	v_exp_f32_e32 v34, v28
	v_mov_b32_e32 v32, v74
	v_exp_f32_e32 v35, v29
	v_mov_b32_e32 v33, v74
	v_pk_mul_f32 v[14:15], v[14:15], v[32:33]
	v_mov_b32_e32 v74, v75
	v_pk_mul_f32 v[4:5], v[4:5], v[12:13]
	v_pk_fma_f32 v[12:13], v[22:23], v[86:87], v[98:99]
	v_pk_mul_f32 v[6:7], v[6:7], v[74:75]
	v_pk_fma_f32 v[12:13], v[14:15], v[90:91], v[12:13]
	v_pk_fma_f32 v[30:31], v[30:31], v[86:87], v[98:99]
	v_pk_fma_f32 v[6:7], v[6:7], v[94:95], v[12:13]
	v_pk_fma_f32 v[30:31], v[22:23], v[90:91], v[30:31]
	v_pk_fma_f32 v[30:31], v[14:15], v[94:95], v[30:31]
	v_exp_f32_e32 v14, v6
	v_exp_f32_e32 v15, v7
	v_pk_mul_f32 v[10:11], v[10:11], v[32:33]
	v_exp_f32_e32 v32, v30
	v_exp_f32_e32 v33, v31
	v_add_f32_e32 v14, 1.0, v14
	v_add_f32_e32 v15, 1.0, v15
	v_add_f32_e32 v34, 1.0, v34
	v_add_f32_e32 v35, 1.0, v35
	v_pk_fma_f32 v[24:25], v[24:25], v[64:65], v[80:81]
	v_rcp_f32_e32 v14, v14
	v_rcp_f32_e32 v15, v15
	v_rcp_f32_e32 v34, v34
	v_rcp_f32_e32 v35, v35
	v_pk_mul_f32 v[8:9], v[8:9], v[46:47]
	v_add_f32_e32 v32, 1.0, v32
	v_add_f32_e32 v33, 1.0, v33
	v_pk_fma_f32 v[24:25], v[16:17], v[68:69], v[24:25]
	v_pk_fma_f32 v[12:13], v[16:17], v[64:65], v[80:81]
	v_rcp_f32_e32 v32, v32
	v_rcp_f32_e32 v33, v33
	v_pk_fma_f32 v[24:25], v[8:9], v[76:77], v[24:25]
	v_pk_mul_f32 v[0:1], v[0:1], v[44:45]
	v_pk_fma_f32 v[8:9], v[8:9], v[68:69], v[12:13]
	v_pk_fma_f32 v[26:27], v[26:27], v[66:67], v[82:83]
	v_pk_fma_f32 v[0:1], v[0:1], v[76:77], v[8:9]
	v_pk_mul_f32 v[28:29], v[28:29], v[34:35]
	v_pk_mul_f32 v[0:1], v[0:1], v[4:5]
	v_pk_mul_f32 v[4:5], v[6:7], v[14:15]
	v_pk_fma_f32 v[6:7], v[18:19], v[66:67], v[82:83]
	v_pk_fma_f32 v[26:27], v[18:19], v[70:71], v[26:27]
	v_pk_mul_f32 v[2:3], v[2:3], v[74:75]
	v_pk_fma_f32 v[6:7], v[10:11], v[70:71], v[6:7]
	v_pk_mul_f32 v[24:25], v[24:25], v[28:29]
	v_pk_mul_f32 v[28:29], v[30:31], v[32:33]
	v_pk_fma_f32 v[26:27], v[10:11], v[78:79], v[26:27]
	v_pk_fma_f32 v[2:3], v[2:3], v[78:79], v[6:7]
	v_pk_mul_f32 v[26:27], v[26:27], v[28:29]
	v_pk_mul_f32 v[2:3], v[2:3], v[4:5]
	v_cvt_pk_bf16_f32 v24, v24, v25
	v_cvt_pk_bf16_f32 v25, v26, v27
	v_lshl_add_u64 v[26:27], v[130:131], 0, v[56:57]
	v_cvt_pk_bf16_f32 v0, v0, v1
	v_cvt_pk_bf16_f32 v1, v2, v3
	v_lshl_add_u64 v[2:3], v[134:135], 0, v[56:57]
	global_store_dwordx2 v[26:27], v[24:25], off
	global_store_dwordx2 v[2:3], v[0:1], off
	s_and_b64 vcc, exec, s[6:7]
	s_mov_b64 s[0:1], -1
	s_cbranch_vccnz .LBB0_1543
	s_xor_b32 s4, s29, 0x400
	v_lshlrev_b32_e32 v0, 2, v226
	v_lshl_add_u32 v0, s4, 2, v0
	v_add_u32_e32 v0, 0x22040, v0
	v_cmp_gt_i32_e32 vcc, s33, v226
	s_waitcnt vmcnt(0)
	v_mul_f32_e32 v228, 0xbfb8aa3b, v228
	v_mul_f32_e32 v227, 0xbf317218, v227
	ds_write2st64_b32 v0, v228, v227 offset1:8
	s_and_saveexec_b64 s[0:1], vcc
	s_cbranch_execz .LBB0_1590
	v_rsq_f32_e32 v0, v229
	v_lshl_add_u32 v1, v226, 2, s4
	v_add_u32_e32 v1, 0x24040, v1
	ds_write_b32 v1, v0

; template <class Epi, class Sched, bool ALIGN_EPI = false, bool SP2 = false>
; __device__ __forceinline__ void gemm_phase(PG8_LAS unsigned char* lds, const Gemm g, const Sched& S, const Epi& E, const int tid_arg) {
;     ...
;         const char* nA = has_next ? (const char*)g.A + (size_t)nxt.pm * tstep : cA; const char* nB = has_next ? (const char*)g.Bt + (size_t)nxt.pn * tstep : cB;
;         for (int t = 0; t < nt; t += 2) {
;             const bool last = (t == nt - 2);
;             const char* a1 = cA + (size_t)(t + 1) * kstep;
;             const char* a2 = last ? nA : cA + (size_t)(t + 2) * kstep; const char* b2 = last ? nB : cB + (size_t)(t + 2) * kstep;
;             const char* a3 = a2 + kstep; const char* b3 = b2 + kstep;
;     ...
; #pragma unroll
;         for (int a = 0; a < 2; ++a)
; #pragma unroll
;             for (int b = 0; b < 2; ++b)
; #pragma unroll
;                 for (int m = 0; m < 4; ++m)
; #pragma unroll
;                     for (int n = 0; n < 2; ++n) acc[a][b][m][n] = (f32x4){0.f, 0.f, 0.f, 0.f};
.LBB0_1826:
	s_ashr_i32 s39, s38, 31
	s_lshl_b64 s[0:1], s[38:39], 19
	s_add_u32 s40, s3, s0
	s_addc_u32 s41, s33, s1
	s_and_b64 s[0:1], s[6:7], exec
	s_cselect_b32 s39, s41, s47
	s_cselect_b32 s75, s40, s46
	s_ashr_i32 s37, s36, 31
	s_lshl_b64 s[0:1], s[36:37], 19
	s_add_u32 s42, s48, s0
	s_addc_u32 s43, s49, s1
	s_and_b64 s[0:1], s[6:7], exec
	s_cselect_b32 s37, s43, s45
	s_cselect_b32 s78, s42, s44
	s_add_u32 s79, s44, 0x100
	s_addc_u32 s80, s45, 0
	s_add_u32 s44, s46, 0x40080
	v_mov_b32_e32 v0, 0
	s_addc_u32 s45, s47, 0
	s_mov_b32 s81, -2
	v_mov_b32_e32 v1, v0
	v_mov_b64_e32 v[2:3], 0
	v_mov_b64_e32 v[4:5], 0
	v_mov_b64_e32 v[6:7], 0
	v_mov_b64_e32 v[16:17], 0
	v_mov_b64_e32 v[18:19], 0
	v_mov_b64_e32 v[20:21], 0
	v_mov_b64_e32 v[22:23], 0
	v_mov_b64_e32 v[32:33], 0
	v_mov_b64_e32 v[34:35], 0
	v_mov_b64_e32 v[36:37], 0
	v_mov_b64_e32 v[38:39], 0
	v_mov_b64_e32 v[48:49], 0
	v_mov_b64_e32 v[50:51], 0
	v_mov_b64_e32 v[52:53], 0
	v_mov_b64_e32 v[54:55], 0
	v_mov_b64_e32 v[8:9], 0
	v_mov_b64_e32 v[10:11], 0
	v_mov_b64_e32 v[12:13], 0
	v_mov_b64_e32 v[14:15], 0
	v_mov_b64_e32 v[24:25], 0
	v_mov_b64_e32 v[26:27], 0
	v_mov_b64_e32 v[28:29], 0
	v_mov_b64_e32 v[30:31], 0
	v_mov_b64_e32 v[40:41], 0
	v_mov_b64_e32 v[42:43], 0
	v_mov_b64_e32 v[44:45], 0
	v_mov_b64_e32 v[46:47], 0
	v_mov_b64_e32 v[56:57], 0
	v_mov_b64_e32 v[58:59], 0
	v_mov_b64_e32 v[60:61], 0
	v_mov_b64_e32 v[62:63], 0
	v_mov_b64_e32 v[64:65], 0
	v_mov_b64_e32 v[66:67], 0
	v_mov_b64_e32 v[68:69], 0
	v_mov_b64_e32 v[70:71], 0
	v_mov_b64_e32 v[80:81], 0
	v_mov_b64_e32 v[82:83], 0
	v_mov_b64_e32 v[84:85], 0
	v_mov_b64_e32 v[86:87], 0
	v_mov_b64_e32 v[96:97], 0
	v_mov_b64_e32 v[98:99], 0
	v_mov_b64_e32 v[100:101], 0
	v_mov_b64_e32 v[102:103], 0
	v_mov_b64_e32 v[112:113], 0
	v_mov_b64_e32 v[114:115], 0
	v_mov_b64_e32 v[116:117], 0
	v_mov_b64_e32 v[118:119], 0
	v_mov_b64_e32 v[72:73], 0
	v_mov_b64_e32 v[74:75], 0
	v_mov_b64_e32 v[76:77], 0
	v_mov_b64_e32 v[78:79], 0
	v_mov_b64_e32 v[88:89], 0
	v_mov_b64_e32 v[90:91], 0
	v_mov_b64_e32 v[92:93], 0
	v_mov_b64_e32 v[94:95], 0
	v_mov_b64_e32 v[104:105], 0
	v_mov_b64_e32 v[106:107], 0
	v_mov_b64_e32 v[108:109], 0
	v_mov_b64_e32 v[110:111], 0
	v_mov_b64_e32 v[120:121], 0
	v_mov_b64_e32 v[122:123], 0
	v_mov_b64_e32 v[124:125], 0
	v_mov_b64_e32 v[126:127], 0

; template <class Epi, class Sched, bool ALIGN_EPI = false, bool SP2 = false>
; __device__ __forceinline__ void gemm_phase(PG8_LAS unsigned char* lds, const Gemm g, const Sched& S, const Epi& E, const int tid_arg) {
;     ...
;     f32x4 acc[2][2][4][2];
; #pragma unroll
;     for (int a = 0; a < 2; ++a)
; #pragma unroll
;         for (int b = 0; b < 2; ++b)
; #pragma unroll
;             for (int m = 0; m < 4; ++m)
; #pragma unroll
;                 for (int n = 0; n < 2; ++n) acc[a][b][m][n] = (f32x4){0.f, 0.f, 0.f, 0.f};
;     ...
; #pragma unroll
;         for (int a = 0; a < 2; ++a)
; #pragma unroll
;             for (int b = 0; b < 2; ++b)
; #pragma unroll
;                 for (int m = 0; m < 4; ++m)
; #pragma unroll
;                     for (int n = 0; n < 2; ++n) acc[a][b][m][n] = (f32x4){0.f, 0.f, 0.f, 0.f};
.LBB0_1909:
	v_mov_b32_e32 v127, 0
	s_and_b64 vcc, exec, s[0:1]
	v_mov_b32_e32 v126, v127
	v_mov_b64_e32 v[124:125], 0
	v_mov_b64_e32 v[122:123], 0
	v_mov_b64_e32 v[120:121], 0
	v_mov_b64_e32 v[110:111], 0
	v_mov_b64_e32 v[108:109], 0
	v_mov_b64_e32 v[106:107], 0
	v_mov_b64_e32 v[104:105], 0
	v_mov_b64_e32 v[94:95], 0
	v_mov_b64_e32 v[92:93], 0
	v_mov_b64_e32 v[90:91], 0
	v_mov_b64_e32 v[88:89], 0
	v_mov_b64_e32 v[78:79], 0
	v_mov_b64_e32 v[76:77], 0
	v_mov_b64_e32 v[74:75], 0
	v_mov_b64_e32 v[72:73], 0
	v_mov_b64_e32 v[118:119], 0
	v_mov_b64_e32 v[116:117], 0
	v_mov_b64_e32 v[114:115], 0
	v_mov_b64_e32 v[112:113], 0
	v_mov_b64_e32 v[102:103], 0
	v_mov_b64_e32 v[100:101], 0
	v_mov_b64_e32 v[98:99], 0
	v_mov_b64_e32 v[96:97], 0
	v_mov_b64_e32 v[86:87], 0
	v_mov_b64_e32 v[84:85], 0
	v_mov_b64_e32 v[82:83], 0
	v_mov_b64_e32 v[80:81], 0
	v_mov_b64_e32 v[70:71], 0
	v_mov_b64_e32 v[68:69], 0
	v_mov_b64_e32 v[66:67], 0
	v_mov_b64_e32 v[64:65], 0
	v_mov_b64_e32 v[62:63], 0
	v_mov_b64_e32 v[60:61], 0
	v_mov_b64_e32 v[58:59], 0
	v_mov_b64_e32 v[56:57], 0
	v_mov_b64_e32 v[46:47], 0
	v_mov_b64_e32 v[44:45], 0
	v_mov_b64_e32 v[42:43], 0
	v_mov_b64_e32 v[40:41], 0
	v_mov_b64_e32 v[30:31], 0
	v_mov_b64_e32 v[28:29], 0
	v_mov_b64_e32 v[26:27], 0
	v_mov_b64_e32 v[24:25], 0
	v_mov_b64_e32 v[14:15], 0
	v_mov_b64_e32 v[12:13], 0
	v_mov_b64_e32 v[10:11], 0
	v_mov_b64_e32 v[8:9], 0
	v_mov_b64_e32 v[54:55], 0
	v_mov_b64_e32 v[52:53], 0
	v_mov_b64_e32 v[50:51], 0
	v_mov_b64_e32 v[48:49], 0
	v_mov_b64_e32 v[38:39], 0
	v_mov_b64_e32 v[36:37], 0
	v_mov_b64_e32 v[34:35], 0
	v_mov_b64_e32 v[32:33], 0
	v_mov_b64_e32 v[22:23], 0
	v_mov_b64_e32 v[20:21], 0
	v_mov_b64_e32 v[18:19], 0
	v_mov_b64_e32 v[16:17], 0
	v_mov_b64_e32 v[6:7], 0
	v_mov_b64_e32 v[4:5], 0
	v_mov_b64_e32 v[2:3], 0
	v_mov_b64_e32 v[0:1], 0
	s_cbranch_vccnz .LBB0_1912
	s_add_u32 s63, s34, 0x100
	s_addc_u32 s64, s35, 0
	s_add_u32 s6, s36, 0x80
	v_mov_b32_e32 v0, 0
	s_addc_u32 s7, s37, 0
	s_mov_b32 s34, 0
	v_mov_b32_e32 v1, v0
	v_mov_b64_e32 v[2:3], 0
	v_mov_b64_e32 v[4:5], 0
	v_mov_b64_e32 v[6:7], 0
	v_mov_b64_e32 v[16:17], 0
	v_mov_b64_e32 v[18:19], 0
	v_mov_b64_e32 v[20:21], 0
	v_mov_b64_e32 v[22:23], 0
	v_mov_b64_e32 v[32:33], 0
	v_mov_b64_e32 v[34:35], 0
	v_mov_b64_e32 v[36:37], 0
	v_mov_b64_e32 v[38:39], 0
	v_mov_b64_e32 v[48:49], 0
	v_mov_b64_e32 v[50:51], 0
	v_mov_b64_e32 v[52:53], 0
	v_mov_b64_e32 v[54:55], 0
	v_mov_b64_e32 v[8:9], 0
	v_mov_b64_e32 v[10:11], 0
	v_mov_b64_e32 v[12:13], 0
	v_mov_b64_e32 v[14:15], 0
	v_mov_b64_e32 v[24:25], 0
	v_mov_b64_e32 v[26:27], 0
	v_mov_b64_e32 v[28:29], 0
	v_mov_b64_e32 v[30:31], 0
	v_mov_b64_e32 v[40:41], 0
	v_mov_b64_e32 v[42:43], 0
	v_mov_b64_e32 v[44:45], 0
	v_mov_b64_e32 v[46:47], 0
	v_mov_b64_e32 v[56:57], 0
	v_mov_b64_e32 v[58:59], 0
	v_mov_b64_e32 v[60:61], 0
	v_mov_b64_e32 v[62:63], 0
	v_mov_b64_e32 v[64:65], 0
	v_mov_b64_e32 v[66:67], 0
	v_mov_b64_e32 v[68:69], 0
	v_mov_b64_e32 v[70:71], 0
	v_mov_b64_e32 v[80:81], 0
	v_mov_b64_e32 v[82:83], 0
	v_mov_b64_e32 v[84:85], 0
	v_mov_b64_e32 v[86:87], 0
	v_mov_b64_e32 v[96:97], 0
	v_mov_b64_e32 v[98:99], 0
	v_mov_b64_e32 v[100:101], 0
	v_mov_b64_e32 v[102:103], 0
	v_mov_b64_e32 v[112:113], 0
	v_mov_b64_e32 v[114:115], 0
	v_mov_b64_e32 v[116:117], 0
	v_mov_b64_e32 v[118:119], 0
	v_mov_b64_e32 v[72:73], 0
	v_mov_b64_e32 v[74:75], 0
	v_mov_b64_e32 v[76:77], 0
	v_mov_b64_e32 v[78:79], 0
	v_mov_b64_e32 v[88:89], 0
	v_mov_b64_e32 v[90:91], 0
	v_mov_b64_e32 v[92:93], 0
	v_mov_b64_e32 v[94:95], 0
	v_mov_b64_e32 v[104:105], 0
	v_mov_b64_e32 v[106:107], 0
	v_mov_b64_e32 v[108:109], 0
	v_mov_b64_e32 v[110:111], 0
	v_mov_b64_e32 v[120:121], 0
	v_mov_b64_e32 v[122:123], 0
	v_mov_b64_e32 v[124:125], 0
	v_mov_b64_e32 v[126:127], 0
